# Hyena FFT: stagger - waves 4-7 sleep 4x64 cycles after every workgroup barrier so SIMD partners alternate LDS and VALU phases
# speedup vs baseline: 1.0034x; 1.0034x over previous
; #define LAS __attribute__((address_space(3)))
; __device__ __forceinline__ f32x2 cmul(f32x2 a, f32x2 b) { return (f32x2){a.x * b.x - a.y * b.y, a.x * b.y + a.y * b.x}; }
; template <int MODE> __device__ __forceinline__ void fft_pair32(LAS f32x2* B, const LAS f32x2* F, int wave, int lane) {
;     ...
;     constexpr float CS[16] = {1.f, 0.98078528040323043f, 0.92387953251128674f, 0.83146961230254524f, 0.70710678118654752f, 0.55557023301960218f, 0.38268343236508977f, 0.19509032201612825f,
;                               0.f, -0.19509032201612825f, -0.38268343236508977f, -0.55557023301960218f, -0.70710678118654752f, -0.83146961230254524f, -0.92387953251128674f, -0.98078528040323043f};
;     constexpr float SN[16] = {0.f, 0.19509032201612825f, 0.38268343236508977f, 0.55557023301960218f, 0.70710678118654752f, 0.83146961230254524f, 0.92387953251128674f, 0.98078528040323043f,
;                               1.f, 0.98078528040323043f, 0.92387953251128674f, 0.83146961230254524f, 0.70710678118654752f, 0.55557023301960218f, 0.38268343236508977f, 0.19509032201612825f};
;     const int hi = lane >> 5, blk = 32 * wave + (lane & 31); const float sg = hi ? -1.f : 1.f;
;     LAS f32x2* p = B + 33 * blk; f32x2 v[16];
; #pragma unroll
;     for (int j = 0; j < 16; ++j) { const f32x2 d = p[j] + p[j + 16] * sg;
;         const f32x2 w = {hi ? CS[j] : 1.f, hi ? -SN[j] : 0.f}; v[j] = j == 0 ? d : cmul(d, w); }
; __device__ __forceinline__ void hyena_fft(LAS unsigned char* lds, int layer, int G, const int wave_s) {
;     ...
;     LAS f32x2* Db = (LAS f32x2*)lds; LAS f32x2* Fb = Db + FPAD; LAS f32x2* TW2 = (LAS f32x2*)(lds + HY_TW2);
;     LAS float* pl0 = (LAS float*)lds; LAS float* pl1 = pl0 + 2 * SEQ;
;     const int n2 = tid;
;     TW2[tid] = tw_base((float)((tid & 31) * (tid >> 5)) * (1.0f / 512.f));
;     f32x2 w1p[16]; tw_powers(tw_base((float)n2 * (1.0f / 8192.f)), w1p); w1p[0] = (f32x2){1.f, 0.f};
;     int c_lo = 4 * (int)blockIdx.x, c_hi = c_lo + 4;
;     if (layer == DEPTH - 1) { const int b = (int)blockIdx.x, i2 = b - NQKV, n5 = HY - 3 * NQKV - 4 * (256 - NQKV);
;         if (b < NQKV) { c_lo = 3 * b; c_hi = c_lo + 3; } else if (i2 < n5) { c_lo = 3 * NQKV + 5 * i2; c_hi = c_lo + 5; } else { c_lo = 3 * NQKV + 5 * n5 + 4 * (i2 - n5); c_hi = c_lo + 4; } }
.LBB0_465:
	v_readlane_b32 s0, v253, 2
	v_mbcnt_lo_u32_b32 v157, -1, 0
	v_mbcnt_hi_u32_b32 v157, -1, v157
	s_mov_b64 s[36:37], s[94:95]
	v_and_b32_e32 v0, 31, v157
	s_waitcnt vmcnt(0)
	v_lshl_add_u32 v2, s0, 6, v157
	s_waitcnt lgkmcnt(0)
	v_ashrrev_i32_e32 v3, 5, v2
	v_mul_lo_u32 v0, v3, v0
	v_cvt_f32_i32_e32 v0, v0
	s_cmp_eq_u32 s76, 3
	s_cselect_b64 s[74:75], -1, 0
	v_mul_f32_e32 v0, 0x3b000000, v0
	s_and_b64 s[28:29], s[74:75], exec
	v_cos_f32_e32 v4, v0
	v_sin_f32_e64 v5, -v0
	v_lshl_add_u32 v0, v2, 3, 0
	v_add_u32_e32 v0, 0x21400, v0
	v_readlane_b32 s11, v254, 25
	ds_write_b64 v0, v[4:5]
	v_cvt_f32_i32_e32 v0, v2
	s_cselect_b32 s93, s1, s11
	v_readlane_b32 s1, v254, 27
	s_cselect_b32 s80, s10, s1
	s_mul_hi_u32 s25, s76, 0x9000
	s_mul_i32 s17, s76, 0x9000
	s_mul_hi_u32 s35, s76, 0x3000
	s_mul_i32 s23, s76, 0x3000
	v_mul_f32_e32 v0, 0x39000000, v0
	s_cmp_ge_i32 s80, s93
	s_cbranch_scc1 .LBB0_677
	v_readlane_b32 s43, v253, 2
	s_load_dwordx2 s[60:61], s[94:95], 0xd8
	s_nop 1
	v_lshl_add_u32 v0, s43, 6, v157
	s_cmp_ge_u32 s43, 4
	s_cselect_b64 vcc, exec, 0
	s_mov_b32 s68, 0x3f6c835e
	s_mov_b32 s69, 0xbec3ef15
	s_mov_b32 s84, 0x3f3504f3
	s_mov_b32 s85, 0xbf3504f3
	s_mov_b32 s88, 0x3ec3ef15
	s_mov_b32 s89, 0xbf6c835e
	s_mov_b32 s90, 0xbf3504f3
	s_mov_b32 s91, 0xbf3504f3
	s_mov_b32 s98, 0xbf6c835e
	s_mov_b32 s99, 0x3ec3ef15
	v_mov_b32_e32 v192, 0x38800000
	v_lshrrev_b32_e32 v65, 5, v157
	v_cvt_f32_u32_e32 v69, v65
	v_fma_f32 v190, v69, -2.0, 1.0
	v_mul_u32_u24_e32 v69, 1, v0
	v_cvt_f32_u32_e32 v69, v69
	v_mul_f32_e32 v69, 0x39000000, v69
	v_cos_f32_e32 v6, v69
	v_sin_f32_e64 v7, -v69
	v_mul_u32_u24_e32 v69, 2, v0
	v_cvt_f32_u32_e32 v69, v69
	v_mul_f32_e32 v69, 0x39000000, v69
	v_cos_f32_e32 v8, v69
	v_sin_f32_e64 v9, -v69
	v_mul_u32_u24_e32 v69, 3, v0
	v_cvt_f32_u32_e32 v69, v69
	v_mul_f32_e32 v69, 0x39000000, v69
	v_cos_f32_e32 v10, v69
	v_sin_f32_e64 v11, -v69
	v_mul_u32_u24_e32 v69, 4, v0
	v_cvt_f32_u32_e32 v69, v69
	v_mul_f32_e32 v69, 0x39000000, v69
	v_cos_f32_e32 v12, v69
	v_sin_f32_e64 v13, -v69
	v_mul_u32_u24_e32 v69, 5, v0
	v_cvt_f32_u32_e32 v69, v69
	v_mul_f32_e32 v69, 0x39000000, v69
	v_cos_f32_e32 v14, v69
	v_sin_f32_e64 v15, -v69
	v_mul_u32_u24_e32 v69, 6, v0
	v_cvt_f32_u32_e32 v69, v69
	v_mul_f32_e32 v69, 0x39000000, v69
	v_cos_f32_e32 v16, v69
	v_sin_f32_e64 v17, -v69
	v_mul_u32_u24_e32 v69, 7, v0
	v_cvt_f32_u32_e32 v69, v69
	v_mul_f32_e32 v69, 0x39000000, v69
	v_cos_f32_e32 v18, v69
	v_sin_f32_e64 v19, -v69
	v_mul_u32_u24_e32 v69, 8, v0
	v_cvt_f32_u32_e32 v69, v69
	v_mul_f32_e32 v69, 0x39000000, v69
	v_cos_f32_e32 v20, v69
	v_sin_f32_e64 v21, -v69
	v_mul_u32_u24_e32 v69, 9, v0
	v_cvt_f32_u32_e32 v69, v69
	v_mul_f32_e32 v69, 0x39000000, v69
	v_cos_f32_e32 v22, v69
	v_sin_f32_e64 v23, -v69
	v_mul_u32_u24_e32 v69, 10, v0
	v_cvt_f32_u32_e32 v69, v69
	v_mul_f32_e32 v69, 0x39000000, v69
	v_cos_f32_e32 v24, v69
	v_sin_f32_e64 v25, -v69
	v_mul_u32_u24_e32 v69, 11, v0
	v_cvt_f32_u32_e32 v69, v69
	v_mul_f32_e32 v69, 0x39000000, v69
	v_cos_f32_e32 v26, v69
	v_sin_f32_e64 v27, -v69
	v_mul_u32_u24_e32 v69, 12, v0
	v_cvt_f32_u32_e32 v69, v69
	v_mul_f32_e32 v69, 0x39000000, v69
	v_cos_f32_e32 v28, v69
	v_sin_f32_e64 v29, -v69
	v_mul_u32_u24_e32 v69, 13, v0
	v_cvt_f32_u32_e32 v69, v69
	v_mul_f32_e32 v69, 0x39000000, v69
	v_cos_f32_e32 v30, v69
	v_sin_f32_e64 v31, -v69
	v_mul_u32_u24_e32 v69, 14, v0
	v_cvt_f32_u32_e32 v69, v69
	v_mul_f32_e32 v69, 0x39000000, v69
	v_cos_f32_e32 v32, v69
	v_sin_f32_e64 v33, -v69
	v_mul_u32_u24_e32 v69, 15, v0
	v_cvt_f32_u32_e32 v69, v69
	v_mul_f32_e32 v69, 0x39000000, v69
	v_cos_f32_e32 v34, v69
	v_sin_f32_e64 v35, -v69
	v_mul_u32_u24_e32 v69, 1, v65
	v_cvt_f32_u32_e32 v69, v69
	v_mul_f32_e32 v69, 0x3d000000, v69
	v_cos_f32_e32 v36, v69
	v_sin_f32_e64 v37, -v69
	v_mul_u32_u24_e32 v69, 2, v65
	v_cvt_f32_u32_e32 v69, v69
	v_mul_f32_e32 v69, 0x3d000000, v69
	v_cos_f32_e32 v38, v69
	v_sin_f32_e64 v39, -v69
	v_mul_u32_u24_e32 v69, 3, v65
	v_cvt_f32_u32_e32 v69, v69
	v_mul_f32_e32 v69, 0x3d000000, v69
	v_cos_f32_e32 v40, v69
	v_sin_f32_e64 v41, -v69
	v_mul_u32_u24_e32 v69, 4, v65
	v_cvt_f32_u32_e32 v69, v69
	v_mul_f32_e32 v69, 0x3d000000, v69
	v_cos_f32_e32 v42, v69
	v_sin_f32_e64 v43, -v69
	v_mul_u32_u24_e32 v69, 5, v65
	v_cvt_f32_u32_e32 v69, v69
	v_mul_f32_e32 v69, 0x3d000000, v69
	v_cos_f32_e32 v44, v69
	v_sin_f32_e64 v45, -v69
	v_mul_u32_u24_e32 v69, 6, v65
	v_cvt_f32_u32_e32 v69, v69
	v_mul_f32_e32 v69, 0x3d000000, v69
	v_cos_f32_e32 v46, v69
	v_sin_f32_e64 v47, -v69
	v_mul_u32_u24_e32 v69, 7, v65
	v_cvt_f32_u32_e32 v69, v69
	v_mul_f32_e32 v69, 0x3d000000, v69
	v_cos_f32_e32 v48, v69
	v_sin_f32_e64 v49, -v69
	v_mul_u32_u24_e32 v69, 8, v65
	v_cvt_f32_u32_e32 v69, v69
	v_mul_f32_e32 v69, 0x3d000000, v69
	v_cos_f32_e32 v50, v69
	v_sin_f32_e64 v51, -v69
	v_mul_u32_u24_e32 v69, 9, v65
	v_cvt_f32_u32_e32 v69, v69
	v_mul_f32_e32 v69, 0x3d000000, v69
	v_cos_f32_e32 v52, v69
	v_sin_f32_e64 v53, -v69
	v_mul_u32_u24_e32 v69, 10, v65
	v_cvt_f32_u32_e32 v69, v69
	v_mul_f32_e32 v69, 0x3d000000, v69
	v_cos_f32_e32 v54, v69
	v_sin_f32_e64 v55, -v69
	v_mul_u32_u24_e32 v69, 11, v65
	v_cvt_f32_u32_e32 v69, v69
	v_mul_f32_e32 v69, 0x3d000000, v69
	v_cos_f32_e32 v90, v69
	v_sin_f32_e64 v91, -v69
	v_mul_u32_u24_e32 v69, 12, v65
	v_cvt_f32_u32_e32 v69, v69
	v_mul_f32_e32 v69, 0x3d000000, v69
	v_cos_f32_e32 v92, v69
	v_sin_f32_e64 v93, -v69
	v_mul_u32_u24_e32 v69, 13, v65
	v_cvt_f32_u32_e32 v69, v69
	v_mul_f32_e32 v69, 0x3d000000, v69
	v_cos_f32_e32 v94, v69
	v_sin_f32_e64 v95, -v69
	v_mul_u32_u24_e32 v69, 14, v65
	v_cvt_f32_u32_e32 v69, v69
	v_mul_f32_e32 v69, 0x3d000000, v69
	v_cos_f32_e32 v96, v69
	v_sin_f32_e64 v97, -v69
; #define LAS __attribute__((address_space(3)))
; #define WG_SYNC() do { asm volatile("s_waitcnt lgkmcnt(0)" ::: "memory"); __builtin_amdgcn_s_barrier(); asm volatile("" ::: "memory"); } while (0)
; __device__ __forceinline__ void hy_stage(LAS float* plane, const bf16_t* PHY, int cg, int jc, int tid) {
;     asm volatile("" : "+v"(tid));
;     const u32x4* src = (const u32x4*)(PHY + (size_t)cg * MT * 4);
; #pragma unroll
;     for (int k = 0; k < 8; ++k) { const int i = tid + 512 * k; const u32x4 v = src[i];
;         const unsigned w0 = (jc & 2) ? v.y : v.x, w1 = (jc & 2) ? v.w : v.z;
;         f32x2 o; o.x = (jc & 1) ? bf_hi(w0) : bf_lo(w0); o.y = (jc & 1) ? bf_hi(w1) : bf_lo(w1);
;         *(LAS f32x2*)(plane + 2 * i) = o; }
; }
; __device__ __forceinline__ void hyena_fft(LAS unsigned char* lds, int layer, int G, const int wave_s) {
;     ...
;     {
; #pragma nounroll
;         for (int c = c_lo; c < c_hi; ++c) { const int unit = c >> 2, jc = c & 3;
;             WG_SYNC();
;             { f32x2 x[16]; const unsigned* tf = TF + (size_t)c * SEQ; const unsigned* tb = TB + (size_t)c * SEQ;
; #pragma unroll
;               for (int r = 0; r < 8; ++r) { const unsigned w = tf[n2 + 512 * r]; x[r] = (f32x2){bf_lo(w), bf_hi(w)}; }
; #pragma unroll
;               for (int r = 8; r < 16; ++r) { const int l = FN - 512 * r - n2; const unsigned w = l < SEQ ? tb[l] : 0u; x[r] = (f32x2){bf_lo(w), bf_hi(w)}; }
;               __builtin_amdgcn_sched_barrier(0); fft_fwd1<false>(x, Fb, n2, w1p); __builtin_amdgcn_sched_barrier(0); }
	v_mul_u32_u24_e32 v69, 15, v65
	v_cvt_f32_u32_e32 v69, v69
	v_mul_f32_e32 v69, 0x3d000000, v69
	v_cos_f32_e32 v98, v69
	v_sin_f32_e64 v99, -v69
	v_lshrrev_b32_e32 v69, 5, v0
	v_add_u32_e32 v69, v69, v0
	v_lshlrev_b32_e32 v3, 3, v69
	v_lshrrev_b32_e32 v69, 5, v0
	v_and_b32_e32 v73, 31, v0
	v_mul_u32_u24_e32 v69, 0x210, v69
	v_add_u32_e32 v69, v69, v73
	v_lshlrev_b32_e32 v5, 3, v69
	v_lshlrev_b32_e32 v56, 3, v73
	v_add_u32_e32 v56, 0x21400, v56
	v_and_b32_e32 v69, 31, v157
	v_lshl_add_u32 v69, s43, 5, v69
	v_mul_u32_u24_e32 v156, 0x108, v69
	v_lshl_add_u32 v196, v65, 3, v156
	v_lshl_add_u32 v198, v65, 7, v156
	v_add_u32_e32 v200, 0x10800, v196
	v_lshrrev_b32_e32 v166, 4, v69
	v_and_b32_e32 v167, 15, v69
	v_sub_u32_e32 v174, 16, v166
	v_and_b32_e32 v174, 15, v174
	v_add_u32_e32 v168, 15, v166
	v_lshrrev_b32_e32 v168, 4, v168
	v_sub_u32_e32 v73, 16, v167
	v_sub_u32_e32 v73, v73, v168
	v_and_b32_e32 v73, 15, v73
	v_lshl_add_u32 v174, v174, 4, v73
	v_add_u32_e32 v169, 15, v167
	v_lshrrev_b32_e32 v169, 4, v169
	v_or_b32_e32 v169, v169, v168
	v_mul_u32_u24_e32 v174, 0x108, v174
	v_add_u32_e32 v174, 0x10800, v174
	v_add_u32_e32 v73, v169, v65
	v_sub_u32_e32 v73, 1, v73
	v_lshlrev_b32_e32 v73, 3, v73
	v_add_u32_e32 v202, v174, v73
	v_add_u32_e32 v73, 0xf8, v174
	v_cmp_ne_u32_e64 s[10:11], v169, 0
	s_nop 1
	v_cndmask_b32_e64 v73, v200, v73, s[10:11]
	v_add_u32_e32 v69, 0xf8, v202
	v_cmp_ne_u32_e64 s[10:11], v65, 0
	s_nop 1
	v_cndmask_b32_e64 v204, v73, v69, s[10:11]
	v_lshlrev_b32_e32 v206, 3, v0
	v_lshlrev_b32_e32 v208, 2, v0
	v_mov_b32_e32 v69, 0
	v_cmp_eq_u32_e64 s[10:11], v0, 0
	s_mov_b32 s53, 0x1ff
	v_cmp_eq_u32_e64 s[28:29], v0, s53
	v_add_u32_e32 v73, -4, v208
	s_nop 0
	v_cndmask_b32_e64 v210, v73, v69, s[10:11]
	v_mov_b32_e32 v212, v208
	v_sub_u32_e32 v214, 0x800, v208
	v_lshlrev_b32_e32 v216, 4, v0
	v_add_u32_e32 v218, 0x2000, v216
	v_add_u32_e32 v220, 0x4000, v216
	v_add_u32_e32 v222, 0x6000, v216
	v_add_u32_e32 v240, 0x8000, v216
	v_add_u32_e32 v242, 0xa000, v216
	v_add_u32_e32 v244, 0xc000, v216
	v_add_u32_e32 v61, 0xe000, v216
	s_waitcnt lgkmcnt(0)
	s_lshl_b32 s53, s76, 24
	s_add_u32 s36, s60, 0x160a6000
	s_addc_u32 s37, s61, 0
	s_add_u32 s36, s36, s53
	s_addc_u32 s37, s37, 0
	s_add_u32 s38, s60, 0x6820000
	s_addc_u32 s39, s61, 0
	s_add_u32 s40, s60, 0xd6a0000
	s_addc_u32 s41, s61, 0
.Lhfft_loop:
	s_lshr_b32 s43, s80, 2
	s_mul_i32 s73, s43, 0x11000
	s_and_b32 s43, s80, 2
	s_lshl_b32 s43, s43, 1
	s_add_u32 s73, s73, s43
	s_and_b32 s43, s80, 1
	s_mov_b32 s15, 0x1000c0c
	s_cmp_eq_u32 s43, 0
	s_cselect_b32 s15, s15, 0x3020c0c
	s_lshl_b32 s43, s80, 14
	s_add_u32 s46, s36, s43
	s_addc_u32 s47, s37, 0
	s_add_u32 s50, s46, 0x4000000
	s_addc_u32 s51, s47, 0
	s_waitcnt lgkmcnt(0)
	s_barrier
	s_cbranch_vccz .Lhfft_st1
	s_sleep 4
.Lhfft_st1:
	s_add_u32 s60, s46, 0
	s_addc_u32 s61, s47, 0
	global_load_dword v176, v212, s[60:61]
	global_load_dword v178, v212, s[60:61] offset:2048
	s_add_u32 s60, s46, 0x1000
	s_addc_u32 s61, s47, 0
	global_load_dword v180, v212, s[60:61]
	global_load_dword v182, v212, s[60:61] offset:2048
	s_add_u32 s60, s46, 0x2000
	s_addc_u32 s61, s47, 0
	global_load_dword v184, v212, s[60:61]
	global_load_dword v186, v212, s[60:61] offset:2048
	s_add_u32 s60, s46, 0x3000
	s_addc_u32 s61, s47, 0
	global_load_dword v188, v212, s[60:61]
	global_load_dword v166, v212, s[60:61] offset:2048
	s_add_u32 s62, s50, 0x3000
	s_addc_u32 s63, s51, 0
	global_load_dword v177, v214, s[62:63] offset:2048
	global_load_dword v179, v214, s[62:63]
	s_add_u32 s62, s50, 0x2000
	s_addc_u32 s63, s51, 0
	global_load_dword v181, v214, s[62:63] offset:2048
	global_load_dword v183, v214, s[62:63]
	s_add_u32 s62, s50, 0x1000
	s_addc_u32 s63, s51, 0
	global_load_dword v185, v214, s[62:63] offset:2048
	global_load_dword v187, v214, s[62:63]
	s_add_u32 s62, s50, 0
	s_addc_u32 s63, s51, 0
	global_load_dword v189, v214, s[62:63] offset:2048
	global_load_dword v167, v214, s[62:63]
	s_add_u32 s56, s38, s73
	s_addc_u32 s57, s39, 0
	s_add_u32 s56, s56, 0x2200000
	s_addc_u32 s57, s57, 0
	global_load_dwordx3 v[58:60], v216, s[56:57]
	global_load_dwordx3 v[62:64], v218, s[56:57]
	global_load_dwordx3 v[66:68], v220, s[56:57]
	global_load_dwordx3 v[70:72], v222, s[56:57]
	global_load_dwordx3 v[74:76], v240, s[56:57]
	global_load_dwordx3 v[78:80], v242, s[56:57]
	global_load_dwordx3 v[82:84], v244, s[56:57]
	global_load_dwordx3 v[86:88], v61, s[56:57]
	s_waitcnt vmcnt(23)
	v_and_b32_e32 v101, 0xffff0000, v176
	v_lshlrev_b32_e32 v100, 16, v176
	s_waitcnt vmcnt(22)
	v_and_b32_e32 v103, 0xffff0000, v178
	v_lshlrev_b32_e32 v102, 16, v178
	s_waitcnt vmcnt(21)
	v_and_b32_e32 v105, 0xffff0000, v180
	v_lshlrev_b32_e32 v104, 16, v180
	s_waitcnt vmcnt(20)
	v_and_b32_e32 v107, 0xffff0000, v182
	v_lshlrev_b32_e32 v106, 16, v182
	s_waitcnt vmcnt(19)
	v_and_b32_e32 v109, 0xffff0000, v184
	v_lshlrev_b32_e32 v108, 16, v184
	s_waitcnt vmcnt(18)
	v_and_b32_e32 v111, 0xffff0000, v186
	v_lshlrev_b32_e32 v110, 16, v186
	s_waitcnt vmcnt(17)
	v_and_b32_e32 v113, 0xffff0000, v188
	v_lshlrev_b32_e32 v112, 16, v188
	s_waitcnt vmcnt(16)
	v_and_b32_e32 v115, 0xffff0000, v166
	v_lshlrev_b32_e32 v114, 16, v166
	s_waitcnt vmcnt(15)
	v_cndmask_b32_e64 v177, v177, 0, s[10:11]
	v_and_b32_e32 v117, 0xffff0000, v177
	v_lshlrev_b32_e32 v116, 16, v177
	s_waitcnt vmcnt(14)
	v_and_b32_e32 v119, 0xffff0000, v179
	v_lshlrev_b32_e32 v118, 16, v179
	s_waitcnt vmcnt(13)
	v_and_b32_e32 v121, 0xffff0000, v181
	v_lshlrev_b32_e32 v120, 16, v181
	s_waitcnt vmcnt(12)
	v_and_b32_e32 v123, 0xffff0000, v183
	v_lshlrev_b32_e32 v122, 16, v183
	s_waitcnt vmcnt(11)
	v_and_b32_e32 v125, 0xffff0000, v185
	v_lshlrev_b32_e32 v124, 16, v185
	s_waitcnt vmcnt(10)
; template <bool INV> __device__ __forceinline__ f32x2 cmul_tw(f32x2 a, f32x2 w) { return INV ? cmulc(a, w) : cmul(a, w); }
; template <bool INV> __device__ __forceinline__ void dft16(f32x2 (&x)[16]) {
;     constexpr float C1 = 0.92387953251128674f, S1 = 0.38268343236508977f, C2 = 0.70710678118654752f;
; #pragma unroll
;     for (int b = 0; b < 4; ++b) dft4<INV>(x[b], x[4 + b], x[8 + b], x[12 + b]);
;     const f32x2 w1 = {C1, -S1}, w2 = {C2, -C2}, w3 = {S1, -C1}, w4 = {0.f, -1.f}, w6 = {-C2, -C2}, w9 = {-C1, S1};
;     x[4 * 1 + 1] = cmul_tw<INV>(x[5], w1); x[4 * 1 + 2] = cmul_tw<INV>(x[6], w2); x[4 * 1 + 3] = cmul_tw<INV>(x[7], w3);
;     x[4 * 2 + 1] = cmul_tw<INV>(x[9], w2); x[4 * 2 + 2] = cmul_tw<INV>(x[10], w4); x[4 * 2 + 3] = cmul_tw<INV>(x[11], w6);
;     x[4 * 3 + 1] = cmul_tw<INV>(x[13], w3); x[4 * 3 + 2] = cmul_tw<INV>(x[14], w6); x[4 * 3 + 3] = cmul_tw<INV>(x[15], w9);
; #pragma unroll
;     for (int c = 0; c < 4; ++c) dft4<INV>(x[4 * c], x[4 * c + 1], x[4 * c + 2], x[4 * c + 3]);
;     f32x2 y[16];
; #pragma unroll
;     for (int k = 0; k < 16; ++k) y[k] = x[4 * (k & 3) + (k >> 2)];
; #pragma unroll
;     for (int k = 0; k < 16; ++k) x[k] = y[k];
; }
; template <bool LO> __device__ __forceinline__ void fft_fwd1(f32x2 (&x)[16], LAS f32x2* B, int n2, const f32x2 (&w)[16]) {
;     ...
;     if (LO) dft16_fwd_lo(x); else dft16<false>(x);
	v_and_b32_e32 v127, 0xffff0000, v187
	v_lshlrev_b32_e32 v126, 16, v187
	s_waitcnt vmcnt(9)
	v_and_b32_e32 v129, 0xffff0000, v189
	v_lshlrev_b32_e32 v128, 16, v189
	s_waitcnt vmcnt(8)
	v_and_b32_e32 v131, 0xffff0000, v167
	v_lshlrev_b32_e32 v130, 16, v167
	v_pk_add_f32 v[168:169], v[100:101], v[116:117]
	v_pk_add_f32 v[174:175], v[100:101], v[116:117] neg_lo:[0,1] neg_hi:[0,1]
	v_pk_add_f32 v[176:177], v[108:109], v[124:125]
	v_pk_add_f32 v[178:179], v[108:109], v[124:125] neg_lo:[0,1] neg_hi:[0,1]
	v_pk_add_f32 v[100:101], v[168:169], v[176:177]
	v_pk_add_f32 v[116:117], v[168:169], v[176:177] neg_lo:[0,1] neg_hi:[0,1]
	v_pk_add_f32 v[108:109], v[174:175], v[178:179] op_sel:[0,1] op_sel_hi:[1,0] neg_hi:[0,1]
	v_pk_add_f32 v[124:125], v[174:175], v[178:179] op_sel:[0,1] op_sel_hi:[1,0] neg_lo:[0,1]
	v_pk_add_f32 v[180:181], v[102:103], v[118:119]
	v_pk_add_f32 v[182:183], v[102:103], v[118:119] neg_lo:[0,1] neg_hi:[0,1]
	v_pk_add_f32 v[184:185], v[110:111], v[126:127]
	v_pk_add_f32 v[186:187], v[110:111], v[126:127] neg_lo:[0,1] neg_hi:[0,1]
	v_pk_add_f32 v[102:103], v[180:181], v[184:185]
	v_pk_add_f32 v[118:119], v[180:181], v[184:185] neg_lo:[0,1] neg_hi:[0,1]
	v_pk_add_f32 v[110:111], v[182:183], v[186:187] op_sel:[0,1] op_sel_hi:[1,0] neg_hi:[0,1]
	v_pk_add_f32 v[126:127], v[182:183], v[186:187] op_sel:[0,1] op_sel_hi:[1,0] neg_lo:[0,1]
	v_pk_add_f32 v[188:189], v[104:105], v[120:121]
	v_pk_add_f32 v[166:167], v[104:105], v[120:121] neg_lo:[0,1] neg_hi:[0,1]
	v_pk_add_f32 v[168:169], v[112:113], v[128:129]
	v_pk_add_f32 v[174:175], v[112:113], v[128:129] neg_lo:[0,1] neg_hi:[0,1]
	v_pk_add_f32 v[104:105], v[188:189], v[168:169]
	v_pk_add_f32 v[120:121], v[188:189], v[168:169] neg_lo:[0,1] neg_hi:[0,1]
	v_pk_add_f32 v[112:113], v[166:167], v[174:175] op_sel:[0,1] op_sel_hi:[1,0] neg_hi:[0,1]
	v_pk_add_f32 v[128:129], v[166:167], v[174:175] op_sel:[0,1] op_sel_hi:[1,0] neg_lo:[0,1]
	v_pk_add_f32 v[176:177], v[106:107], v[122:123]
	v_pk_add_f32 v[178:179], v[106:107], v[122:123] neg_lo:[0,1] neg_hi:[0,1]
	v_pk_add_f32 v[180:181], v[114:115], v[130:131]
	v_pk_add_f32 v[182:183], v[114:115], v[130:131] neg_lo:[0,1] neg_hi:[0,1]
	v_pk_add_f32 v[106:107], v[176:177], v[180:181]
	v_pk_add_f32 v[122:123], v[176:177], v[180:181] neg_lo:[0,1] neg_hi:[0,1]
	v_pk_add_f32 v[114:115], v[178:179], v[182:183] op_sel:[0,1] op_sel_hi:[1,0] neg_hi:[0,1]
	v_pk_add_f32 v[130:131], v[178:179], v[182:183] op_sel:[0,1] op_sel_hi:[1,0] neg_lo:[0,1]
	v_pk_mul_f32 v[184:185], v[110:111], s[68:69] op_sel:[1,1] op_sel_hi:[0,1]
	v_pk_fma_f32 v[110:111], v[110:111], s[68:69], v[184:185] op_sel_hi:[1,0,1] neg_lo:[0,0,1]
	v_pk_mul_f32 v[186:187], v[112:113], s[84:85] op_sel:[1,1] op_sel_hi:[0,1]
	v_pk_fma_f32 v[112:113], v[112:113], s[84:85], v[186:187] op_sel_hi:[1,0,1] neg_lo:[0,0,1]
	v_pk_mul_f32 v[188:189], v[114:115], s[88:89] op_sel:[1,1] op_sel_hi:[0,1]
	v_pk_fma_f32 v[114:115], v[114:115], s[88:89], v[188:189] op_sel_hi:[1,0,1] neg_lo:[0,0,1]
	v_pk_mul_f32 v[166:167], v[118:119], s[84:85] op_sel:[1,1] op_sel_hi:[0,1]
	v_pk_fma_f32 v[118:119], v[118:119], s[84:85], v[166:167] op_sel_hi:[1,0,1] neg_lo:[0,0,1]
	v_pk_mul_f32 v[168:169], v[122:123], s[90:91] op_sel:[1,1] op_sel_hi:[0,1]
	v_pk_fma_f32 v[122:123], v[122:123], s[90:91], v[168:169] op_sel_hi:[1,0,1] neg_lo:[0,0,1]
	v_pk_mul_f32 v[174:175], v[126:127], s[88:89] op_sel:[1,1] op_sel_hi:[0,1]
	v_pk_fma_f32 v[126:127], v[126:127], s[88:89], v[174:175] op_sel_hi:[1,0,1] neg_lo:[0,0,1]
	v_pk_mul_f32 v[176:177], v[128:129], s[90:91] op_sel:[1,1] op_sel_hi:[0,1]
	v_pk_fma_f32 v[128:129], v[128:129], s[90:91], v[176:177] op_sel_hi:[1,0,1] neg_lo:[0,0,1]
	v_pk_mul_f32 v[178:179], v[130:131], s[98:99] op_sel:[1,1] op_sel_hi:[0,1]
	v_pk_fma_f32 v[130:131], v[130:131], s[98:99], v[178:179] op_sel_hi:[1,0,1] neg_lo:[0,0,1]
	v_pk_add_f32 v[180:181], v[100:101], v[104:105]
	v_pk_add_f32 v[182:183], v[100:101], v[104:105] neg_lo:[0,1] neg_hi:[0,1]
	v_pk_add_f32 v[184:185], v[102:103], v[106:107]
	v_pk_add_f32 v[186:187], v[102:103], v[106:107] neg_lo:[0,1] neg_hi:[0,1]
	v_pk_add_f32 v[100:101], v[180:181], v[184:185]
	v_pk_add_f32 v[104:105], v[180:181], v[184:185] neg_lo:[0,1] neg_hi:[0,1]
	v_pk_add_f32 v[102:103], v[182:183], v[186:187] op_sel:[0,1] op_sel_hi:[1,0] neg_hi:[0,1]
	v_pk_add_f32 v[106:107], v[182:183], v[186:187] op_sel:[0,1] op_sel_hi:[1,0] neg_lo:[0,1]
	v_pk_add_f32 v[188:189], v[108:109], v[112:113]
	v_pk_add_f32 v[166:167], v[108:109], v[112:113] neg_lo:[0,1] neg_hi:[0,1]
	v_pk_add_f32 v[168:169], v[110:111], v[114:115]
	v_pk_add_f32 v[174:175], v[110:111], v[114:115] neg_lo:[0,1] neg_hi:[0,1]
	v_pk_add_f32 v[108:109], v[188:189], v[168:169]
	v_pk_add_f32 v[112:113], v[188:189], v[168:169] neg_lo:[0,1] neg_hi:[0,1]
	v_pk_add_f32 v[110:111], v[166:167], v[174:175] op_sel:[0,1] op_sel_hi:[1,0] neg_hi:[0,1]
	v_pk_add_f32 v[114:115], v[166:167], v[174:175] op_sel:[0,1] op_sel_hi:[1,0] neg_lo:[0,1]
	v_pk_add_f32 v[176:177], v[116:117], v[120:121] op_sel:[0,1] op_sel_hi:[1,0] neg_hi:[0,1]
	v_pk_add_f32 v[178:179], v[116:117], v[120:121] op_sel:[0,1] op_sel_hi:[1,0] neg_lo:[0,1]
	v_pk_add_f32 v[180:181], v[118:119], v[122:123]
	v_pk_add_f32 v[182:183], v[118:119], v[122:123] neg_lo:[0,1] neg_hi:[0,1]
	v_pk_add_f32 v[116:117], v[176:177], v[180:181]
	v_pk_add_f32 v[120:121], v[176:177], v[180:181] neg_lo:[0,1] neg_hi:[0,1]
	v_pk_add_f32 v[118:119], v[178:179], v[182:183] op_sel:[0,1] op_sel_hi:[1,0] neg_hi:[0,1]
	v_pk_add_f32 v[122:123], v[178:179], v[182:183] op_sel:[0,1] op_sel_hi:[1,0] neg_lo:[0,1]
	v_pk_add_f32 v[184:185], v[124:125], v[128:129]
	v_pk_add_f32 v[186:187], v[124:125], v[128:129] neg_lo:[0,1] neg_hi:[0,1]
; #define LAS __attribute__((address_space(3)))
; #define WG_SYNC() do { asm volatile("s_waitcnt lgkmcnt(0)" ::: "memory"); __builtin_amdgcn_s_barrier(); asm volatile("" ::: "memory"); } while (0)
; __device__ __forceinline__ void hy_stage(LAS float* plane, const bf16_t* PHY, int cg, int jc, int tid) {
;     asm volatile("" : "+v"(tid));
;     const u32x4* src = (const u32x4*)(PHY + (size_t)cg * MT * 4);
; #pragma unroll
;     for (int k = 0; k < 8; ++k) { const int i = tid + 512 * k; const u32x4 v = src[i];
;         const unsigned w0 = (jc & 2) ? v.y : v.x, w1 = (jc & 2) ? v.w : v.z;
;         f32x2 o; o.x = (jc & 1) ? bf_hi(w0) : bf_lo(w0); o.y = (jc & 1) ? bf_hi(w1) : bf_lo(w1);
;         *(LAS f32x2*)(plane + 2 * i) = o; }
; }
; __device__ __forceinline__ void hyena_fft(LAS unsigned char* lds, int layer, int G, const int wave_s) {
;     ...
;               __builtin_amdgcn_sched_barrier(0); fft_fwd1<false>(x, Fb, n2, w1p); __builtin_amdgcn_sched_barrier(0); }
;             hy_stage(pl0, PHY, 2 * (HY / 4) + unit, jc, tid); __builtin_amdgcn_sched_barrier(0); hy_stage(pl1, PHY, unit, jc, tid); __builtin_amdgcn_sched_barrier(0);
;             WG_SYNC();
	v_pk_add_f32 v[188:189], v[126:127], v[130:131]
	v_pk_add_f32 v[166:167], v[126:127], v[130:131] neg_lo:[0,1] neg_hi:[0,1]
	v_pk_add_f32 v[124:125], v[184:185], v[188:189]
	v_pk_add_f32 v[128:129], v[184:185], v[188:189] neg_lo:[0,1] neg_hi:[0,1]
	v_pk_add_f32 v[126:127], v[186:187], v[166:167] op_sel:[0,1] op_sel_hi:[1,0] neg_hi:[0,1]
	v_pk_add_f32 v[130:131], v[186:187], v[166:167] op_sel:[0,1] op_sel_hi:[1,0] neg_lo:[0,1]
	v_add_u32_e32 v65, 0x10800, v3
	ds_write_b64 v65, v[100:101]
	v_pk_mul_f32 v[174:175], v[108:109], v[6:7] op_sel:[1,1] op_sel_hi:[0,1]
	v_pk_fma_f32 v[168:169], v[108:109], v[6:7], v[174:175] op_sel_hi:[1,0,1] neg_lo:[0,0,1]
	ds_write_b64 v65, v[168:169] offset:4224
	v_pk_mul_f32 v[178:179], v[116:117], v[8:9] op_sel:[1,1] op_sel_hi:[0,1]
	v_pk_fma_f32 v[176:177], v[116:117], v[8:9], v[178:179] op_sel_hi:[1,0,1] neg_lo:[0,0,1]
	ds_write_b64 v65, v[176:177] offset:8448
	v_pk_mul_f32 v[182:183], v[124:125], v[10:11] op_sel:[1,1] op_sel_hi:[0,1]
	v_pk_fma_f32 v[180:181], v[124:125], v[10:11], v[182:183] op_sel_hi:[1,0,1] neg_lo:[0,0,1]
	ds_write_b64 v65, v[180:181] offset:12672
	v_pk_mul_f32 v[186:187], v[102:103], v[12:13] op_sel:[1,1] op_sel_hi:[0,1]
	v_pk_fma_f32 v[184:185], v[102:103], v[12:13], v[186:187] op_sel_hi:[1,0,1] neg_lo:[0,0,1]
	ds_write_b64 v65, v[184:185] offset:16896
	v_pk_mul_f32 v[166:167], v[110:111], v[14:15] op_sel:[1,1] op_sel_hi:[0,1]
	v_pk_fma_f32 v[188:189], v[110:111], v[14:15], v[166:167] op_sel_hi:[1,0,1] neg_lo:[0,0,1]
	ds_write_b64 v65, v[188:189] offset:21120
	v_pk_mul_f32 v[168:169], v[118:119], v[16:17] op_sel:[1,1] op_sel_hi:[0,1]
	v_pk_fma_f32 v[174:175], v[118:119], v[16:17], v[168:169] op_sel_hi:[1,0,1] neg_lo:[0,0,1]
	ds_write_b64 v65, v[174:175] offset:25344
	v_pk_mul_f32 v[176:177], v[126:127], v[18:19] op_sel:[1,1] op_sel_hi:[0,1]
	v_pk_fma_f32 v[178:179], v[126:127], v[18:19], v[176:177] op_sel_hi:[1,0,1] neg_lo:[0,0,1]
	ds_write_b64 v65, v[178:179] offset:29568
	v_pk_mul_f32 v[180:181], v[104:105], v[20:21] op_sel:[1,1] op_sel_hi:[0,1]
	v_pk_fma_f32 v[182:183], v[104:105], v[20:21], v[180:181] op_sel_hi:[1,0,1] neg_lo:[0,0,1]
	ds_write_b64 v65, v[182:183] offset:33792
	v_pk_mul_f32 v[184:185], v[112:113], v[22:23] op_sel:[1,1] op_sel_hi:[0,1]
	v_pk_fma_f32 v[186:187], v[112:113], v[22:23], v[184:185] op_sel_hi:[1,0,1] neg_lo:[0,0,1]
	ds_write_b64 v65, v[186:187] offset:38016
	v_pk_mul_f32 v[188:189], v[120:121], v[24:25] op_sel:[1,1] op_sel_hi:[0,1]
	v_pk_fma_f32 v[166:167], v[120:121], v[24:25], v[188:189] op_sel_hi:[1,0,1] neg_lo:[0,0,1]
	ds_write_b64 v65, v[166:167] offset:42240
	v_pk_mul_f32 v[174:175], v[128:129], v[26:27] op_sel:[1,1] op_sel_hi:[0,1]
	v_pk_fma_f32 v[168:169], v[128:129], v[26:27], v[174:175] op_sel_hi:[1,0,1] neg_lo:[0,0,1]
	ds_write_b64 v65, v[168:169] offset:46464
	v_pk_mul_f32 v[178:179], v[106:107], v[28:29] op_sel:[1,1] op_sel_hi:[0,1]
	v_pk_fma_f32 v[176:177], v[106:107], v[28:29], v[178:179] op_sel_hi:[1,0,1] neg_lo:[0,0,1]
	ds_write_b64 v65, v[176:177] offset:50688
	v_pk_mul_f32 v[182:183], v[114:115], v[30:31] op_sel:[1,1] op_sel_hi:[0,1]
	v_pk_fma_f32 v[180:181], v[114:115], v[30:31], v[182:183] op_sel_hi:[1,0,1] neg_lo:[0,0,1]
	ds_write_b64 v65, v[180:181] offset:54912
	v_pk_mul_f32 v[186:187], v[122:123], v[32:33] op_sel:[1,1] op_sel_hi:[0,1]
	v_pk_fma_f32 v[184:185], v[122:123], v[32:33], v[186:187] op_sel_hi:[1,0,1] neg_lo:[0,0,1]
	ds_write_b64 v65, v[184:185] offset:59136
	v_pk_mul_f32 v[166:167], v[130:131], v[34:35] op_sel:[1,1] op_sel_hi:[0,1]
	v_pk_fma_f32 v[188:189], v[130:131], v[34:35], v[166:167] op_sel_hi:[1,0,1] neg_lo:[0,0,1]
	ds_write_b64 v65, v[188:189] offset:63360
	s_waitcnt vmcnt(7)
	v_perm_b32 v174, 0, v58, s15
	v_perm_b32 v175, 0, v60, s15
	ds_write_b64 v206, v[174:175]
	s_waitcnt vmcnt(6)
	v_perm_b32 v168, 0, v62, s15
	v_perm_b32 v169, 0, v64, s15
	ds_write_b64 v206, v[168:169] offset:4096
	s_waitcnt vmcnt(5)
	v_perm_b32 v178, 0, v66, s15
	v_perm_b32 v179, 0, v68, s15
	ds_write_b64 v206, v[178:179] offset:8192
	s_waitcnt vmcnt(4)
	v_perm_b32 v176, 0, v70, s15
	v_perm_b32 v177, 0, v72, s15
	ds_write_b64 v206, v[176:177] offset:12288
	s_waitcnt vmcnt(3)
	v_perm_b32 v182, 0, v74, s15
	v_perm_b32 v183, 0, v76, s15
	ds_write_b64 v206, v[182:183] offset:16384
	s_waitcnt vmcnt(2)
	v_perm_b32 v180, 0, v78, s15
	v_perm_b32 v181, 0, v80, s15
	ds_write_b64 v206, v[180:181] offset:20480
	s_waitcnt vmcnt(1)
	v_perm_b32 v186, 0, v82, s15
	v_perm_b32 v187, 0, v84, s15
	ds_write_b64 v206, v[186:187] offset:24576
	s_waitcnt vmcnt(0)
	v_perm_b32 v184, 0, v86, s15
	v_perm_b32 v185, 0, v88, s15
	ds_write_b64 v206, v[184:185] offset:28672
	s_add_u32 s56, s38, s73
	s_addc_u32 s57, s39, 0
	global_load_dwordx3 v[58:60], v216, s[56:57]
	global_load_dwordx3 v[62:64], v218, s[56:57]
	global_load_dwordx3 v[66:68], v220, s[56:57]
	global_load_dwordx3 v[70:72], v222, s[56:57]
	global_load_dwordx3 v[74:76], v240, s[56:57]
	global_load_dwordx3 v[78:80], v242, s[56:57]
	global_load_dwordx3 v[82:84], v244, s[56:57]
	global_load_dwordx3 v[86:88], v61, s[56:57]
	s_load_dwordx2 s[60:61], s[94:95], 0x48
	s_load_dwordx2 s[62:63], s[94:95], 0x50
	s_load_dwordx2 s[50:51], s[94:95], 0x88
	s_lshl_b32 s43, s80, 2
	s_mul_i32 s53, s76, 0x9000
	s_add_u32 s53, s53, s43
	s_mul_i32 s55, s76, 0x3000
	s_add_u32 s55, s55, s43
	s_waitcnt lgkmcnt(0)
	s_add_u32 s60, s60, s53
	s_addc_u32 s61, s61, 0
	s_add_u32 s62, s62, s55
	s_addc_u32 s63, s63, 0
	s_mul_i32 s53, s76, 0x2000
	s_add_u32 s53, s53, s43
	s_add_u32 s50, s50, s53
	s_addc_u32 s51, s51, 0
	s_load_dword s17, s[60:61], 0x2000
	s_load_dword s23, s[60:61], 0x5000
	s_load_dword s25, s[60:61], 0x8000
	s_load_dword s26, s[62:63], 0x2000
	s_waitcnt lgkmcnt(0)
	s_barrier
	s_cbranch_vccz .Lhfft_st2
	s_sleep 4
; #define LAS __attribute__((address_space(3)))
; __device__ __forceinline__ void hy_sconv(const LAS float* plane, float w0, float w1, float w2, float cb, int n2, float (&u)[8][2]) {
;     asm volatile("" : "+v"(n2));
; #pragma unroll
;     for (int r = 0; r < 8; ++r)
; #pragma unroll
;         for (int b = 0; b < 2; ++b) { const int t = n2 + 512 * r, row = b * SEQ + t;
;             float a = cb + w1 * plane[row];
;             if (t > 0) a += w0 * plane[row - 1];
;             if (t < SEQ - 1) a += w2 * plane[row + 1];
;             u[r][b] = a; }
; }
; __device__ __forceinline__ void hyena_fft(LAS unsigned char* lds, int layer, int G, const int wave_s) {
;     ...
;             hy_stage(pl0, PHY, 2 * (HY / 4) + unit, jc, tid); __builtin_amdgcn_sched_barrier(0); hy_stage(pl1, PHY, unit, jc, tid); __builtin_amdgcn_sched_barrier(0);
;     ...
;             hy_sconv(pl0, cw[2 * HY + c], cw[3 * HY + 2 * HY + c], cw[6 * HY + 2 * HY + c], cb[2 * HY + c], n2, uz);
.Lhfft_st2:
	v_mov_b32_e32 v166, s17
	v_mov_b32_e32 v167, s23
	v_mov_b32_e32 v188, s25
	v_mov_b32_e32 v189, s26
	ds_read_b32 v174, v208
	ds_read_b32 v168, v210
	ds_read_b32 v178, v208 offset:4
	ds_read_b32 v175, v208 offset:16384
	ds_read_b32 v169, v210 offset:16384
	ds_read_b32 v179, v208 offset:16388
	ds_read_b32 v176, v208 offset:2048
	ds_read_b32 v182, v208 offset:2044
	ds_read_b32 v180, v208 offset:2052
	ds_read_b32 v177, v208 offset:18432
	ds_read_b32 v183, v208 offset:18428
	ds_read_b32 v181, v208 offset:18436
	s_waitcnt lgkmcnt(10)
	v_cndmask_b32_e64 v168, v168, 0, s[10:11]
	s_waitcnt lgkmcnt(7)
	v_cndmask_b32_e64 v169, v169, 0, s[10:11]
	v_pk_fma_f32 v[132:133], v[166:167], v[174:175], v[188:189] op_sel:[1,0,1]
	v_pk_fma_f32 v[132:133], v[166:167], v[168:169], v[132:133] op_sel_hi:[0,1,1]
	s_waitcnt lgkmcnt(6)
	v_pk_fma_f32 v[132:133], v[188:189], v[178:179], v[132:133] op_sel_hi:[0,1,1]
	s_waitcnt lgkmcnt(2)
	v_pk_fma_f32 v[134:135], v[166:167], v[176:177], v[188:189] op_sel:[1,0,1]
	s_waitcnt lgkmcnt(1)
	v_pk_fma_f32 v[134:135], v[166:167], v[182:183], v[134:135] op_sel_hi:[0,1,1]
	s_waitcnt lgkmcnt(0)
	v_pk_fma_f32 v[134:135], v[188:189], v[180:181], v[134:135] op_sel_hi:[0,1,1]
	ds_read_b32 v186, v208 offset:4096
	ds_read_b32 v184, v208 offset:4092
	ds_read_b32 v174, v208 offset:4100
	ds_read_b32 v187, v208 offset:20480
	ds_read_b32 v185, v208 offset:20476
	ds_read_b32 v175, v208 offset:20484
	ds_read_b32 v168, v208 offset:6144
	ds_read_b32 v178, v208 offset:6140
	ds_read_b32 v176, v208 offset:6148
	ds_read_b32 v169, v208 offset:22528
	ds_read_b32 v179, v208 offset:22524
	ds_read_b32 v177, v208 offset:22532
	s_waitcnt lgkmcnt(8)
	v_pk_fma_f32 v[136:137], v[166:167], v[186:187], v[188:189] op_sel:[1,0,1]
	s_waitcnt lgkmcnt(7)
	v_pk_fma_f32 v[136:137], v[166:167], v[184:185], v[136:137] op_sel_hi:[0,1,1]
	s_waitcnt lgkmcnt(6)
	v_pk_fma_f32 v[136:137], v[188:189], v[174:175], v[136:137] op_sel_hi:[0,1,1]
	s_waitcnt lgkmcnt(2)
	v_pk_fma_f32 v[138:139], v[166:167], v[168:169], v[188:189] op_sel:[1,0,1]
	s_waitcnt lgkmcnt(1)
	v_pk_fma_f32 v[138:139], v[166:167], v[178:179], v[138:139] op_sel_hi:[0,1,1]
	s_waitcnt lgkmcnt(0)
	v_pk_fma_f32 v[138:139], v[188:189], v[176:177], v[138:139] op_sel_hi:[0,1,1]
	ds_read_b32 v182, v208 offset:8192
	ds_read_b32 v180, v208 offset:8188
	ds_read_b32 v186, v208 offset:8196
	ds_read_b32 v183, v208 offset:24576
	ds_read_b32 v181, v208 offset:24572
	ds_read_b32 v187, v208 offset:24580
	ds_read_b32 v184, v208 offset:10240
	ds_read_b32 v174, v208 offset:10236
	ds_read_b32 v168, v208 offset:10244
	ds_read_b32 v185, v208 offset:26624
	ds_read_b32 v175, v208 offset:26620
	ds_read_b32 v169, v208 offset:26628
	s_waitcnt lgkmcnt(8)
	v_pk_fma_f32 v[140:141], v[166:167], v[182:183], v[188:189] op_sel:[1,0,1]
	s_waitcnt lgkmcnt(7)
	v_pk_fma_f32 v[140:141], v[166:167], v[180:181], v[140:141] op_sel_hi:[0,1,1]
	s_waitcnt lgkmcnt(6)
	v_pk_fma_f32 v[140:141], v[188:189], v[186:187], v[140:141] op_sel_hi:[0,1,1]
	s_waitcnt lgkmcnt(2)
	v_pk_fma_f32 v[142:143], v[166:167], v[184:185], v[188:189] op_sel:[1,0,1]
	s_waitcnt lgkmcnt(1)
	v_pk_fma_f32 v[142:143], v[166:167], v[174:175], v[142:143] op_sel_hi:[0,1,1]
	s_waitcnt lgkmcnt(0)
	v_pk_fma_f32 v[142:143], v[188:189], v[168:169], v[142:143] op_sel_hi:[0,1,1]
	ds_read_b32 v178, v208 offset:12288
	ds_read_b32 v176, v208 offset:12284
	ds_read_b32 v182, v208 offset:12292
	ds_read_b32 v179, v208 offset:28672
	ds_read_b32 v177, v208 offset:28668
	ds_read_b32 v183, v208 offset:28676
	ds_read_b32 v180, v208 offset:14336
	ds_read_b32 v186, v208 offset:14332
	ds_read_b32 v184, v208 offset:14340
	ds_read_b32 v181, v208 offset:30720
	ds_read_b32 v187, v208 offset:30716
	ds_read_b32 v185, v208 offset:30724
	s_waitcnt lgkmcnt(8)
	v_pk_fma_f32 v[144:145], v[166:167], v[178:179], v[188:189] op_sel:[1,0,1]
	s_waitcnt lgkmcnt(7)
	v_pk_fma_f32 v[144:145], v[166:167], v[176:177], v[144:145] op_sel_hi:[0,1,1]
	s_waitcnt lgkmcnt(6)
	v_pk_fma_f32 v[144:145], v[188:189], v[182:183], v[144:145] op_sel_hi:[0,1,1]
	s_waitcnt lgkmcnt(3)
	v_cndmask_b32_e64 v184, v184, 0, s[28:29]
	s_waitcnt lgkmcnt(0)
	v_cndmask_b32_e64 v185, v185, 0, s[28:29]
	v_pk_fma_f32 v[146:147], v[166:167], v[180:181], v[188:189] op_sel:[1,0,1]
	v_pk_fma_f32 v[146:147], v[166:167], v[186:187], v[146:147] op_sel_hi:[0,1,1]
	v_pk_fma_f32 v[146:147], v[188:189], v[184:185], v[146:147] op_sel_hi:[0,1,1]
	s_load_dword s17, s[60:61], 0x0
	s_load_dword s23, s[60:61], 0x3000
	s_load_dword s25, s[60:61], 0x6000
	s_load_dword s26, s[62:63], 0x0
	s_waitcnt vmcnt(7)
	v_perm_b32 v174, 0, v58, s15
	v_perm_b32 v175, 0, v60, s15
	ds_write_b64 v206, v[174:175] offset:32768
	s_waitcnt vmcnt(6)
	v_perm_b32 v168, 0, v62, s15
	v_perm_b32 v169, 0, v64, s15
	ds_write_b64 v206, v[168:169] offset:36864
	s_waitcnt vmcnt(5)
	v_perm_b32 v178, 0, v66, s15
	v_perm_b32 v179, 0, v68, s15
	ds_write_b64 v206, v[178:179] offset:40960
	s_waitcnt vmcnt(4)
	v_perm_b32 v176, 0, v70, s15
	v_perm_b32 v177, 0, v72, s15
	ds_write_b64 v206, v[176:177] offset:45056
	s_waitcnt vmcnt(3)
	v_perm_b32 v182, 0, v74, s15
	v_perm_b32 v183, 0, v76, s15
	ds_write_b64 v206, v[182:183] offset:49152
	s_waitcnt vmcnt(2)
	v_perm_b32 v180, 0, v78, s15
	v_perm_b32 v181, 0, v80, s15
	ds_write_b64 v206, v[180:181] offset:53248
	s_waitcnt vmcnt(1)
	v_perm_b32 v186, 0, v82, s15
	v_perm_b32 v187, 0, v84, s15
	ds_write_b64 v206, v[186:187] offset:57344
	s_waitcnt vmcnt(0)
; #define LAS __attribute__((address_space(3)))
; __device__ __forceinline__ f32x2 cmul(f32x2 a, f32x2 b) { return (f32x2){a.x * b.x - a.y * b.y, a.x * b.y + a.y * b.x}; }
; template <bool INV> __device__ __forceinline__ f32x2 cmul_tw(f32x2 a, f32x2 w) { return INV ? cmulc(a, w) : cmul(a, w); }
; template <bool INV> __device__ __forceinline__ void dft16(f32x2 (&x)[16]) {
;     constexpr float C1 = 0.92387953251128674f, S1 = 0.38268343236508977f, C2 = 0.70710678118654752f;
; #pragma unroll
;     for (int b = 0; b < 4; ++b) dft4<INV>(x[b], x[4 + b], x[8 + b], x[12 + b]);
;     const f32x2 w1 = {C1, -S1}, w2 = {C2, -C2}, w3 = {S1, -C1}, w4 = {0.f, -1.f}, w6 = {-C2, -C2}, w9 = {-C1, S1};
;     x[4 * 1 + 1] = cmul_tw<INV>(x[5], w1); x[4 * 1 + 2] = cmul_tw<INV>(x[6], w2); x[4 * 1 + 3] = cmul_tw<INV>(x[7], w3);
;     x[4 * 2 + 1] = cmul_tw<INV>(x[9], w2); x[4 * 2 + 2] = cmul_tw<INV>(x[10], w4); x[4 * 2 + 3] = cmul_tw<INV>(x[11], w6);
;     x[4 * 3 + 1] = cmul_tw<INV>(x[13], w3); x[4 * 3 + 2] = cmul_tw<INV>(x[14], w6); x[4 * 3 + 3] = cmul_tw<INV>(x[15], w9);
; #pragma unroll
;     for (int c = 0; c < 4; ++c) dft4<INV>(x[4 * c], x[4 * c + 1], x[4 * c + 2], x[4 * c + 3]);
;     f32x2 y[16];
; #pragma unroll
;     for (int k = 0; k < 16; ++k) y[k] = x[4 * (k & 3) + (k >> 2)];
; #pragma unroll
;     for (int k = 0; k < 16; ++k) x[k] = y[k];
; }
; __device__ __forceinline__ void fft_fwd2(LAS f32x2* B, const LAS f32x2* TW2, int tid) {
;     asm volatile("" : "+v"(tid));
;     const int b = tid >> 5, n2 = tid & 31, base = 512 * b + n2; f32x2 x[16];
; #pragma unroll
;     for (int r = 0; r < 16; ++r) x[r] = B[fpad(base + 32 * r)];
;     dft16<false>(x);
;     B[fpad(base)] = x[0];
; #pragma unroll
;     for (int k = 1; k < 16; ++k) B[fpad(base + 32 * k)] = cmul(x[k], TW2[k * 32 + n2]);
; }
	v_perm_b32 v184, 0, v86, s15
	v_perm_b32 v185, 0, v88, s15
	ds_write_b64 v206, v[184:185] offset:61440
	s_add_u32 s56, s38, s73
	s_addc_u32 s57, s39, 0
	s_add_u32 s56, s56, 0x1100000
	s_addc_u32 s57, s57, 0
	global_load_dwordx3 v[58:60], v216, s[56:57]
	global_load_dwordx3 v[62:64], v218, s[56:57]
	global_load_dwordx3 v[66:68], v220, s[56:57]
	global_load_dwordx3 v[70:72], v222, s[56:57]
	global_load_dwordx3 v[74:76], v240, s[56:57]
	global_load_dwordx3 v[78:80], v242, s[56:57]
	global_load_dwordx3 v[82:84], v244, s[56:57]
	global_load_dwordx3 v[86:88], v61, s[56:57]
	v_add_u32_e32 v65, 0x10800, v5
	ds_read_b64 v[100:101], v65
	ds_read_b64 v[102:103], v65 offset:1056
	ds_read_b64 v[104:105], v65 offset:2112
	ds_read_b64 v[106:107], v65 offset:3168
	ds_read_b64 v[108:109], v65 offset:264
	ds_read_b64 v[110:111], v65 offset:1320
	ds_read_b64 v[112:113], v65 offset:2376
	ds_read_b64 v[114:115], v65 offset:3432
	ds_read_b64 v[116:117], v65 offset:528
	ds_read_b64 v[118:119], v65 offset:1584
	ds_read_b64 v[120:121], v65 offset:2640
	ds_read_b64 v[122:123], v65 offset:3696
	s_waitcnt lgkmcnt(8)
	ds_read_b64 v[124:125], v65 offset:792
	ds_read_b64 v[126:127], v65 offset:1848
	ds_read_b64 v[128:129], v65 offset:2904
	ds_read_b64 v[130:131], v65 offset:3960
	v_pk_add_f32 v[166:167], v[100:101], v[104:105]
	v_pk_add_f32 v[188:189], v[100:101], v[104:105] neg_lo:[0,1] neg_hi:[0,1]
	v_pk_add_f32 v[174:175], v[102:103], v[106:107]
	v_pk_add_f32 v[168:169], v[102:103], v[106:107] neg_lo:[0,1] neg_hi:[0,1]
	v_pk_add_f32 v[100:101], v[166:167], v[174:175]
	v_pk_add_f32 v[104:105], v[166:167], v[174:175] neg_lo:[0,1] neg_hi:[0,1]
	v_pk_add_f32 v[102:103], v[188:189], v[168:169] op_sel:[0,1] op_sel_hi:[1,0] neg_hi:[0,1]
	v_pk_add_f32 v[106:107], v[188:189], v[168:169] op_sel:[0,1] op_sel_hi:[1,0] neg_lo:[0,1]
	s_waitcnt lgkmcnt(9)
	v_pk_add_f32 v[178:179], v[108:109], v[112:113]
	v_pk_add_f32 v[176:177], v[108:109], v[112:113] neg_lo:[0,1] neg_hi:[0,1]
	s_waitcnt lgkmcnt(8)
	v_pk_add_f32 v[182:183], v[110:111], v[114:115]
	v_pk_add_f32 v[180:181], v[110:111], v[114:115] neg_lo:[0,1] neg_hi:[0,1]
	v_pk_add_f32 v[108:109], v[178:179], v[182:183]
	v_pk_add_f32 v[112:113], v[178:179], v[182:183] neg_lo:[0,1] neg_hi:[0,1]
	v_pk_add_f32 v[110:111], v[176:177], v[180:181] op_sel:[0,1] op_sel_hi:[1,0] neg_hi:[0,1]
	v_pk_add_f32 v[114:115], v[176:177], v[180:181] op_sel:[0,1] op_sel_hi:[1,0] neg_lo:[0,1]
	s_waitcnt lgkmcnt(5)
	v_pk_add_f32 v[186:187], v[116:117], v[120:121]
	v_pk_add_f32 v[184:185], v[116:117], v[120:121] neg_lo:[0,1] neg_hi:[0,1]
	s_waitcnt lgkmcnt(4)
	v_pk_add_f32 v[166:167], v[118:119], v[122:123]
	v_pk_add_f32 v[188:189], v[118:119], v[122:123] neg_lo:[0,1] neg_hi:[0,1]
	v_pk_add_f32 v[116:117], v[186:187], v[166:167]
	v_pk_add_f32 v[120:121], v[186:187], v[166:167] neg_lo:[0,1] neg_hi:[0,1]
	v_pk_add_f32 v[118:119], v[184:185], v[188:189] op_sel:[0,1] op_sel_hi:[1,0] neg_hi:[0,1]
	v_pk_add_f32 v[122:123], v[184:185], v[188:189] op_sel:[0,1] op_sel_hi:[1,0] neg_lo:[0,1]
	s_waitcnt lgkmcnt(1)
	v_pk_add_f32 v[174:175], v[124:125], v[128:129]
	v_pk_add_f32 v[168:169], v[124:125], v[128:129] neg_lo:[0,1] neg_hi:[0,1]
	s_waitcnt lgkmcnt(0)
	v_pk_add_f32 v[178:179], v[126:127], v[130:131]
	v_pk_add_f32 v[176:177], v[126:127], v[130:131] neg_lo:[0,1] neg_hi:[0,1]
	v_pk_add_f32 v[124:125], v[174:175], v[178:179]
	v_pk_add_f32 v[128:129], v[174:175], v[178:179] neg_lo:[0,1] neg_hi:[0,1]
	v_pk_add_f32 v[126:127], v[168:169], v[176:177] op_sel:[0,1] op_sel_hi:[1,0] neg_hi:[0,1]
	v_pk_add_f32 v[130:131], v[168:169], v[176:177] op_sel:[0,1] op_sel_hi:[1,0] neg_lo:[0,1]
	v_pk_mul_f32 v[182:183], v[110:111], s[68:69] op_sel:[1,1] op_sel_hi:[0,1]
	v_pk_fma_f32 v[110:111], v[110:111], s[68:69], v[182:183] op_sel_hi:[1,0,1] neg_lo:[0,0,1]
	v_pk_mul_f32 v[180:181], v[118:119], s[84:85] op_sel:[1,1] op_sel_hi:[0,1]
	v_pk_fma_f32 v[118:119], v[118:119], s[84:85], v[180:181] op_sel_hi:[1,0,1] neg_lo:[0,0,1]
	v_pk_mul_f32 v[186:187], v[126:127], s[88:89] op_sel:[1,1] op_sel_hi:[0,1]
	v_pk_fma_f32 v[126:127], v[126:127], s[88:89], v[186:187] op_sel_hi:[1,0,1] neg_lo:[0,0,1]
	v_pk_mul_f32 v[184:185], v[112:113], s[84:85] op_sel:[1,1] op_sel_hi:[0,1]
	v_pk_fma_f32 v[112:113], v[112:113], s[84:85], v[184:185] op_sel_hi:[1,0,1] neg_lo:[0,0,1]
	v_pk_mul_f32 v[166:167], v[128:129], s[90:91] op_sel:[1,1] op_sel_hi:[0,1]
	v_pk_fma_f32 v[128:129], v[128:129], s[90:91], v[166:167] op_sel_hi:[1,0,1] neg_lo:[0,0,1]
	v_pk_mul_f32 v[188:189], v[114:115], s[88:89] op_sel:[1,1] op_sel_hi:[0,1]
	v_pk_fma_f32 v[114:115], v[114:115], s[88:89], v[188:189] op_sel_hi:[1,0,1] neg_lo:[0,0,1]
	v_pk_mul_f32 v[174:175], v[122:123], s[90:91] op_sel:[1,1] op_sel_hi:[0,1]
	v_pk_fma_f32 v[122:123], v[122:123], s[90:91], v[174:175] op_sel_hi:[1,0,1] neg_lo:[0,0,1]
	v_pk_mul_f32 v[168:169], v[130:131], s[98:99] op_sel:[1,1] op_sel_hi:[0,1]
	v_pk_fma_f32 v[130:131], v[130:131], s[98:99], v[168:169] op_sel_hi:[1,0,1] neg_lo:[0,0,1]
	v_pk_add_f32 v[178:179], v[100:101], v[116:117]
	v_pk_add_f32 v[176:177], v[100:101], v[116:117] neg_lo:[0,1] neg_hi:[0,1]
	v_pk_add_f32 v[182:183], v[108:109], v[124:125]
	v_pk_add_f32 v[180:181], v[108:109], v[124:125] neg_lo:[0,1] neg_hi:[0,1]
	v_pk_add_f32 v[100:101], v[178:179], v[182:183]
	v_pk_add_f32 v[116:117], v[178:179], v[182:183] neg_lo:[0,1] neg_hi:[0,1]
	v_pk_add_f32 v[108:109], v[176:177], v[180:181] op_sel:[0,1] op_sel_hi:[1,0] neg_hi:[0,1]
	v_pk_add_f32 v[124:125], v[176:177], v[180:181] op_sel:[0,1] op_sel_hi:[1,0] neg_lo:[0,1]
	v_pk_add_f32 v[186:187], v[102:103], v[118:119]
	v_pk_add_f32 v[184:185], v[102:103], v[118:119] neg_lo:[0,1] neg_hi:[0,1]
; __device__ __forceinline__ f32x2 cmul(f32x2 a, f32x2 b) { return (f32x2){a.x * b.x - a.y * b.y, a.x * b.y + a.y * b.x}; }
; #define WAVE_FENCE() do { asm volatile("s_waitcnt lgkmcnt(0)" ::: "memory"); __builtin_amdgcn_sched_barrier(0); } while (0)
; __device__ __forceinline__ void fft_fwd2(LAS f32x2* B, const LAS f32x2* TW2, int tid) {
;     ...
;     dft16<false>(x);
;     B[fpad(base)] = x[0];
; #pragma unroll
;     for (int k = 1; k < 16; ++k) B[fpad(base + 32 * k)] = cmul(x[k], TW2[k * 32 + n2]);
; __device__ __forceinline__ void hyena_fft(LAS unsigned char* lds, int layer, int G, const int wave_s) {
;     ...
;             fft_fwd2(Fb, TW2, tid); WAVE_FENCE(); fft_pair32<2>(Fb, Fb, wave, lane); __builtin_amdgcn_sched_barrier(0);
	v_pk_add_f32 v[166:167], v[110:111], v[126:127]
	v_pk_add_f32 v[188:189], v[110:111], v[126:127] neg_lo:[0,1] neg_hi:[0,1]
	v_pk_add_f32 v[102:103], v[186:187], v[166:167]
	v_pk_add_f32 v[118:119], v[186:187], v[166:167] neg_lo:[0,1] neg_hi:[0,1]
	v_pk_add_f32 v[110:111], v[184:185], v[188:189] op_sel:[0,1] op_sel_hi:[1,0] neg_hi:[0,1]
	v_pk_add_f32 v[126:127], v[184:185], v[188:189] op_sel:[0,1] op_sel_hi:[1,0] neg_lo:[0,1]
	v_pk_add_f32 v[174:175], v[104:105], v[120:121] op_sel:[0,1] op_sel_hi:[1,0] neg_hi:[0,1]
	v_pk_add_f32 v[168:169], v[104:105], v[120:121] op_sel:[0,1] op_sel_hi:[1,0] neg_lo:[0,1]
	v_pk_add_f32 v[178:179], v[112:113], v[128:129]
	v_pk_add_f32 v[176:177], v[112:113], v[128:129] neg_lo:[0,1] neg_hi:[0,1]
	v_pk_add_f32 v[104:105], v[174:175], v[178:179]
	v_pk_add_f32 v[120:121], v[174:175], v[178:179] neg_lo:[0,1] neg_hi:[0,1]
	v_pk_add_f32 v[112:113], v[168:169], v[176:177] op_sel:[0,1] op_sel_hi:[1,0] neg_hi:[0,1]
	v_pk_add_f32 v[128:129], v[168:169], v[176:177] op_sel:[0,1] op_sel_hi:[1,0] neg_lo:[0,1]
	v_pk_add_f32 v[182:183], v[106:107], v[122:123]
	v_pk_add_f32 v[180:181], v[106:107], v[122:123] neg_lo:[0,1] neg_hi:[0,1]
	v_pk_add_f32 v[186:187], v[114:115], v[130:131]
	v_pk_add_f32 v[184:185], v[114:115], v[130:131] neg_lo:[0,1] neg_hi:[0,1]
	v_pk_add_f32 v[106:107], v[182:183], v[186:187]
	v_pk_add_f32 v[122:123], v[182:183], v[186:187] neg_lo:[0,1] neg_hi:[0,1]
	v_pk_add_f32 v[114:115], v[180:181], v[184:185] op_sel:[0,1] op_sel_hi:[1,0] neg_hi:[0,1]
	v_pk_add_f32 v[130:131], v[180:181], v[184:185] op_sel:[0,1] op_sel_hi:[1,0] neg_lo:[0,1]
	ds_write_b64 v65, v[100:101]
	ds_read_b64 v[166:167], v56 offset:256
	ds_read_b64 v[188:189], v56 offset:512
	ds_read_b64 v[174:175], v56 offset:768
	ds_read_b64 v[168:169], v56 offset:1024
	s_waitcnt lgkmcnt(3)
	v_pk_mul_f32 v[178:179], v[102:103], v[166:167] op_sel:[1,1] op_sel_hi:[0,1]
	v_pk_fma_f32 v[102:103], v[102:103], v[166:167], v[178:179] op_sel_hi:[1,0,1] neg_lo:[0,0,1]
	ds_write_b64 v65, v[102:103] offset:264
	s_waitcnt lgkmcnt(3)
	v_pk_mul_f32 v[176:177], v[104:105], v[188:189] op_sel:[1,1] op_sel_hi:[0,1]
	v_pk_fma_f32 v[104:105], v[104:105], v[188:189], v[176:177] op_sel_hi:[1,0,1] neg_lo:[0,0,1]
	ds_write_b64 v65, v[104:105] offset:528
	s_waitcnt lgkmcnt(3)
	v_pk_mul_f32 v[182:183], v[106:107], v[174:175] op_sel:[1,1] op_sel_hi:[0,1]
	v_pk_fma_f32 v[106:107], v[106:107], v[174:175], v[182:183] op_sel_hi:[1,0,1] neg_lo:[0,0,1]
	ds_write_b64 v65, v[106:107] offset:792
	s_waitcnt lgkmcnt(3)
	v_pk_mul_f32 v[180:181], v[108:109], v[168:169] op_sel:[1,1] op_sel_hi:[0,1]
	v_pk_fma_f32 v[108:109], v[108:109], v[168:169], v[180:181] op_sel_hi:[1,0,1] neg_lo:[0,0,1]
	ds_write_b64 v65, v[108:109] offset:1056
	ds_read_b64 v[186:187], v56 offset:1280
	ds_read_b64 v[184:185], v56 offset:1536
	ds_read_b64 v[178:179], v56 offset:1792
	ds_read_b64 v[176:177], v56 offset:2048
	s_waitcnt lgkmcnt(3)
	v_pk_mul_f32 v[182:183], v[110:111], v[186:187] op_sel:[1,1] op_sel_hi:[0,1]
	v_pk_fma_f32 v[110:111], v[110:111], v[186:187], v[182:183] op_sel_hi:[1,0,1] neg_lo:[0,0,1]
	ds_write_b64 v65, v[110:111] offset:1320
	s_waitcnt lgkmcnt(3)
	v_pk_mul_f32 v[180:181], v[112:113], v[184:185] op_sel:[1,1] op_sel_hi:[0,1]
	v_pk_fma_f32 v[112:113], v[112:113], v[184:185], v[180:181] op_sel_hi:[1,0,1] neg_lo:[0,0,1]
	ds_write_b64 v65, v[112:113] offset:1584
	s_waitcnt lgkmcnt(3)
	v_pk_mul_f32 v[166:167], v[114:115], v[178:179] op_sel:[1,1] op_sel_hi:[0,1]
	v_pk_fma_f32 v[114:115], v[114:115], v[178:179], v[166:167] op_sel_hi:[1,0,1] neg_lo:[0,0,1]
	ds_write_b64 v65, v[114:115] offset:1848
	s_waitcnt lgkmcnt(3)
	v_pk_mul_f32 v[188:189], v[116:117], v[176:177] op_sel:[1,1] op_sel_hi:[0,1]
	v_pk_fma_f32 v[116:117], v[116:117], v[176:177], v[188:189] op_sel_hi:[1,0,1] neg_lo:[0,0,1]
	ds_write_b64 v65, v[116:117] offset:2112
	ds_read_b64 v[174:175], v56 offset:2304
	ds_read_b64 v[168:169], v56 offset:2560
	ds_read_b64 v[182:183], v56 offset:2816
	ds_read_b64 v[180:181], v56 offset:3072
	s_waitcnt lgkmcnt(3)
	v_pk_mul_f32 v[166:167], v[118:119], v[174:175] op_sel:[1,1] op_sel_hi:[0,1]
	v_pk_fma_f32 v[118:119], v[118:119], v[174:175], v[166:167] op_sel_hi:[1,0,1] neg_lo:[0,0,1]
	ds_write_b64 v65, v[118:119] offset:2376
	s_waitcnt lgkmcnt(3)
	v_pk_mul_f32 v[188:189], v[120:121], v[168:169] op_sel:[1,1] op_sel_hi:[0,1]
	v_pk_fma_f32 v[120:121], v[120:121], v[168:169], v[188:189] op_sel_hi:[1,0,1] neg_lo:[0,0,1]
	ds_write_b64 v65, v[120:121] offset:2640
	s_waitcnt lgkmcnt(3)
	v_pk_mul_f32 v[186:187], v[122:123], v[182:183] op_sel:[1,1] op_sel_hi:[0,1]
	v_pk_fma_f32 v[122:123], v[122:123], v[182:183], v[186:187] op_sel_hi:[1,0,1] neg_lo:[0,0,1]
	ds_write_b64 v65, v[122:123] offset:2904
	s_waitcnt lgkmcnt(3)
	v_pk_mul_f32 v[184:185], v[124:125], v[180:181] op_sel:[1,1] op_sel_hi:[0,1]
	v_pk_fma_f32 v[124:125], v[124:125], v[180:181], v[184:185] op_sel_hi:[1,0,1] neg_lo:[0,0,1]
	ds_write_b64 v65, v[124:125] offset:3168
	ds_read_b64 v[178:179], v56 offset:3328
	ds_read_b64 v[176:177], v56 offset:3584
	ds_read_b64 v[166:167], v56 offset:3840
	s_waitcnt lgkmcnt(2)
	v_pk_mul_f32 v[188:189], v[126:127], v[178:179] op_sel:[1,1] op_sel_hi:[0,1]
	v_pk_fma_f32 v[126:127], v[126:127], v[178:179], v[188:189] op_sel_hi:[1,0,1] neg_lo:[0,0,1]
	ds_write_b64 v65, v[126:127] offset:3432
	s_waitcnt lgkmcnt(2)
	v_pk_mul_f32 v[186:187], v[128:129], v[176:177] op_sel:[1,1] op_sel_hi:[0,1]
	v_pk_fma_f32 v[128:129], v[128:129], v[176:177], v[186:187] op_sel_hi:[1,0,1] neg_lo:[0,0,1]
	ds_write_b64 v65, v[128:129] offset:3696
	s_waitcnt lgkmcnt(2)
	v_pk_mul_f32 v[184:185], v[130:131], v[166:167] op_sel:[1,1] op_sel_hi:[0,1]
	v_pk_fma_f32 v[130:131], v[130:131], v[166:167], v[184:185] op_sel_hi:[1,0,1] neg_lo:[0,0,1]
	ds_write_b64 v65, v[130:131] offset:3960
	s_waitcnt lgkmcnt(0)
	s_barrier
	s_cbranch_vccz .Lhfft_st3
	s_sleep 4
; #define LAS __attribute__((address_space(3)))
; __device__ __forceinline__ f32x2 cmul(f32x2 a, f32x2 b) { return (f32x2){a.x * b.x - a.y * b.y, a.x * b.y + a.y * b.x}; }
; template <int MODE> __device__ __forceinline__ void fft_pair32(LAS f32x2* B, const LAS f32x2* F, int wave, int lane) {
;     asm volatile("" : "+v"(lane));
;     constexpr float CS[16] = {1.f, 0.98078528040323043f, 0.92387953251128674f, 0.83146961230254524f, 0.70710678118654752f, 0.55557023301960218f, 0.38268343236508977f, 0.19509032201612825f,
;                               0.f, -0.19509032201612825f, -0.38268343236508977f, -0.55557023301960218f, -0.70710678118654752f, -0.83146961230254524f, -0.92387953251128674f, -0.98078528040323043f};
;     constexpr float SN[16] = {0.f, 0.19509032201612825f, 0.38268343236508977f, 0.55557023301960218f, 0.70710678118654752f, 0.83146961230254524f, 0.92387953251128674f, 0.98078528040323043f,
;                               1.f, 0.98078528040323043f, 0.92387953251128674f, 0.83146961230254524f, 0.70710678118654752f, 0.55557023301960218f, 0.38268343236508977f, 0.19509032201612825f};
;     const int hi = lane >> 5, blk = 32 * wave + (lane & 31); const float sg = hi ? -1.f : 1.f;
;     LAS f32x2* p = B + 33 * blk; f32x2 v[16];
; #pragma unroll
;     for (int j = 0; j < 16; ++j) { const f32x2 d = p[j] + p[j + 16] * sg;
;         const f32x2 w = {hi ? CS[j] : 1.f, hi ? -SN[j] : 0.f}; v[j] = j == 0 ? d : cmul(d, w); }
; __device__ __forceinline__ void hy_sconv(const LAS float* plane, float w0, float w1, float w2, float cb, int n2, float (&u)[8][2]) {
;     asm volatile("" : "+v"(n2));
; #pragma unroll
;     for (int r = 0; r < 8; ++r)
; #pragma unroll
;         for (int b = 0; b < 2; ++b) { const int t = n2 + 512 * r, row = b * SEQ + t;
;             float a = cb + w1 * plane[row];
;             if (t > 0) a += w0 * plane[row - 1];
;             if (t < SEQ - 1) a += w2 * plane[row + 1];
;             u[r][b] = a; }
; }
; __device__ __forceinline__ void hyena_fft(LAS unsigned char* lds, int layer, int G, const int wave_s) {
;     ...
;             hy_sconv(pl0, cw[2 * HY + c], cw[3 * HY + 2 * HY + c], cw[6 * HY + 2 * HY + c], cb[2 * HY + c], n2, uz);
;             __builtin_amdgcn_sched_barrier(0); hy_sconv(pl1, cw[c], cw[3 * HY + c], cw[6 * HY + c], cb[c], n2, ux); __builtin_amdgcn_sched_barrier(0);
.Lhfft_st3:
	v_mov_b32_e32 v174, s17
	v_mov_b32_e32 v175, s23
	v_mov_b32_e32 v168, s25
	v_mov_b32_e32 v169, s26
	ds_read_b32 v182, v208 offset:32768
	ds_read_b32 v180, v210 offset:32768
	ds_read_b32 v188, v208 offset:32772
	ds_read_b32 v183, v208 offset:49152
	ds_read_b32 v181, v210 offset:49152
	ds_read_b32 v189, v208 offset:49156
	ds_read_b32 v186, v208 offset:34816
	ds_read_b32 v184, v208 offset:34812
	ds_read_b32 v178, v208 offset:34820
	ds_read_b32 v187, v208 offset:51200
	ds_read_b32 v185, v208 offset:51196
	ds_read_b32 v179, v208 offset:51204
	s_waitcnt lgkmcnt(10)
	v_cndmask_b32_e64 v180, v180, 0, s[10:11]
	s_waitcnt lgkmcnt(7)
	v_cndmask_b32_e64 v181, v181, 0, s[10:11]
	v_pk_fma_f32 v[148:149], v[174:175], v[182:183], v[168:169] op_sel:[1,0,1]
	v_pk_fma_f32 v[148:149], v[174:175], v[180:181], v[148:149] op_sel_hi:[0,1,1]
	s_waitcnt lgkmcnt(6)
	v_pk_fma_f32 v[148:149], v[168:169], v[188:189], v[148:149] op_sel_hi:[0,1,1]
	s_waitcnt lgkmcnt(2)
	v_pk_fma_f32 v[150:151], v[174:175], v[186:187], v[168:169] op_sel:[1,0,1]
	s_waitcnt lgkmcnt(1)
	v_pk_fma_f32 v[150:151], v[174:175], v[184:185], v[150:151] op_sel_hi:[0,1,1]
	s_waitcnt lgkmcnt(0)
	v_pk_fma_f32 v[150:151], v[168:169], v[178:179], v[150:151] op_sel_hi:[0,1,1]
	ds_read_b32 v176, v208 offset:36864
	ds_read_b32 v166, v208 offset:36860
	ds_read_b32 v182, v208 offset:36868
	ds_read_b32 v177, v208 offset:53248
	ds_read_b32 v167, v208 offset:53244
	ds_read_b32 v183, v208 offset:53252
	ds_read_b32 v180, v208 offset:38912
	ds_read_b32 v188, v208 offset:38908
	ds_read_b32 v186, v208 offset:38916
	ds_read_b32 v181, v208 offset:55296
	ds_read_b32 v189, v208 offset:55292
	ds_read_b32 v187, v208 offset:55300
	s_waitcnt lgkmcnt(8)
	v_pk_fma_f32 v[152:153], v[174:175], v[176:177], v[168:169] op_sel:[1,0,1]
	s_waitcnt lgkmcnt(7)
	v_pk_fma_f32 v[152:153], v[174:175], v[166:167], v[152:153] op_sel_hi:[0,1,1]
	s_waitcnt lgkmcnt(6)
	v_pk_fma_f32 v[152:153], v[168:169], v[182:183], v[152:153] op_sel_hi:[0,1,1]
	s_waitcnt lgkmcnt(2)
	v_pk_fma_f32 v[154:155], v[174:175], v[180:181], v[168:169] op_sel:[1,0,1]
	s_waitcnt lgkmcnt(1)
	v_pk_fma_f32 v[154:155], v[174:175], v[188:189], v[154:155] op_sel_hi:[0,1,1]
	s_waitcnt lgkmcnt(0)
	v_pk_fma_f32 v[154:155], v[168:169], v[186:187], v[154:155] op_sel_hi:[0,1,1]
	ds_read_b32 v184, v208 offset:40960
	ds_read_b32 v178, v208 offset:40956
	ds_read_b32 v176, v208 offset:40964
	ds_read_b32 v185, v208 offset:57344
	ds_read_b32 v179, v208 offset:57340
	ds_read_b32 v177, v208 offset:57348
	ds_read_b32 v166, v208 offset:43008
	ds_read_b32 v182, v208 offset:43004
	ds_read_b32 v180, v208 offset:43012
	ds_read_b32 v167, v208 offset:59392
	ds_read_b32 v183, v208 offset:59388
	ds_read_b32 v181, v208 offset:59396
	s_waitcnt lgkmcnt(8)
	v_pk_fma_f32 v[158:159], v[174:175], v[184:185], v[168:169] op_sel:[1,0,1]
	s_waitcnt lgkmcnt(7)
	v_pk_fma_f32 v[158:159], v[174:175], v[178:179], v[158:159] op_sel_hi:[0,1,1]
	s_waitcnt lgkmcnt(6)
	v_pk_fma_f32 v[158:159], v[168:169], v[176:177], v[158:159] op_sel_hi:[0,1,1]
	s_waitcnt lgkmcnt(2)
	v_pk_fma_f32 v[160:161], v[174:175], v[166:167], v[168:169] op_sel:[1,0,1]
	s_waitcnt lgkmcnt(1)
	v_pk_fma_f32 v[160:161], v[174:175], v[182:183], v[160:161] op_sel_hi:[0,1,1]
	s_waitcnt lgkmcnt(0)
	v_pk_fma_f32 v[160:161], v[168:169], v[180:181], v[160:161] op_sel_hi:[0,1,1]
	ds_read_b32 v188, v208 offset:45056
	ds_read_b32 v186, v208 offset:45052
	ds_read_b32 v184, v208 offset:45060
	ds_read_b32 v189, v208 offset:61440
	ds_read_b32 v187, v208 offset:61436
	ds_read_b32 v185, v208 offset:61444
	ds_read_b32 v178, v208 offset:47104
	ds_read_b32 v176, v208 offset:47100
	ds_read_b32 v166, v208 offset:47108
	ds_read_b32 v179, v208 offset:63488
	ds_read_b32 v177, v208 offset:63484
	ds_read_b32 v167, v208 offset:63492
	s_waitcnt lgkmcnt(8)
	v_pk_fma_f32 v[162:163], v[174:175], v[188:189], v[168:169] op_sel:[1,0,1]
	s_waitcnt lgkmcnt(7)
	v_pk_fma_f32 v[162:163], v[174:175], v[186:187], v[162:163] op_sel_hi:[0,1,1]
	s_waitcnt lgkmcnt(6)
	v_pk_fma_f32 v[162:163], v[168:169], v[184:185], v[162:163] op_sel_hi:[0,1,1]
	s_waitcnt lgkmcnt(3)
	v_cndmask_b32_e64 v166, v166, 0, s[28:29]
	s_waitcnt lgkmcnt(0)
	v_cndmask_b32_e64 v167, v167, 0, s[28:29]
	v_pk_fma_f32 v[164:165], v[174:175], v[178:179], v[168:169] op_sel:[1,0,1]
	v_pk_fma_f32 v[164:165], v[174:175], v[176:177], v[164:165] op_sel_hi:[0,1,1]
	v_pk_fma_f32 v[164:165], v[168:169], v[166:167], v[164:165] op_sel_hi:[0,1,1]
	s_load_dword s17, s[60:61], 0x1000
	s_load_dword s23, s[60:61], 0x4000
	s_load_dword s25, s[60:61], 0x7000
	s_load_dword s26, s[62:63], 0x1000
	v_add_u32_e32 v65, 0x10800, v156
	v_add_u32_e32 v69, 0x10800, v196
	ds_read_b64 v[100:101], v65
	ds_read_b64 v[182:183], v65 offset:128
	ds_read_b64 v[102:103], v65 offset:8
	ds_read_b64 v[180:181], v65 offset:136
	ds_read_b64 v[104:105], v65 offset:16
	ds_read_b64 v[188:189], v65 offset:144
	ds_read_b64 v[106:107], v65 offset:24
	ds_read_b64 v[186:187], v65 offset:152
	s_waitcnt lgkmcnt(0)
	v_pk_fma_f32 v[100:101], v[182:183], v[190:191], v[100:101] op_sel_hi:[1,0,1]
	v_pk_fma_f32 v[102:103], v[180:181], v[190:191], v[102:103] op_sel_hi:[1,0,1]
	v_pk_mul_f32 v[184:185], v[102:103], v[36:37] op_sel:[1,1] op_sel_hi:[0,1]
	v_pk_fma_f32 v[102:103], v[102:103], v[36:37], v[184:185] op_sel_hi:[1,0,1] neg_lo:[0,0,1]
	v_pk_fma_f32 v[104:105], v[188:189], v[190:191], v[104:105] op_sel_hi:[1,0,1]
	v_pk_mul_f32 v[178:179], v[104:105], v[38:39] op_sel:[1,1] op_sel_hi:[0,1]
	v_pk_fma_f32 v[104:105], v[104:105], v[38:39], v[178:179] op_sel_hi:[1,0,1] neg_lo:[0,0,1]
	v_pk_fma_f32 v[106:107], v[186:187], v[190:191], v[106:107] op_sel_hi:[1,0,1]
	v_pk_mul_f32 v[176:177], v[106:107], v[40:41] op_sel:[1,1] op_sel_hi:[0,1]
	v_pk_fma_f32 v[106:107], v[106:107], v[40:41], v[176:177] op_sel_hi:[1,0,1] neg_lo:[0,0,1]
	ds_read_b64 v[108:109], v65 offset:32
	ds_read_b64 v[166:167], v65 offset:160
	ds_read_b64 v[110:111], v65 offset:40
	ds_read_b64 v[174:175], v65 offset:168
	ds_read_b64 v[112:113], v65 offset:48
	ds_read_b64 v[168:169], v65 offset:176
	ds_read_b64 v[114:115], v65 offset:56
	ds_read_b64 v[184:185], v65 offset:184
	s_waitcnt lgkmcnt(6)
; __device__ __forceinline__ f32x2 cmul(f32x2 a, f32x2 b) { return (f32x2){a.x * b.x - a.y * b.y, a.x * b.y + a.y * b.x}; }
; template <bool INV> __device__ __forceinline__ f32x2 cmul_tw(f32x2 a, f32x2 w) { return INV ? cmulc(a, w) : cmul(a, w); }
; template <bool INV> __device__ __forceinline__ void dft16(f32x2 (&x)[16]) {
;     constexpr float C1 = 0.92387953251128674f, S1 = 0.38268343236508977f, C2 = 0.70710678118654752f;
; #pragma unroll
;     for (int b = 0; b < 4; ++b) dft4<INV>(x[b], x[4 + b], x[8 + b], x[12 + b]);
;     const f32x2 w1 = {C1, -S1}, w2 = {C2, -C2}, w3 = {S1, -C1}, w4 = {0.f, -1.f}, w6 = {-C2, -C2}, w9 = {-C1, S1};
;     x[4 * 1 + 1] = cmul_tw<INV>(x[5], w1); x[4 * 1 + 2] = cmul_tw<INV>(x[6], w2); x[4 * 1 + 3] = cmul_tw<INV>(x[7], w3);
;     x[4 * 2 + 1] = cmul_tw<INV>(x[9], w2); x[4 * 2 + 2] = cmul_tw<INV>(x[10], w4); x[4 * 2 + 3] = cmul_tw<INV>(x[11], w6);
;     x[4 * 3 + 1] = cmul_tw<INV>(x[13], w3); x[4 * 3 + 2] = cmul_tw<INV>(x[14], w6); x[4 * 3 + 3] = cmul_tw<INV>(x[15], w9);
; #pragma unroll
;     for (int c = 0; c < 4; ++c) dft4<INV>(x[4 * c], x[4 * c + 1], x[4 * c + 2], x[4 * c + 3]);
;     f32x2 y[16];
; #pragma unroll
;     for (int k = 0; k < 16; ++k) y[k] = x[4 * (k & 3) + (k >> 2)];
; #pragma unroll
;     for (int k = 0; k < 16; ++k) x[k] = y[k];
; }
; template <int MODE> __device__ __forceinline__ void fft_pair32(LAS f32x2* B, const LAS f32x2* F, int wave, int lane) {
;     ...
;     for (int j = 0; j < 16; ++j) { const f32x2 d = p[j] + p[j + 16] * sg;
;         const f32x2 w = {hi ? CS[j] : 1.f, hi ? -SN[j] : 0.f}; v[j] = j == 0 ? d : cmul(d, w); }
;     dft16<false>(v);
	v_pk_fma_f32 v[108:109], v[166:167], v[190:191], v[108:109] op_sel_hi:[1,0,1]
	v_pk_mul_f32 v[178:179], v[108:109], v[42:43] op_sel:[1,1] op_sel_hi:[0,1]
	v_pk_fma_f32 v[108:109], v[108:109], v[42:43], v[178:179] op_sel_hi:[1,0,1] neg_lo:[0,0,1]
	s_waitcnt lgkmcnt(4)
	v_pk_fma_f32 v[110:111], v[174:175], v[190:191], v[110:111] op_sel_hi:[1,0,1]
	v_pk_mul_f32 v[176:177], v[110:111], v[44:45] op_sel:[1,1] op_sel_hi:[0,1]
	v_pk_fma_f32 v[110:111], v[110:111], v[44:45], v[176:177] op_sel_hi:[1,0,1] neg_lo:[0,0,1]
	s_waitcnt lgkmcnt(2)
	v_pk_fma_f32 v[112:113], v[168:169], v[190:191], v[112:113] op_sel_hi:[1,0,1]
	v_pk_mul_f32 v[182:183], v[112:113], v[46:47] op_sel:[1,1] op_sel_hi:[0,1]
	v_pk_fma_f32 v[112:113], v[112:113], v[46:47], v[182:183] op_sel_hi:[1,0,1] neg_lo:[0,0,1]
	s_waitcnt lgkmcnt(0)
	v_pk_fma_f32 v[114:115], v[184:185], v[190:191], v[114:115] op_sel_hi:[1,0,1]
	v_pk_mul_f32 v[180:181], v[114:115], v[48:49] op_sel:[1,1] op_sel_hi:[0,1]
	v_pk_fma_f32 v[114:115], v[114:115], v[48:49], v[180:181] op_sel_hi:[1,0,1] neg_lo:[0,0,1]
	ds_read_b64 v[116:117], v65 offset:64
	ds_read_b64 v[188:189], v65 offset:192
	ds_read_b64 v[118:119], v65 offset:72
	ds_read_b64 v[186:187], v65 offset:200
	ds_read_b64 v[120:121], v65 offset:80
	ds_read_b64 v[178:179], v65 offset:208
	ds_read_b64 v[122:123], v65 offset:88
	ds_read_b64 v[176:177], v65 offset:216
	s_waitcnt lgkmcnt(6)
	v_pk_fma_f32 v[116:117], v[188:189], v[190:191], v[116:117] op_sel_hi:[1,0,1]
	v_pk_mul_f32 v[182:183], v[116:117], v[50:51] op_sel:[1,1] op_sel_hi:[0,1]
	v_pk_fma_f32 v[116:117], v[116:117], v[50:51], v[182:183] op_sel_hi:[1,0,1] neg_lo:[0,0,1]
	s_waitcnt lgkmcnt(4)
	v_pk_fma_f32 v[118:119], v[186:187], v[190:191], v[118:119] op_sel_hi:[1,0,1]
	v_pk_mul_f32 v[180:181], v[118:119], v[52:53] op_sel:[1,1] op_sel_hi:[0,1]
	v_pk_fma_f32 v[118:119], v[118:119], v[52:53], v[180:181] op_sel_hi:[1,0,1] neg_lo:[0,0,1]
	s_waitcnt lgkmcnt(2)
	v_pk_fma_f32 v[120:121], v[178:179], v[190:191], v[120:121] op_sel_hi:[1,0,1]
	v_pk_mul_f32 v[166:167], v[120:121], v[54:55] op_sel:[1,1] op_sel_hi:[0,1]
	v_pk_fma_f32 v[120:121], v[120:121], v[54:55], v[166:167] op_sel_hi:[1,0,1] neg_lo:[0,0,1]
	s_waitcnt lgkmcnt(0)
	v_pk_fma_f32 v[122:123], v[176:177], v[190:191], v[122:123] op_sel_hi:[1,0,1]
	v_pk_mul_f32 v[174:175], v[122:123], v[90:91] op_sel:[1,1] op_sel_hi:[0,1]
	v_pk_fma_f32 v[122:123], v[122:123], v[90:91], v[174:175] op_sel_hi:[1,0,1] neg_lo:[0,0,1]
	ds_read_b64 v[124:125], v65 offset:96
	ds_read_b64 v[168:169], v65 offset:224
	ds_read_b64 v[126:127], v65 offset:104
	ds_read_b64 v[184:185], v65 offset:232
	ds_read_b64 v[128:129], v65 offset:112
	ds_read_b64 v[182:183], v65 offset:240
	ds_read_b64 v[130:131], v65 offset:120
	ds_read_b64 v[180:181], v65 offset:248
	s_waitcnt lgkmcnt(6)
	v_pk_fma_f32 v[124:125], v[168:169], v[190:191], v[124:125] op_sel_hi:[1,0,1]
	v_pk_mul_f32 v[166:167], v[124:125], v[92:93] op_sel:[1,1] op_sel_hi:[0,1]
	v_pk_fma_f32 v[124:125], v[124:125], v[92:93], v[166:167] op_sel_hi:[1,0,1] neg_lo:[0,0,1]
	s_waitcnt lgkmcnt(4)
	v_pk_fma_f32 v[126:127], v[184:185], v[190:191], v[126:127] op_sel_hi:[1,0,1]
	v_pk_mul_f32 v[174:175], v[126:127], v[94:95] op_sel:[1,1] op_sel_hi:[0,1]
	v_pk_fma_f32 v[126:127], v[126:127], v[94:95], v[174:175] op_sel_hi:[1,0,1] neg_lo:[0,0,1]
	s_waitcnt lgkmcnt(2)
	v_pk_fma_f32 v[128:129], v[182:183], v[190:191], v[128:129] op_sel_hi:[1,0,1]
	v_pk_mul_f32 v[188:189], v[128:129], v[96:97] op_sel:[1,1] op_sel_hi:[0,1]
	v_pk_fma_f32 v[128:129], v[128:129], v[96:97], v[188:189] op_sel_hi:[1,0,1] neg_lo:[0,0,1]
	s_waitcnt lgkmcnt(0)
	v_pk_fma_f32 v[130:131], v[180:181], v[190:191], v[130:131] op_sel_hi:[1,0,1]
	v_pk_mul_f32 v[186:187], v[130:131], v[98:99] op_sel:[1,1] op_sel_hi:[0,1]
	v_pk_fma_f32 v[130:131], v[130:131], v[98:99], v[186:187] op_sel_hi:[1,0,1] neg_lo:[0,0,1]
	v_pk_add_f32 v[178:179], v[100:101], v[116:117]
	v_pk_add_f32 v[176:177], v[100:101], v[116:117] neg_lo:[0,1] neg_hi:[0,1]
	v_pk_add_f32 v[166:167], v[108:109], v[124:125]
	v_pk_add_f32 v[174:175], v[108:109], v[124:125] neg_lo:[0,1] neg_hi:[0,1]
	v_pk_add_f32 v[100:101], v[178:179], v[166:167]
	v_pk_add_f32 v[116:117], v[178:179], v[166:167] neg_lo:[0,1] neg_hi:[0,1]
	v_pk_add_f32 v[108:109], v[176:177], v[174:175] op_sel:[0,1] op_sel_hi:[1,0] neg_hi:[0,1]
	v_pk_add_f32 v[124:125], v[176:177], v[174:175] op_sel:[0,1] op_sel_hi:[1,0] neg_lo:[0,1]
	v_pk_add_f32 v[188:189], v[102:103], v[118:119]
	v_pk_add_f32 v[186:187], v[102:103], v[118:119] neg_lo:[0,1] neg_hi:[0,1]
	v_pk_add_f32 v[168:169], v[110:111], v[126:127]
	v_pk_add_f32 v[184:185], v[110:111], v[126:127] neg_lo:[0,1] neg_hi:[0,1]
	v_pk_add_f32 v[102:103], v[188:189], v[168:169]
	v_pk_add_f32 v[118:119], v[188:189], v[168:169] neg_lo:[0,1] neg_hi:[0,1]
	v_pk_add_f32 v[110:111], v[186:187], v[184:185] op_sel:[0,1] op_sel_hi:[1,0] neg_hi:[0,1]
	v_pk_add_f32 v[126:127], v[186:187], v[184:185] op_sel:[0,1] op_sel_hi:[1,0] neg_lo:[0,1]
	v_pk_add_f32 v[182:183], v[104:105], v[120:121]
	v_pk_add_f32 v[180:181], v[104:105], v[120:121] neg_lo:[0,1] neg_hi:[0,1]
	v_pk_add_f32 v[178:179], v[112:113], v[128:129]
	v_pk_add_f32 v[176:177], v[112:113], v[128:129] neg_lo:[0,1] neg_hi:[0,1]
	v_pk_add_f32 v[104:105], v[182:183], v[178:179]
	v_pk_add_f32 v[120:121], v[182:183], v[178:179] neg_lo:[0,1] neg_hi:[0,1]
	v_pk_add_f32 v[112:113], v[180:181], v[176:177] op_sel:[0,1] op_sel_hi:[1,0] neg_hi:[0,1]
	v_pk_add_f32 v[128:129], v[180:181], v[176:177] op_sel:[0,1] op_sel_hi:[1,0] neg_lo:[0,1]
	v_pk_add_f32 v[166:167], v[106:107], v[122:123]
	v_pk_add_f32 v[174:175], v[106:107], v[122:123] neg_lo:[0,1] neg_hi:[0,1]
; template <int MODE> __device__ __forceinline__ void fft_pair32(LAS f32x2* B, const LAS f32x2* F, int wave, int lane) {
;     ...
;     dft16<false>(v);
;     if (MODE == 2) {
; #pragma unroll
;         for (int k = 0; k < 16; ++k) p[2 * k + hi] = v[k];
;         return; }
	v_pk_add_f32 v[188:189], v[114:115], v[130:131]
	v_pk_add_f32 v[186:187], v[114:115], v[130:131] neg_lo:[0,1] neg_hi:[0,1]
	v_pk_add_f32 v[106:107], v[166:167], v[188:189]
	v_pk_add_f32 v[122:123], v[166:167], v[188:189] neg_lo:[0,1] neg_hi:[0,1]
	v_pk_add_f32 v[114:115], v[174:175], v[186:187] op_sel:[0,1] op_sel_hi:[1,0] neg_hi:[0,1]
	v_pk_add_f32 v[130:131], v[174:175], v[186:187] op_sel:[0,1] op_sel_hi:[1,0] neg_lo:[0,1]
	v_pk_mul_f32 v[168:169], v[110:111], s[68:69] op_sel:[1,1] op_sel_hi:[0,1]
	v_pk_fma_f32 v[110:111], v[110:111], s[68:69], v[168:169] op_sel_hi:[1,0,1] neg_lo:[0,0,1]
	v_pk_mul_f32 v[184:185], v[112:113], s[84:85] op_sel:[1,1] op_sel_hi:[0,1]
	v_pk_fma_f32 v[112:113], v[112:113], s[84:85], v[184:185] op_sel_hi:[1,0,1] neg_lo:[0,0,1]
	v_pk_mul_f32 v[182:183], v[114:115], s[88:89] op_sel:[1,1] op_sel_hi:[0,1]
	v_pk_fma_f32 v[114:115], v[114:115], s[88:89], v[182:183] op_sel_hi:[1,0,1] neg_lo:[0,0,1]
	v_pk_mul_f32 v[180:181], v[118:119], s[84:85] op_sel:[1,1] op_sel_hi:[0,1]
	v_pk_fma_f32 v[118:119], v[118:119], s[84:85], v[180:181] op_sel_hi:[1,0,1] neg_lo:[0,0,1]
	v_pk_mul_f32 v[178:179], v[122:123], s[90:91] op_sel:[1,1] op_sel_hi:[0,1]
	v_pk_fma_f32 v[122:123], v[122:123], s[90:91], v[178:179] op_sel_hi:[1,0,1] neg_lo:[0,0,1]
	v_pk_mul_f32 v[176:177], v[126:127], s[88:89] op_sel:[1,1] op_sel_hi:[0,1]
	v_pk_fma_f32 v[126:127], v[126:127], s[88:89], v[176:177] op_sel_hi:[1,0,1] neg_lo:[0,0,1]
	v_pk_mul_f32 v[166:167], v[128:129], s[90:91] op_sel:[1,1] op_sel_hi:[0,1]
	v_pk_fma_f32 v[128:129], v[128:129], s[90:91], v[166:167] op_sel_hi:[1,0,1] neg_lo:[0,0,1]
	v_pk_mul_f32 v[174:175], v[130:131], s[98:99] op_sel:[1,1] op_sel_hi:[0,1]
	v_pk_fma_f32 v[130:131], v[130:131], s[98:99], v[174:175] op_sel_hi:[1,0,1] neg_lo:[0,0,1]
	v_pk_add_f32 v[188:189], v[100:101], v[104:105]
	v_pk_add_f32 v[186:187], v[100:101], v[104:105] neg_lo:[0,1] neg_hi:[0,1]
	v_pk_add_f32 v[168:169], v[102:103], v[106:107]
	v_pk_add_f32 v[184:185], v[102:103], v[106:107] neg_lo:[0,1] neg_hi:[0,1]
	v_pk_add_f32 v[100:101], v[188:189], v[168:169]
	v_pk_add_f32 v[104:105], v[188:189], v[168:169] neg_lo:[0,1] neg_hi:[0,1]
	v_pk_add_f32 v[102:103], v[186:187], v[184:185] op_sel:[0,1] op_sel_hi:[1,0] neg_hi:[0,1]
	v_pk_add_f32 v[106:107], v[186:187], v[184:185] op_sel:[0,1] op_sel_hi:[1,0] neg_lo:[0,1]
	v_pk_add_f32 v[182:183], v[108:109], v[112:113]
	v_pk_add_f32 v[180:181], v[108:109], v[112:113] neg_lo:[0,1] neg_hi:[0,1]
	v_pk_add_f32 v[178:179], v[110:111], v[114:115]
	v_pk_add_f32 v[176:177], v[110:111], v[114:115] neg_lo:[0,1] neg_hi:[0,1]
	v_pk_add_f32 v[108:109], v[182:183], v[178:179]
	v_pk_add_f32 v[112:113], v[182:183], v[178:179] neg_lo:[0,1] neg_hi:[0,1]
	v_pk_add_f32 v[110:111], v[180:181], v[176:177] op_sel:[0,1] op_sel_hi:[1,0] neg_hi:[0,1]
	v_pk_add_f32 v[114:115], v[180:181], v[176:177] op_sel:[0,1] op_sel_hi:[1,0] neg_lo:[0,1]
	v_pk_add_f32 v[166:167], v[116:117], v[120:121] op_sel:[0,1] op_sel_hi:[1,0] neg_hi:[0,1]
	v_pk_add_f32 v[174:175], v[116:117], v[120:121] op_sel:[0,1] op_sel_hi:[1,0] neg_lo:[0,1]
	v_pk_add_f32 v[188:189], v[118:119], v[122:123]
	v_pk_add_f32 v[186:187], v[118:119], v[122:123] neg_lo:[0,1] neg_hi:[0,1]
	v_pk_add_f32 v[116:117], v[166:167], v[188:189]
	v_pk_add_f32 v[120:121], v[166:167], v[188:189] neg_lo:[0,1] neg_hi:[0,1]
	v_pk_add_f32 v[118:119], v[174:175], v[186:187] op_sel:[0,1] op_sel_hi:[1,0] neg_hi:[0,1]
	v_pk_add_f32 v[122:123], v[174:175], v[186:187] op_sel:[0,1] op_sel_hi:[1,0] neg_lo:[0,1]
	v_pk_add_f32 v[168:169], v[124:125], v[128:129]
	v_pk_add_f32 v[184:185], v[124:125], v[128:129] neg_lo:[0,1] neg_hi:[0,1]
	v_pk_add_f32 v[182:183], v[126:127], v[130:131]
	v_pk_add_f32 v[180:181], v[126:127], v[130:131] neg_lo:[0,1] neg_hi:[0,1]
	v_pk_add_f32 v[124:125], v[168:169], v[182:183]
	v_pk_add_f32 v[128:129], v[168:169], v[182:183] neg_lo:[0,1] neg_hi:[0,1]
	v_pk_add_f32 v[126:127], v[184:185], v[180:181] op_sel:[0,1] op_sel_hi:[1,0] neg_hi:[0,1]
	v_pk_add_f32 v[130:131], v[184:185], v[180:181] op_sel:[0,1] op_sel_hi:[1,0] neg_lo:[0,1]
	v_pk_mul_f32 v[100:101], v[100:101], v[192:193] op_sel_hi:[1,0]
	ds_write_b64 v69, v[100:101]
	v_pk_mul_f32 v[108:109], v[108:109], v[192:193] op_sel_hi:[1,0]
	ds_write_b64 v69, v[108:109] offset:16
	v_pk_mul_f32 v[116:117], v[116:117], v[192:193] op_sel_hi:[1,0]
	ds_write_b64 v69, v[116:117] offset:32
	v_pk_mul_f32 v[124:125], v[124:125], v[192:193] op_sel_hi:[1,0]
	ds_write_b64 v69, v[124:125] offset:48
	v_pk_mul_f32 v[102:103], v[102:103], v[192:193] op_sel_hi:[1,0]
	ds_write_b64 v69, v[102:103] offset:64
	v_pk_mul_f32 v[110:111], v[110:111], v[192:193] op_sel_hi:[1,0]
	ds_write_b64 v69, v[110:111] offset:80
	v_pk_mul_f32 v[118:119], v[118:119], v[192:193] op_sel_hi:[1,0]
	ds_write_b64 v69, v[118:119] offset:96
	v_pk_mul_f32 v[126:127], v[126:127], v[192:193] op_sel_hi:[1,0]
	ds_write_b64 v69, v[126:127] offset:112
	v_pk_mul_f32 v[104:105], v[104:105], v[192:193] op_sel_hi:[1,0]
	ds_write_b64 v69, v[104:105] offset:128
	v_pk_mul_f32 v[112:113], v[112:113], v[192:193] op_sel_hi:[1,0]
	ds_write_b64 v69, v[112:113] offset:144
	v_pk_mul_f32 v[120:121], v[120:121], v[192:193] op_sel_hi:[1,0]
	ds_write_b64 v69, v[120:121] offset:160
	v_pk_mul_f32 v[128:129], v[128:129], v[192:193] op_sel_hi:[1,0]
	ds_write_b64 v69, v[128:129] offset:176
	v_pk_mul_f32 v[106:107], v[106:107], v[192:193] op_sel_hi:[1,0]
	ds_write_b64 v69, v[106:107] offset:192
	v_pk_mul_f32 v[114:115], v[114:115], v[192:193] op_sel_hi:[1,0]
	ds_write_b64 v69, v[114:115] offset:208
	v_pk_mul_f32 v[122:123], v[122:123], v[192:193] op_sel_hi:[1,0]
	ds_write_b64 v69, v[122:123] offset:224
	v_pk_mul_f32 v[130:131], v[130:131], v[192:193] op_sel_hi:[1,0]
	ds_write_b64 v69, v[130:131] offset:240
	s_waitcnt lgkmcnt(0)
	s_barrier
	s_cbranch_vccz .Lhfft_st4
	s_sleep 4
; #define LAS __attribute__((address_space(3)))
; __device__ __forceinline__ f32x2 cmul(f32x2 a, f32x2 b) { return (f32x2){a.x * b.x - a.y * b.y, a.x * b.y + a.y * b.x}; }
; #define WG_SYNC() do { asm volatile("s_waitcnt lgkmcnt(0)" ::: "memory"); __builtin_amdgcn_s_barrier(); asm volatile("" ::: "memory"); } while (0)
; __device__ __forceinline__ void dft16_fwd_lo(f32x2 (&x)[16]) {
;     constexpr float C1 = 0.92387953251128674f, S1 = 0.38268343236508977f, C2 = 0.70710678118654752f;
; #pragma unroll
;     for (int b = 0; b < 4; ++b) { const f32x2 x0 = x[b], x1 = x[4 + b]; const f32x2 j1 = {x1.y, -x1.x};
;         x[b] = x0 + x1; x[4 + b] = x0 + j1; x[8 + b] = x0 - x1; x[12 + b] = x0 - j1; }
;     const f32x2 w1 = {C1, -S1}, w2 = {C2, -C2}, w3 = {S1, -C1}, w4 = {0.f, -1.f}, w6 = {-C2, -C2}, w9 = {-C1, S1};
;     x[5] = cmul(x[5], w1); x[6] = cmul(x[6], w2); x[7] = cmul(x[7], w3);
;     x[9] = cmul(x[9], w2); x[10] = cmul(x[10], w4); x[11] = cmul(x[11], w6);
;     x[13] = cmul(x[13], w3); x[14] = cmul(x[14], w6); x[15] = cmul(x[15], w9);
; #pragma unroll
;     for (int c = 0; c < 4; ++c) dft4<false>(x[4 * c], x[4 * c + 1], x[4 * c + 2], x[4 * c + 3]);
;     f32x2 y[16];
; #pragma unroll
;     for (int k = 0; k < 16; ++k) y[k] = x[4 * (k & 3) + (k >> 2)];
; #pragma unroll
;     for (int k = 0; k < 16; ++k) x[k] = y[k];
; }
; template <bool LO> __device__ __forceinline__ void fft_fwd1(f32x2 (&x)[16], LAS f32x2* B, int n2, const f32x2 (&w)[16]) {
;     asm volatile("" : "+v"(n2));
;     if (LO) dft16_fwd_lo(x); else dft16<false>(x);
;     B[fpad(n2)] = x[0];
; #pragma unroll
;     for (int k = 1; k < 16; ++k) B[fpad(512 * k + n2)] = cmul(x[k], w[k]);
; }
; __device__ __forceinline__ void hyena_fft(LAS unsigned char* lds, int layer, int G, const int wave_s) {
;     ...
;             for (int r = 0; r < 8; ++r) { x[r] = (f32x2){uz[r][0], uz[r][1]}; x[r + 8] = (f32x2){0.f, 0.f}; }
;             fft_fwd1<true>(x, Db, n2, w1p); WG_SYNC();
.Lhfft_st4:
	v_pk_add_f32 v[104:105], v[132:133], v[140:141] neg_lo:[0,1] neg_hi:[0,1]
	v_pk_add_f32 v[106:107], v[132:133], v[140:141] op_sel:[0,1] op_sel_hi:[1,0] neg_lo:[0,1]
	v_pk_add_f32 v[178:179], v[132:133], v[140:141] op_sel:[0,1] op_sel_hi:[1,0] neg_hi:[0,1]
	v_pk_add_f32 v[100:101], v[132:133], v[140:141]
	v_pk_add_f32 v[112:113], v[134:135], v[142:143] neg_lo:[0,1] neg_hi:[0,1]
	v_pk_add_f32 v[114:115], v[134:135], v[142:143] op_sel:[0,1] op_sel_hi:[1,0] neg_lo:[0,1]
	v_pk_add_f32 v[176:177], v[134:135], v[142:143] op_sel:[0,1] op_sel_hi:[1,0] neg_hi:[0,1]
	v_pk_add_f32 v[108:109], v[134:135], v[142:143]
	v_pk_add_f32 v[120:121], v[136:137], v[144:145] neg_lo:[0,1] neg_hi:[0,1]
	v_pk_add_f32 v[122:123], v[136:137], v[144:145] op_sel:[0,1] op_sel_hi:[1,0] neg_lo:[0,1]
	v_pk_add_f32 v[166:167], v[136:137], v[144:145] op_sel:[0,1] op_sel_hi:[1,0] neg_hi:[0,1]
	v_pk_add_f32 v[116:117], v[136:137], v[144:145]
	v_pk_add_f32 v[128:129], v[138:139], v[146:147] neg_lo:[0,1] neg_hi:[0,1]
	v_pk_add_f32 v[130:131], v[138:139], v[146:147] op_sel:[0,1] op_sel_hi:[1,0] neg_lo:[0,1]
	v_pk_add_f32 v[174:175], v[138:139], v[146:147] op_sel:[0,1] op_sel_hi:[1,0] neg_hi:[0,1]
	v_pk_add_f32 v[124:125], v[138:139], v[146:147]
	v_pk_mul_f32 v[188:189], v[176:177], s[68:69] op_sel:[1,1] op_sel_hi:[0,1]
	v_pk_fma_f32 v[176:177], v[176:177], s[68:69], v[188:189] op_sel_hi:[1,0,1] neg_lo:[0,0,1]
	v_pk_mul_f32 v[186:187], v[166:167], s[84:85] op_sel:[1,1] op_sel_hi:[0,1]
	v_pk_fma_f32 v[166:167], v[166:167], s[84:85], v[186:187] op_sel_hi:[1,0,1] neg_lo:[0,0,1]
	v_pk_mul_f32 v[168:169], v[174:175], s[88:89] op_sel:[1,1] op_sel_hi:[0,1]
	v_pk_fma_f32 v[174:175], v[174:175], s[88:89], v[168:169] op_sel_hi:[1,0,1] neg_lo:[0,0,1]
	v_pk_mul_f32 v[184:185], v[112:113], s[84:85] op_sel:[1,1] op_sel_hi:[0,1]
	v_pk_fma_f32 v[112:113], v[112:113], s[84:85], v[184:185] op_sel_hi:[1,0,1] neg_lo:[0,0,1]
	v_pk_mul_f32 v[182:183], v[128:129], s[90:91] op_sel:[1,1] op_sel_hi:[0,1]
	v_pk_fma_f32 v[128:129], v[128:129], s[90:91], v[182:183] op_sel_hi:[1,0,1] neg_lo:[0,0,1]
	v_pk_mul_f32 v[180:181], v[114:115], s[88:89] op_sel:[1,1] op_sel_hi:[0,1]
	v_pk_fma_f32 v[114:115], v[114:115], s[88:89], v[180:181] op_sel_hi:[1,0,1] neg_lo:[0,0,1]
	v_pk_mul_f32 v[102:103], v[122:123], s[90:91] op_sel:[1,1] op_sel_hi:[0,1]
	v_pk_fma_f32 v[122:123], v[122:123], s[90:91], v[102:103] op_sel_hi:[1,0,1] neg_lo:[0,0,1]
	v_pk_mul_f32 v[110:111], v[130:131], s[98:99] op_sel:[1,1] op_sel_hi:[0,1]
	v_pk_fma_f32 v[130:131], v[130:131], s[98:99], v[110:111] op_sel_hi:[1,0,1] neg_lo:[0,0,1]
	v_pk_add_f32 v[118:119], v[100:101], v[116:117]
	v_pk_add_f32 v[126:127], v[100:101], v[116:117] neg_lo:[0,1] neg_hi:[0,1]
	v_pk_add_f32 v[188:189], v[108:109], v[124:125]
	v_pk_add_f32 v[186:187], v[108:109], v[124:125] neg_lo:[0,1] neg_hi:[0,1]
	v_pk_add_f32 v[100:101], v[118:119], v[188:189]
	v_pk_add_f32 v[116:117], v[118:119], v[188:189] neg_lo:[0,1] neg_hi:[0,1]
	v_pk_add_f32 v[108:109], v[126:127], v[186:187] op_sel:[0,1] op_sel_hi:[1,0] neg_hi:[0,1]
	v_pk_add_f32 v[124:125], v[126:127], v[186:187] op_sel:[0,1] op_sel_hi:[1,0] neg_lo:[0,1]
	v_pk_add_f32 v[168:169], v[178:179], v[166:167]
	v_pk_add_f32 v[184:185], v[178:179], v[166:167] neg_lo:[0,1] neg_hi:[0,1]
	v_pk_add_f32 v[182:183], v[176:177], v[174:175]
	v_pk_add_f32 v[180:181], v[176:177], v[174:175] neg_lo:[0,1] neg_hi:[0,1]
	v_pk_add_f32 v[178:179], v[168:169], v[182:183]
	v_pk_add_f32 v[166:167], v[168:169], v[182:183] neg_lo:[0,1] neg_hi:[0,1]
	v_pk_add_f32 v[176:177], v[184:185], v[180:181] op_sel:[0,1] op_sel_hi:[1,0] neg_hi:[0,1]
	v_pk_add_f32 v[174:175], v[184:185], v[180:181] op_sel:[0,1] op_sel_hi:[1,0] neg_lo:[0,1]
	v_pk_add_f32 v[102:103], v[104:105], v[120:121] op_sel:[0,1] op_sel_hi:[1,0] neg_hi:[0,1]
	v_pk_add_f32 v[110:111], v[104:105], v[120:121] op_sel:[0,1] op_sel_hi:[1,0] neg_lo:[0,1]
	v_pk_add_f32 v[118:119], v[112:113], v[128:129]
	v_pk_add_f32 v[126:127], v[112:113], v[128:129] neg_lo:[0,1] neg_hi:[0,1]
	v_pk_add_f32 v[104:105], v[102:103], v[118:119]
	v_pk_add_f32 v[120:121], v[102:103], v[118:119] neg_lo:[0,1] neg_hi:[0,1]
	v_pk_add_f32 v[112:113], v[110:111], v[126:127] op_sel:[0,1] op_sel_hi:[1,0] neg_hi:[0,1]
	v_pk_add_f32 v[128:129], v[110:111], v[126:127] op_sel:[0,1] op_sel_hi:[1,0] neg_lo:[0,1]
	v_pk_add_f32 v[188:189], v[106:107], v[122:123]
	v_pk_add_f32 v[186:187], v[106:107], v[122:123] neg_lo:[0,1] neg_hi:[0,1]
	v_pk_add_f32 v[168:169], v[114:115], v[130:131]
	v_pk_add_f32 v[184:185], v[114:115], v[130:131] neg_lo:[0,1] neg_hi:[0,1]
	v_pk_add_f32 v[106:107], v[188:189], v[168:169]
	v_pk_add_f32 v[122:123], v[188:189], v[168:169] neg_lo:[0,1] neg_hi:[0,1]
	v_pk_add_f32 v[114:115], v[186:187], v[184:185] op_sel:[0,1] op_sel_hi:[1,0] neg_hi:[0,1]
	v_pk_add_f32 v[130:131], v[186:187], v[184:185] op_sel:[0,1] op_sel_hi:[1,0] neg_lo:[0,1]
	ds_write_b64 v3, v[100:101]
	v_pk_mul_f32 v[180:181], v[178:179], v[6:7] op_sel:[1,1] op_sel_hi:[0,1]
	v_pk_fma_f32 v[182:183], v[178:179], v[6:7], v[180:181] op_sel_hi:[1,0,1] neg_lo:[0,0,1]
	ds_write_b64 v3, v[182:183] offset:4224
	v_pk_mul_f32 v[110:111], v[104:105], v[8:9] op_sel:[1,1] op_sel_hi:[0,1]
	v_pk_fma_f32 v[102:103], v[104:105], v[8:9], v[110:111] op_sel_hi:[1,0,1] neg_lo:[0,0,1]
	ds_write_b64 v3, v[102:103] offset:8448
	v_pk_mul_f32 v[126:127], v[106:107], v[10:11] op_sel:[1,1] op_sel_hi:[0,1]
	v_pk_fma_f32 v[118:119], v[106:107], v[10:11], v[126:127] op_sel_hi:[1,0,1] neg_lo:[0,0,1]
	ds_write_b64 v3, v[118:119] offset:12672
	v_pk_mul_f32 v[186:187], v[108:109], v[12:13] op_sel:[1,1] op_sel_hi:[0,1]
	v_pk_fma_f32 v[188:189], v[108:109], v[12:13], v[186:187] op_sel_hi:[1,0,1] neg_lo:[0,0,1]
; #define LAS __attribute__((address_space(3)))
; __device__ __forceinline__ f32x2 cmul(f32x2 a, f32x2 b) { return (f32x2){a.x * b.x - a.y * b.y, a.x * b.y + a.y * b.x}; }
; #define WG_SYNC() do { asm volatile("s_waitcnt lgkmcnt(0)" ::: "memory"); __builtin_amdgcn_s_barrier(); asm volatile("" ::: "memory"); } while (0)
; #define WAVE_FENCE() do { asm volatile("s_waitcnt lgkmcnt(0)" ::: "memory"); __builtin_amdgcn_sched_barrier(0); } while (0)
; template <bool LO> __device__ __forceinline__ void fft_fwd1(f32x2 (&x)[16], LAS f32x2* B, int n2, const f32x2 (&w)[16]) {
;     ...
; #pragma unroll
;     for (int k = 1; k < 16; ++k) B[fpad(512 * k + n2)] = cmul(x[k], w[k]);
; }
; __device__ __forceinline__ void fft_fwd2(LAS f32x2* B, const LAS f32x2* TW2, int tid) {
;     asm volatile("" : "+v"(tid));
;     const int b = tid >> 5, n2 = tid & 31, base = 512 * b + n2; f32x2 x[16];
; #pragma unroll
;     for (int r = 0; r < 16; ++r) x[r] = B[fpad(base + 32 * r)];
;     dft16<false>(x);
; __device__ __forceinline__ void hyena_fft(LAS unsigned char* lds, int layer, int G, const int wave_s) {
;     ...
;             fft_fwd1<true>(x, Db, n2, w1p); WG_SYNC();
;             fft_fwd2(Db, TW2, tid); WAVE_FENCE(); fft_pair32<0>(Db, Fb, wave, lane); WAVE_FENCE(); fft_inv2(Db, TW2, tid);
	ds_write_b64 v3, v[188:189] offset:16896
	v_pk_mul_f32 v[184:185], v[176:177], v[14:15] op_sel:[1,1] op_sel_hi:[0,1]
	v_pk_fma_f32 v[168:169], v[176:177], v[14:15], v[184:185] op_sel_hi:[1,0,1] neg_lo:[0,0,1]
	ds_write_b64 v3, v[168:169] offset:21120
	v_pk_mul_f32 v[182:183], v[112:113], v[16:17] op_sel:[1,1] op_sel_hi:[0,1]
	v_pk_fma_f32 v[180:181], v[112:113], v[16:17], v[182:183] op_sel_hi:[1,0,1] neg_lo:[0,0,1]
	ds_write_b64 v3, v[180:181] offset:25344
	v_pk_mul_f32 v[102:103], v[114:115], v[18:19] op_sel:[1,1] op_sel_hi:[0,1]
	v_pk_fma_f32 v[110:111], v[114:115], v[18:19], v[102:103] op_sel_hi:[1,0,1] neg_lo:[0,0,1]
	ds_write_b64 v3, v[110:111] offset:29568
	v_pk_mul_f32 v[118:119], v[116:117], v[20:21] op_sel:[1,1] op_sel_hi:[0,1]
	v_pk_fma_f32 v[126:127], v[116:117], v[20:21], v[118:119] op_sel_hi:[1,0,1] neg_lo:[0,0,1]
	ds_write_b64 v3, v[126:127] offset:33792
	v_pk_mul_f32 v[188:189], v[166:167], v[22:23] op_sel:[1,1] op_sel_hi:[0,1]
	v_pk_fma_f32 v[186:187], v[166:167], v[22:23], v[188:189] op_sel_hi:[1,0,1] neg_lo:[0,0,1]
	ds_write_b64 v3, v[186:187] offset:38016
	v_pk_mul_f32 v[168:169], v[120:121], v[24:25] op_sel:[1,1] op_sel_hi:[0,1]
	v_pk_fma_f32 v[184:185], v[120:121], v[24:25], v[168:169] op_sel_hi:[1,0,1] neg_lo:[0,0,1]
	ds_write_b64 v3, v[184:185] offset:42240
	v_pk_mul_f32 v[180:181], v[122:123], v[26:27] op_sel:[1,1] op_sel_hi:[0,1]
	v_pk_fma_f32 v[182:183], v[122:123], v[26:27], v[180:181] op_sel_hi:[1,0,1] neg_lo:[0,0,1]
	ds_write_b64 v3, v[182:183] offset:46464
	v_pk_mul_f32 v[110:111], v[124:125], v[28:29] op_sel:[1,1] op_sel_hi:[0,1]
	v_pk_fma_f32 v[102:103], v[124:125], v[28:29], v[110:111] op_sel_hi:[1,0,1] neg_lo:[0,0,1]
	ds_write_b64 v3, v[102:103] offset:50688
	v_pk_mul_f32 v[126:127], v[174:175], v[30:31] op_sel:[1,1] op_sel_hi:[0,1]
	v_pk_fma_f32 v[118:119], v[174:175], v[30:31], v[126:127] op_sel_hi:[1,0,1] neg_lo:[0,0,1]
	ds_write_b64 v3, v[118:119] offset:54912
	v_pk_mul_f32 v[186:187], v[128:129], v[32:33] op_sel:[1,1] op_sel_hi:[0,1]
	v_pk_fma_f32 v[188:189], v[128:129], v[32:33], v[186:187] op_sel_hi:[1,0,1] neg_lo:[0,0,1]
	ds_write_b64 v3, v[188:189] offset:59136
	v_pk_mul_f32 v[184:185], v[130:131], v[34:35] op_sel:[1,1] op_sel_hi:[0,1]
	v_pk_fma_f32 v[168:169], v[130:131], v[34:35], v[184:185] op_sel_hi:[1,0,1] neg_lo:[0,0,1]
	ds_write_b64 v3, v[168:169] offset:63360
	s_waitcnt lgkmcnt(0)
	s_barrier
	s_cbranch_vccz .Lhfft_st5
	s_sleep 4
.Lhfft_st5:
	ds_read_b64 v[100:101], v5
	ds_read_b64 v[108:109], v5 offset:1056
	ds_read_b64 v[116:117], v5 offset:2112
	ds_read_b64 v[124:125], v5 offset:3168
	ds_read_b64 v[178:179], v5 offset:264
	ds_read_b64 v[176:177], v5 offset:1320
	ds_read_b64 v[166:167], v5 offset:2376
	ds_read_b64 v[174:175], v5 offset:3432
	ds_read_b64 v[104:105], v5 offset:528
	ds_read_b64 v[112:113], v5 offset:1584
	ds_read_b64 v[120:121], v5 offset:2640
	ds_read_b64 v[128:129], v5 offset:3696
	s_waitcnt lgkmcnt(8)
	ds_read_b64 v[106:107], v5 offset:792
	ds_read_b64 v[114:115], v5 offset:1848
	ds_read_b64 v[122:123], v5 offset:2904
	ds_read_b64 v[130:131], v5 offset:3960
	v_pk_add_f32 v[180:181], v[100:101], v[116:117]
	v_pk_add_f32 v[182:183], v[100:101], v[116:117] neg_lo:[0,1] neg_hi:[0,1]
	v_pk_add_f32 v[110:111], v[108:109], v[124:125]
	v_pk_add_f32 v[102:103], v[108:109], v[124:125] neg_lo:[0,1] neg_hi:[0,1]
	v_pk_add_f32 v[100:101], v[180:181], v[110:111]
	v_pk_add_f32 v[116:117], v[180:181], v[110:111] neg_lo:[0,1] neg_hi:[0,1]
	v_pk_add_f32 v[108:109], v[182:183], v[102:103] op_sel:[0,1] op_sel_hi:[1,0] neg_hi:[0,1]
	v_pk_add_f32 v[124:125], v[182:183], v[102:103] op_sel:[0,1] op_sel_hi:[1,0] neg_lo:[0,1]
	s_waitcnt lgkmcnt(9)
	v_pk_add_f32 v[126:127], v[178:179], v[166:167]
	v_pk_add_f32 v[118:119], v[178:179], v[166:167] neg_lo:[0,1] neg_hi:[0,1]
	s_waitcnt lgkmcnt(8)
	v_pk_add_f32 v[186:187], v[176:177], v[174:175]
	v_pk_add_f32 v[188:189], v[176:177], v[174:175] neg_lo:[0,1] neg_hi:[0,1]
	v_pk_add_f32 v[178:179], v[126:127], v[186:187]
	v_pk_add_f32 v[166:167], v[126:127], v[186:187] neg_lo:[0,1] neg_hi:[0,1]
	v_pk_add_f32 v[176:177], v[118:119], v[188:189] op_sel:[0,1] op_sel_hi:[1,0] neg_hi:[0,1]
	v_pk_add_f32 v[174:175], v[118:119], v[188:189] op_sel:[0,1] op_sel_hi:[1,0] neg_lo:[0,1]
	s_waitcnt lgkmcnt(5)
	v_pk_add_f32 v[184:185], v[104:105], v[120:121]
	v_pk_add_f32 v[168:169], v[104:105], v[120:121] neg_lo:[0,1] neg_hi:[0,1]
	s_waitcnt lgkmcnt(4)
	v_pk_add_f32 v[180:181], v[112:113], v[128:129]
	v_pk_add_f32 v[182:183], v[112:113], v[128:129] neg_lo:[0,1] neg_hi:[0,1]
	v_pk_add_f32 v[104:105], v[184:185], v[180:181]
	v_pk_add_f32 v[120:121], v[184:185], v[180:181] neg_lo:[0,1] neg_hi:[0,1]
	v_pk_add_f32 v[112:113], v[168:169], v[182:183] op_sel:[0,1] op_sel_hi:[1,0] neg_hi:[0,1]
	v_pk_add_f32 v[128:129], v[168:169], v[182:183] op_sel:[0,1] op_sel_hi:[1,0] neg_lo:[0,1]
	s_waitcnt lgkmcnt(1)
	v_pk_add_f32 v[110:111], v[106:107], v[122:123]
	v_pk_add_f32 v[102:103], v[106:107], v[122:123] neg_lo:[0,1] neg_hi:[0,1]
	s_waitcnt lgkmcnt(0)
; __device__ __forceinline__ f32x2 cmul(f32x2 a, f32x2 b) { return (f32x2){a.x * b.x - a.y * b.y, a.x * b.y + a.y * b.x}; }
; template <bool INV> __device__ __forceinline__ f32x2 cmul_tw(f32x2 a, f32x2 w) { return INV ? cmulc(a, w) : cmul(a, w); }
; template <bool INV> __device__ __forceinline__ void dft16(f32x2 (&x)[16]) {
;     constexpr float C1 = 0.92387953251128674f, S1 = 0.38268343236508977f, C2 = 0.70710678118654752f;
; #pragma unroll
;     for (int b = 0; b < 4; ++b) dft4<INV>(x[b], x[4 + b], x[8 + b], x[12 + b]);
;     const f32x2 w1 = {C1, -S1}, w2 = {C2, -C2}, w3 = {S1, -C1}, w4 = {0.f, -1.f}, w6 = {-C2, -C2}, w9 = {-C1, S1};
;     x[4 * 1 + 1] = cmul_tw<INV>(x[5], w1); x[4 * 1 + 2] = cmul_tw<INV>(x[6], w2); x[4 * 1 + 3] = cmul_tw<INV>(x[7], w3);
;     x[4 * 2 + 1] = cmul_tw<INV>(x[9], w2); x[4 * 2 + 2] = cmul_tw<INV>(x[10], w4); x[4 * 2 + 3] = cmul_tw<INV>(x[11], w6);
;     x[4 * 3 + 1] = cmul_tw<INV>(x[13], w3); x[4 * 3 + 2] = cmul_tw<INV>(x[14], w6); x[4 * 3 + 3] = cmul_tw<INV>(x[15], w9);
; #pragma unroll
;     for (int c = 0; c < 4; ++c) dft4<INV>(x[4 * c], x[4 * c + 1], x[4 * c + 2], x[4 * c + 3]);
;     f32x2 y[16];
; #pragma unroll
;     for (int k = 0; k < 16; ++k) y[k] = x[4 * (k & 3) + (k >> 2)];
; #pragma unroll
;     for (int k = 0; k < 16; ++k) x[k] = y[k];
; }
; __device__ __forceinline__ void fft_fwd2(LAS f32x2* B, const LAS f32x2* TW2, int tid) {
;     ...
;     dft16<false>(x);
;     B[fpad(base)] = x[0];
; #pragma unroll
;     for (int k = 1; k < 16; ++k) B[fpad(base + 32 * k)] = cmul(x[k], TW2[k * 32 + n2]);
	v_pk_add_f32 v[126:127], v[114:115], v[130:131]
	v_pk_add_f32 v[118:119], v[114:115], v[130:131] neg_lo:[0,1] neg_hi:[0,1]
	v_pk_add_f32 v[106:107], v[110:111], v[126:127]
	v_pk_add_f32 v[122:123], v[110:111], v[126:127] neg_lo:[0,1] neg_hi:[0,1]
	v_pk_add_f32 v[114:115], v[102:103], v[118:119] op_sel:[0,1] op_sel_hi:[1,0] neg_hi:[0,1]
	v_pk_add_f32 v[130:131], v[102:103], v[118:119] op_sel:[0,1] op_sel_hi:[1,0] neg_lo:[0,1]
	v_pk_mul_f32 v[186:187], v[176:177], s[68:69] op_sel:[1,1] op_sel_hi:[0,1]
	v_pk_fma_f32 v[176:177], v[176:177], s[68:69], v[186:187] op_sel_hi:[1,0,1] neg_lo:[0,0,1]
	v_pk_mul_f32 v[188:189], v[112:113], s[84:85] op_sel:[1,1] op_sel_hi:[0,1]
	v_pk_fma_f32 v[112:113], v[112:113], s[84:85], v[188:189] op_sel_hi:[1,0,1] neg_lo:[0,0,1]
	v_pk_mul_f32 v[184:185], v[114:115], s[88:89] op_sel:[1,1] op_sel_hi:[0,1]
	v_pk_fma_f32 v[114:115], v[114:115], s[88:89], v[184:185] op_sel_hi:[1,0,1] neg_lo:[0,0,1]
	v_pk_mul_f32 v[168:169], v[166:167], s[84:85] op_sel:[1,1] op_sel_hi:[0,1]
	v_pk_fma_f32 v[166:167], v[166:167], s[84:85], v[168:169] op_sel_hi:[1,0,1] neg_lo:[0,0,1]
	v_pk_mul_f32 v[180:181], v[122:123], s[90:91] op_sel:[1,1] op_sel_hi:[0,1]
	v_pk_fma_f32 v[122:123], v[122:123], s[90:91], v[180:181] op_sel_hi:[1,0,1] neg_lo:[0,0,1]
	v_pk_mul_f32 v[182:183], v[174:175], s[88:89] op_sel:[1,1] op_sel_hi:[0,1]
	v_pk_fma_f32 v[174:175], v[174:175], s[88:89], v[182:183] op_sel_hi:[1,0,1] neg_lo:[0,0,1]
	v_pk_mul_f32 v[110:111], v[128:129], s[90:91] op_sel:[1,1] op_sel_hi:[0,1]
	v_pk_fma_f32 v[128:129], v[128:129], s[90:91], v[110:111] op_sel_hi:[1,0,1] neg_lo:[0,0,1]
	v_pk_mul_f32 v[102:103], v[130:131], s[98:99] op_sel:[1,1] op_sel_hi:[0,1]
	v_pk_fma_f32 v[130:131], v[130:131], s[98:99], v[102:103] op_sel_hi:[1,0,1] neg_lo:[0,0,1]
	v_pk_add_f32 v[126:127], v[100:101], v[104:105]
	v_pk_add_f32 v[118:119], v[100:101], v[104:105] neg_lo:[0,1] neg_hi:[0,1]
	v_pk_add_f32 v[186:187], v[178:179], v[106:107]
	v_pk_add_f32 v[188:189], v[178:179], v[106:107] neg_lo:[0,1] neg_hi:[0,1]
	v_pk_add_f32 v[100:101], v[126:127], v[186:187]
	v_pk_add_f32 v[104:105], v[126:127], v[186:187] neg_lo:[0,1] neg_hi:[0,1]
	v_pk_add_f32 v[178:179], v[118:119], v[188:189] op_sel:[0,1] op_sel_hi:[1,0] neg_hi:[0,1]
	v_pk_add_f32 v[106:107], v[118:119], v[188:189] op_sel:[0,1] op_sel_hi:[1,0] neg_lo:[0,1]
	v_pk_add_f32 v[184:185], v[108:109], v[112:113]
	v_pk_add_f32 v[168:169], v[108:109], v[112:113] neg_lo:[0,1] neg_hi:[0,1]
	v_pk_add_f32 v[180:181], v[176:177], v[114:115]
	v_pk_add_f32 v[182:183], v[176:177], v[114:115] neg_lo:[0,1] neg_hi:[0,1]
	v_pk_add_f32 v[108:109], v[184:185], v[180:181]
	v_pk_add_f32 v[112:113], v[184:185], v[180:181] neg_lo:[0,1] neg_hi:[0,1]
	v_pk_add_f32 v[176:177], v[168:169], v[182:183] op_sel:[0,1] op_sel_hi:[1,0] neg_hi:[0,1]
	v_pk_add_f32 v[114:115], v[168:169], v[182:183] op_sel:[0,1] op_sel_hi:[1,0] neg_lo:[0,1]
	v_pk_add_f32 v[110:111], v[116:117], v[120:121] op_sel:[0,1] op_sel_hi:[1,0] neg_hi:[0,1]
	v_pk_add_f32 v[102:103], v[116:117], v[120:121] op_sel:[0,1] op_sel_hi:[1,0] neg_lo:[0,1]
	v_pk_add_f32 v[126:127], v[166:167], v[122:123]
	v_pk_add_f32 v[118:119], v[166:167], v[122:123] neg_lo:[0,1] neg_hi:[0,1]
	v_pk_add_f32 v[116:117], v[110:111], v[126:127]
	v_pk_add_f32 v[120:121], v[110:111], v[126:127] neg_lo:[0,1] neg_hi:[0,1]
	v_pk_add_f32 v[166:167], v[102:103], v[118:119] op_sel:[0,1] op_sel_hi:[1,0] neg_hi:[0,1]
	v_pk_add_f32 v[122:123], v[102:103], v[118:119] op_sel:[0,1] op_sel_hi:[1,0] neg_lo:[0,1]
	v_pk_add_f32 v[186:187], v[124:125], v[128:129]
	v_pk_add_f32 v[188:189], v[124:125], v[128:129] neg_lo:[0,1] neg_hi:[0,1]
	v_pk_add_f32 v[184:185], v[174:175], v[130:131]
	v_pk_add_f32 v[168:169], v[174:175], v[130:131] neg_lo:[0,1] neg_hi:[0,1]
	v_pk_add_f32 v[124:125], v[186:187], v[184:185]
	v_pk_add_f32 v[128:129], v[186:187], v[184:185] neg_lo:[0,1] neg_hi:[0,1]
	v_pk_add_f32 v[174:175], v[188:189], v[168:169] op_sel:[0,1] op_sel_hi:[1,0] neg_hi:[0,1]
	v_pk_add_f32 v[130:131], v[188:189], v[168:169] op_sel:[0,1] op_sel_hi:[1,0] neg_lo:[0,1]
	ds_write_b64 v5, v[100:101]
	ds_read_b64 v[180:181], v56 offset:256
	ds_read_b64 v[182:183], v56 offset:512
	ds_read_b64 v[110:111], v56 offset:768
	ds_read_b64 v[102:103], v56 offset:1024
	s_waitcnt lgkmcnt(3)
	v_pk_mul_f32 v[126:127], v[108:109], v[180:181] op_sel:[1,1] op_sel_hi:[0,1]
	v_pk_fma_f32 v[108:109], v[108:109], v[180:181], v[126:127] op_sel_hi:[1,0,1] neg_lo:[0,0,1]
	ds_write_b64 v5, v[108:109] offset:264
	s_waitcnt lgkmcnt(3)
	v_pk_mul_f32 v[118:119], v[116:117], v[182:183] op_sel:[1,1] op_sel_hi:[0,1]
	v_pk_fma_f32 v[116:117], v[116:117], v[182:183], v[118:119] op_sel_hi:[1,0,1] neg_lo:[0,0,1]
	ds_write_b64 v5, v[116:117] offset:528
	s_waitcnt lgkmcnt(3)
	v_pk_mul_f32 v[186:187], v[124:125], v[110:111] op_sel:[1,1] op_sel_hi:[0,1]
	v_pk_fma_f32 v[124:125], v[124:125], v[110:111], v[186:187] op_sel_hi:[1,0,1] neg_lo:[0,0,1]
	ds_write_b64 v5, v[124:125] offset:792
	s_waitcnt lgkmcnt(3)
	v_pk_mul_f32 v[188:189], v[178:179], v[102:103] op_sel:[1,1] op_sel_hi:[0,1]
	v_pk_fma_f32 v[178:179], v[178:179], v[102:103], v[188:189] op_sel_hi:[1,0,1] neg_lo:[0,0,1]
	ds_write_b64 v5, v[178:179] offset:1056
	ds_read_b64 v[184:185], v56 offset:1280
	ds_read_b64 v[168:169], v56 offset:1536
	ds_read_b64 v[126:127], v56 offset:1792
	ds_read_b64 v[118:119], v56 offset:2048
	s_waitcnt lgkmcnt(3)
	v_pk_mul_f32 v[186:187], v[176:177], v[184:185] op_sel:[1,1] op_sel_hi:[0,1]
	v_pk_fma_f32 v[176:177], v[176:177], v[184:185], v[186:187] op_sel_hi:[1,0,1] neg_lo:[0,0,1]
	ds_write_b64 v5, v[176:177] offset:1320
	s_waitcnt lgkmcnt(3)
; #define LAS __attribute__((address_space(3)))
; __device__ __forceinline__ f32x2 cmul(f32x2 a, f32x2 b) { return (f32x2){a.x * b.x - a.y * b.y, a.x * b.y + a.y * b.x}; }
; __device__ __forceinline__ void fft_fwd2(LAS f32x2* B, const LAS f32x2* TW2, int tid) {
;     ...
; #pragma unroll
;     for (int k = 1; k < 16; ++k) B[fpad(base + 32 * k)] = cmul(x[k], TW2[k * 32 + n2]);
; template <int MODE> __device__ __forceinline__ void fft_pair32(LAS f32x2* B, const LAS f32x2* F, int wave, int lane) {
;     ...
;     const int hi = lane >> 5, blk = 32 * wave + (lane & 31); const float sg = hi ? -1.f : 1.f;
;     LAS f32x2* p = B + 33 * blk; f32x2 v[16];
; #pragma unroll
;     for (int j = 0; j < 16; ++j) { const f32x2 d = p[j] + p[j + 16] * sg;
;         const f32x2 w = {hi ? CS[j] : 1.f, hi ? -SN[j] : 0.f}; v[j] = j == 0 ? d : cmul(d, w); }
	v_pk_mul_f32 v[188:189], v[166:167], v[168:169] op_sel:[1,1] op_sel_hi:[0,1]
	v_pk_fma_f32 v[166:167], v[166:167], v[168:169], v[188:189] op_sel_hi:[1,0,1] neg_lo:[0,0,1]
	ds_write_b64 v5, v[166:167] offset:1584
	s_waitcnt lgkmcnt(3)
	v_pk_mul_f32 v[180:181], v[174:175], v[126:127] op_sel:[1,1] op_sel_hi:[0,1]
	v_pk_fma_f32 v[174:175], v[174:175], v[126:127], v[180:181] op_sel_hi:[1,0,1] neg_lo:[0,0,1]
	ds_write_b64 v5, v[174:175] offset:1848
	s_waitcnt lgkmcnt(3)
	v_pk_mul_f32 v[182:183], v[104:105], v[118:119] op_sel:[1,1] op_sel_hi:[0,1]
	v_pk_fma_f32 v[104:105], v[104:105], v[118:119], v[182:183] op_sel_hi:[1,0,1] neg_lo:[0,0,1]
	ds_write_b64 v5, v[104:105] offset:2112
	ds_read_b64 v[110:111], v56 offset:2304
	ds_read_b64 v[102:103], v56 offset:2560
	ds_read_b64 v[186:187], v56 offset:2816
	ds_read_b64 v[188:189], v56 offset:3072
	s_waitcnt lgkmcnt(3)
	v_pk_mul_f32 v[180:181], v[112:113], v[110:111] op_sel:[1,1] op_sel_hi:[0,1]
	v_pk_fma_f32 v[112:113], v[112:113], v[110:111], v[180:181] op_sel_hi:[1,0,1] neg_lo:[0,0,1]
	ds_write_b64 v5, v[112:113] offset:2376
	s_waitcnt lgkmcnt(3)
	v_pk_mul_f32 v[182:183], v[120:121], v[102:103] op_sel:[1,1] op_sel_hi:[0,1]
	v_pk_fma_f32 v[120:121], v[120:121], v[102:103], v[182:183] op_sel_hi:[1,0,1] neg_lo:[0,0,1]
	ds_write_b64 v5, v[120:121] offset:2640
	s_waitcnt lgkmcnt(3)
	v_pk_mul_f32 v[184:185], v[128:129], v[186:187] op_sel:[1,1] op_sel_hi:[0,1]
	v_pk_fma_f32 v[128:129], v[128:129], v[186:187], v[184:185] op_sel_hi:[1,0,1] neg_lo:[0,0,1]
	ds_write_b64 v5, v[128:129] offset:2904
	s_waitcnt lgkmcnt(3)
	v_pk_mul_f32 v[168:169], v[106:107], v[188:189] op_sel:[1,1] op_sel_hi:[0,1]
	v_pk_fma_f32 v[106:107], v[106:107], v[188:189], v[168:169] op_sel_hi:[1,0,1] neg_lo:[0,0,1]
	ds_write_b64 v5, v[106:107] offset:3168
	ds_read_b64 v[126:127], v56 offset:3328
	ds_read_b64 v[118:119], v56 offset:3584
	ds_read_b64 v[180:181], v56 offset:3840
	s_waitcnt lgkmcnt(2)
	v_pk_mul_f32 v[182:183], v[114:115], v[126:127] op_sel:[1,1] op_sel_hi:[0,1]
	v_pk_fma_f32 v[114:115], v[114:115], v[126:127], v[182:183] op_sel_hi:[1,0,1] neg_lo:[0,0,1]
	ds_write_b64 v5, v[114:115] offset:3432
	s_waitcnt lgkmcnt(2)
	v_pk_mul_f32 v[184:185], v[122:123], v[118:119] op_sel:[1,1] op_sel_hi:[0,1]
	v_pk_fma_f32 v[122:123], v[122:123], v[118:119], v[184:185] op_sel_hi:[1,0,1] neg_lo:[0,0,1]
	ds_write_b64 v5, v[122:123] offset:3696
	s_waitcnt lgkmcnt(2)
	v_pk_mul_f32 v[168:169], v[130:131], v[180:181] op_sel:[1,1] op_sel_hi:[0,1]
	v_pk_fma_f32 v[130:131], v[130:131], v[180:181], v[168:169] op_sel_hi:[1,0,1] neg_lo:[0,0,1]
	ds_write_b64 v5, v[130:131] offset:3960
	s_waitcnt lgkmcnt(0)
	ds_read_b64 v[100:101], v156
	ds_read_b64 v[110:111], v156 offset:128
	ds_read_b64 v[108:109], v156 offset:8
	ds_read_b64 v[102:103], v156 offset:136
	ds_read_b64 v[116:117], v156 offset:16
	ds_read_b64 v[186:187], v156 offset:144
	ds_read_b64 v[124:125], v156 offset:24
	ds_read_b64 v[188:189], v156 offset:152
	s_waitcnt lgkmcnt(6)
	v_pk_fma_f32 v[100:101], v[110:111], v[190:191], v[100:101] op_sel_hi:[1,0,1]
	s_waitcnt lgkmcnt(4)
	v_pk_fma_f32 v[108:109], v[102:103], v[190:191], v[108:109] op_sel_hi:[1,0,1]
	v_pk_mul_f32 v[182:183], v[108:109], v[36:37] op_sel:[1,1] op_sel_hi:[0,1]
	v_pk_fma_f32 v[108:109], v[108:109], v[36:37], v[182:183] op_sel_hi:[1,0,1] neg_lo:[0,0,1]
	s_waitcnt lgkmcnt(2)
	v_pk_fma_f32 v[116:117], v[186:187], v[190:191], v[116:117] op_sel_hi:[1,0,1]
	v_pk_mul_f32 v[184:185], v[116:117], v[38:39] op_sel:[1,1] op_sel_hi:[0,1]
	v_pk_fma_f32 v[116:117], v[116:117], v[38:39], v[184:185] op_sel_hi:[1,0,1] neg_lo:[0,0,1]
	s_waitcnt lgkmcnt(0)
	v_pk_fma_f32 v[124:125], v[188:189], v[190:191], v[124:125] op_sel_hi:[1,0,1]
	v_pk_mul_f32 v[168:169], v[124:125], v[40:41] op_sel:[1,1] op_sel_hi:[0,1]
	v_pk_fma_f32 v[124:125], v[124:125], v[40:41], v[168:169] op_sel_hi:[1,0,1] neg_lo:[0,0,1]
	ds_read_b64 v[178:179], v156 offset:32
	ds_read_b64 v[126:127], v156 offset:160
	ds_read_b64 v[176:177], v156 offset:40
	ds_read_b64 v[118:119], v156 offset:168
	ds_read_b64 v[166:167], v156 offset:48
	ds_read_b64 v[180:181], v156 offset:176
	ds_read_b64 v[174:175], v156 offset:56
	ds_read_b64 v[182:183], v156 offset:184
	s_waitcnt lgkmcnt(6)
	v_pk_fma_f32 v[178:179], v[126:127], v[190:191], v[178:179] op_sel_hi:[1,0,1]
	v_pk_mul_f32 v[184:185], v[178:179], v[42:43] op_sel:[1,1] op_sel_hi:[0,1]
	v_pk_fma_f32 v[178:179], v[178:179], v[42:43], v[184:185] op_sel_hi:[1,0,1] neg_lo:[0,0,1]
	s_waitcnt lgkmcnt(4)
	v_pk_fma_f32 v[176:177], v[118:119], v[190:191], v[176:177] op_sel_hi:[1,0,1]
	v_pk_mul_f32 v[168:169], v[176:177], v[44:45] op_sel:[1,1] op_sel_hi:[0,1]
	v_pk_fma_f32 v[176:177], v[176:177], v[44:45], v[168:169] op_sel_hi:[1,0,1] neg_lo:[0,0,1]
	s_waitcnt lgkmcnt(2)
	v_pk_fma_f32 v[166:167], v[180:181], v[190:191], v[166:167] op_sel_hi:[1,0,1]
	v_pk_mul_f32 v[110:111], v[166:167], v[46:47] op_sel:[1,1] op_sel_hi:[0,1]
	v_pk_fma_f32 v[166:167], v[166:167], v[46:47], v[110:111] op_sel_hi:[1,0,1] neg_lo:[0,0,1]
	s_waitcnt lgkmcnt(0)
	v_pk_fma_f32 v[174:175], v[182:183], v[190:191], v[174:175] op_sel_hi:[1,0,1]
	v_pk_mul_f32 v[102:103], v[174:175], v[48:49] op_sel:[1,1] op_sel_hi:[0,1]
	v_pk_fma_f32 v[174:175], v[174:175], v[48:49], v[102:103] op_sel_hi:[1,0,1] neg_lo:[0,0,1]
	ds_read_b64 v[104:105], v156 offset:64
	ds_read_b64 v[186:187], v156 offset:192
	ds_read_b64 v[112:113], v156 offset:72
	ds_read_b64 v[188:189], v156 offset:200
	ds_read_b64 v[120:121], v156 offset:80
	ds_read_b64 v[184:185], v156 offset:208
	ds_read_b64 v[128:129], v156 offset:88
	ds_read_b64 v[168:169], v156 offset:216
	s_waitcnt lgkmcnt(6)
; __device__ __forceinline__ f32x2 cmul(f32x2 a, f32x2 b) { return (f32x2){a.x * b.x - a.y * b.y, a.x * b.y + a.y * b.x}; }
; template <bool INV> __device__ __forceinline__ f32x2 cmul_tw(f32x2 a, f32x2 w) { return INV ? cmulc(a, w) : cmul(a, w); }
; template <bool INV> __device__ __forceinline__ void dft16(f32x2 (&x)[16]) {
;     constexpr float C1 = 0.92387953251128674f, S1 = 0.38268343236508977f, C2 = 0.70710678118654752f;
; #pragma unroll
;     for (int b = 0; b < 4; ++b) dft4<INV>(x[b], x[4 + b], x[8 + b], x[12 + b]);
;     const f32x2 w1 = {C1, -S1}, w2 = {C2, -C2}, w3 = {S1, -C1}, w4 = {0.f, -1.f}, w6 = {-C2, -C2}, w9 = {-C1, S1};
;     x[4 * 1 + 1] = cmul_tw<INV>(x[5], w1); x[4 * 1 + 2] = cmul_tw<INV>(x[6], w2); x[4 * 1 + 3] = cmul_tw<INV>(x[7], w3);
;     x[4 * 2 + 1] = cmul_tw<INV>(x[9], w2); x[4 * 2 + 2] = cmul_tw<INV>(x[10], w4); x[4 * 2 + 3] = cmul_tw<INV>(x[11], w6);
;     x[4 * 3 + 1] = cmul_tw<INV>(x[13], w3); x[4 * 3 + 2] = cmul_tw<INV>(x[14], w6); x[4 * 3 + 3] = cmul_tw<INV>(x[15], w9);
; #pragma unroll
;     for (int c = 0; c < 4; ++c) dft4<INV>(x[4 * c], x[4 * c + 1], x[4 * c + 2], x[4 * c + 3]);
; template <int MODE> __device__ __forceinline__ void fft_pair32(LAS f32x2* B, const LAS f32x2* F, int wave, int lane) {
;     ...
;     for (int j = 0; j < 16; ++j) { const f32x2 d = p[j] + p[j + 16] * sg;
;         const f32x2 w = {hi ? CS[j] : 1.f, hi ? -SN[j] : 0.f}; v[j] = j == 0 ? d : cmul(d, w); }
;     dft16<false>(v);
	v_pk_fma_f32 v[104:105], v[186:187], v[190:191], v[104:105] op_sel_hi:[1,0,1]
	v_pk_mul_f32 v[110:111], v[104:105], v[50:51] op_sel:[1,1] op_sel_hi:[0,1]
	v_pk_fma_f32 v[104:105], v[104:105], v[50:51], v[110:111] op_sel_hi:[1,0,1] neg_lo:[0,0,1]
	s_waitcnt lgkmcnt(4)
	v_pk_fma_f32 v[112:113], v[188:189], v[190:191], v[112:113] op_sel_hi:[1,0,1]
	v_pk_mul_f32 v[102:103], v[112:113], v[52:53] op_sel:[1,1] op_sel_hi:[0,1]
	v_pk_fma_f32 v[112:113], v[112:113], v[52:53], v[102:103] op_sel_hi:[1,0,1] neg_lo:[0,0,1]
	s_waitcnt lgkmcnt(2)
	v_pk_fma_f32 v[120:121], v[184:185], v[190:191], v[120:121] op_sel_hi:[1,0,1]
	v_pk_mul_f32 v[126:127], v[120:121], v[54:55] op_sel:[1,1] op_sel_hi:[0,1]
	v_pk_fma_f32 v[120:121], v[120:121], v[54:55], v[126:127] op_sel_hi:[1,0,1] neg_lo:[0,0,1]
	s_waitcnt lgkmcnt(0)
	v_pk_fma_f32 v[128:129], v[168:169], v[190:191], v[128:129] op_sel_hi:[1,0,1]
	v_pk_mul_f32 v[118:119], v[128:129], v[90:91] op_sel:[1,1] op_sel_hi:[0,1]
	v_pk_fma_f32 v[128:129], v[128:129], v[90:91], v[118:119] op_sel_hi:[1,0,1] neg_lo:[0,0,1]
	ds_read_b64 v[106:107], v156 offset:96
	ds_read_b64 v[180:181], v156 offset:224
	ds_read_b64 v[114:115], v156 offset:104
	ds_read_b64 v[182:183], v156 offset:232
	ds_read_b64 v[122:123], v156 offset:112
	ds_read_b64 v[110:111], v156 offset:240
	ds_read_b64 v[130:131], v156 offset:120
	ds_read_b64 v[102:103], v156 offset:248
	s_waitcnt lgkmcnt(6)
	v_pk_fma_f32 v[106:107], v[180:181], v[190:191], v[106:107] op_sel_hi:[1,0,1]
	v_pk_mul_f32 v[126:127], v[106:107], v[92:93] op_sel:[1,1] op_sel_hi:[0,1]
	v_pk_fma_f32 v[106:107], v[106:107], v[92:93], v[126:127] op_sel_hi:[1,0,1] neg_lo:[0,0,1]
	s_waitcnt lgkmcnt(4)
	v_pk_fma_f32 v[114:115], v[182:183], v[190:191], v[114:115] op_sel_hi:[1,0,1]
	v_pk_mul_f32 v[118:119], v[114:115], v[94:95] op_sel:[1,1] op_sel_hi:[0,1]
	v_pk_fma_f32 v[114:115], v[114:115], v[94:95], v[118:119] op_sel_hi:[1,0,1] neg_lo:[0,0,1]
	s_waitcnt lgkmcnt(2)
	v_pk_fma_f32 v[122:123], v[110:111], v[190:191], v[122:123] op_sel_hi:[1,0,1]
	v_pk_mul_f32 v[186:187], v[122:123], v[96:97] op_sel:[1,1] op_sel_hi:[0,1]
	v_pk_fma_f32 v[122:123], v[122:123], v[96:97], v[186:187] op_sel_hi:[1,0,1] neg_lo:[0,0,1]
	s_waitcnt lgkmcnt(0)
	v_pk_fma_f32 v[130:131], v[102:103], v[190:191], v[130:131] op_sel_hi:[1,0,1]
	v_pk_mul_f32 v[188:189], v[130:131], v[98:99] op_sel:[1,1] op_sel_hi:[0,1]
	v_pk_fma_f32 v[130:131], v[130:131], v[98:99], v[188:189] op_sel_hi:[1,0,1] neg_lo:[0,0,1]
	v_pk_add_f32 v[184:185], v[100:101], v[104:105]
	v_pk_add_f32 v[168:169], v[100:101], v[104:105] neg_lo:[0,1] neg_hi:[0,1]
	v_pk_add_f32 v[126:127], v[178:179], v[106:107]
	v_pk_add_f32 v[118:119], v[178:179], v[106:107] neg_lo:[0,1] neg_hi:[0,1]
	v_pk_add_f32 v[100:101], v[184:185], v[126:127]
	v_pk_add_f32 v[104:105], v[184:185], v[126:127] neg_lo:[0,1] neg_hi:[0,1]
	v_pk_add_f32 v[178:179], v[168:169], v[118:119] op_sel:[0,1] op_sel_hi:[1,0] neg_hi:[0,1]
	v_pk_add_f32 v[106:107], v[168:169], v[118:119] op_sel:[0,1] op_sel_hi:[1,0] neg_lo:[0,1]
	v_pk_add_f32 v[186:187], v[108:109], v[112:113]
	v_pk_add_f32 v[188:189], v[108:109], v[112:113] neg_lo:[0,1] neg_hi:[0,1]
	v_pk_add_f32 v[180:181], v[176:177], v[114:115]
	v_pk_add_f32 v[182:183], v[176:177], v[114:115] neg_lo:[0,1] neg_hi:[0,1]
	v_pk_add_f32 v[108:109], v[186:187], v[180:181]
	v_pk_add_f32 v[112:113], v[186:187], v[180:181] neg_lo:[0,1] neg_hi:[0,1]
	v_pk_add_f32 v[176:177], v[188:189], v[182:183] op_sel:[0,1] op_sel_hi:[1,0] neg_hi:[0,1]
	v_pk_add_f32 v[114:115], v[188:189], v[182:183] op_sel:[0,1] op_sel_hi:[1,0] neg_lo:[0,1]
	v_pk_add_f32 v[110:111], v[116:117], v[120:121]
	v_pk_add_f32 v[102:103], v[116:117], v[120:121] neg_lo:[0,1] neg_hi:[0,1]
	v_pk_add_f32 v[184:185], v[166:167], v[122:123]
	v_pk_add_f32 v[168:169], v[166:167], v[122:123] neg_lo:[0,1] neg_hi:[0,1]
	v_pk_add_f32 v[116:117], v[110:111], v[184:185]
	v_pk_add_f32 v[120:121], v[110:111], v[184:185] neg_lo:[0,1] neg_hi:[0,1]
	v_pk_add_f32 v[166:167], v[102:103], v[168:169] op_sel:[0,1] op_sel_hi:[1,0] neg_hi:[0,1]
	v_pk_add_f32 v[122:123], v[102:103], v[168:169] op_sel:[0,1] op_sel_hi:[1,0] neg_lo:[0,1]
	v_pk_add_f32 v[126:127], v[124:125], v[128:129]
	v_pk_add_f32 v[118:119], v[124:125], v[128:129] neg_lo:[0,1] neg_hi:[0,1]
	v_pk_add_f32 v[186:187], v[174:175], v[130:131]
	v_pk_add_f32 v[188:189], v[174:175], v[130:131] neg_lo:[0,1] neg_hi:[0,1]
	v_pk_add_f32 v[124:125], v[126:127], v[186:187]
	v_pk_add_f32 v[128:129], v[126:127], v[186:187] neg_lo:[0,1] neg_hi:[0,1]
	v_pk_add_f32 v[174:175], v[118:119], v[188:189] op_sel:[0,1] op_sel_hi:[1,0] neg_hi:[0,1]
	v_pk_add_f32 v[130:131], v[118:119], v[188:189] op_sel:[0,1] op_sel_hi:[1,0] neg_lo:[0,1]
	v_pk_mul_f32 v[180:181], v[176:177], s[68:69] op_sel:[1,1] op_sel_hi:[0,1]
	v_pk_fma_f32 v[176:177], v[176:177], s[68:69], v[180:181] op_sel_hi:[1,0,1] neg_lo:[0,0,1]
	v_pk_mul_f32 v[182:183], v[166:167], s[84:85] op_sel:[1,1] op_sel_hi:[0,1]
	v_pk_fma_f32 v[166:167], v[166:167], s[84:85], v[182:183] op_sel_hi:[1,0,1] neg_lo:[0,0,1]
	v_pk_mul_f32 v[110:111], v[174:175], s[88:89] op_sel:[1,1] op_sel_hi:[0,1]
	v_pk_fma_f32 v[174:175], v[174:175], s[88:89], v[110:111] op_sel_hi:[1,0,1] neg_lo:[0,0,1]
	v_pk_mul_f32 v[102:103], v[112:113], s[84:85] op_sel:[1,1] op_sel_hi:[0,1]
	v_pk_fma_f32 v[112:113], v[112:113], s[84:85], v[102:103] op_sel_hi:[1,0,1] neg_lo:[0,0,1]
	v_pk_mul_f32 v[184:185], v[128:129], s[90:91] op_sel:[1,1] op_sel_hi:[0,1]
	v_pk_fma_f32 v[128:129], v[128:129], s[90:91], v[184:185] op_sel_hi:[1,0,1] neg_lo:[0,0,1]
	v_pk_mul_f32 v[168:169], v[114:115], s[88:89] op_sel:[1,1] op_sel_hi:[0,1]
	v_pk_fma_f32 v[114:115], v[114:115], s[88:89], v[168:169] op_sel_hi:[1,0,1] neg_lo:[0,0,1]
; #define LAS __attribute__((address_space(3)))
; __device__ __forceinline__ f32x2 cmul(f32x2 a, f32x2 b) { return (f32x2){a.x * b.x - a.y * b.y, a.x * b.y + a.y * b.x}; }
; template <bool INV> __device__ __forceinline__ f32x2 cmul_tw(f32x2 a, f32x2 w) { return INV ? cmulc(a, w) : cmul(a, w); }
; template <bool INV> __device__ __forceinline__ void dft16(f32x2 (&x)[16]) {
;     ...
;     for (int b = 0; b < 4; ++b) dft4<INV>(x[b], x[4 + b], x[8 + b], x[12 + b]);
;     const f32x2 w1 = {C1, -S1}, w2 = {C2, -C2}, w3 = {S1, -C1}, w4 = {0.f, -1.f}, w6 = {-C2, -C2}, w9 = {-C1, S1};
;     x[4 * 1 + 1] = cmul_tw<INV>(x[5], w1); x[4 * 1 + 2] = cmul_tw<INV>(x[6], w2); x[4 * 1 + 3] = cmul_tw<INV>(x[7], w3);
;     x[4 * 2 + 1] = cmul_tw<INV>(x[9], w2); x[4 * 2 + 2] = cmul_tw<INV>(x[10], w4); x[4 * 2 + 3] = cmul_tw<INV>(x[11], w6);
;     x[4 * 3 + 1] = cmul_tw<INV>(x[13], w3); x[4 * 3 + 2] = cmul_tw<INV>(x[14], w6); x[4 * 3 + 3] = cmul_tw<INV>(x[15], w9);
; #pragma unroll
;     for (int c = 0; c < 4; ++c) dft4<INV>(x[4 * c], x[4 * c + 1], x[4 * c + 2], x[4 * c + 3]);
; template <int MODE> __device__ __forceinline__ void fft_pair32(LAS f32x2* B, const LAS f32x2* F, int wave, int lane) {
;     ...
;     const int k1 = blk >> 4, k2 = blk & 15, kb1 = (16 - k1) & 15, b1 = k1 != 0 ? 1 : 0, kb2 = (16 - k2 - b1) & 15, b2 = (k2 != 0 || b1) ? 1 : 0;
;     const LAS f32x2* fa = F + 33 * blk; const LAS f32x2* fb = F + 33 * (16 * kb1 + kb2);
;     const LAS f32x2* fah = fa + hi; const LAS f32x2* fbh = fb + (1 - b2) - hi;
;     constexpr float SC = 1.0f / (2.0f * (float)FN);
; #pragma unroll
;     for (int k = 0; k < 16; ++k) { const f32x2 A = fah[2 * k]; f32x2 Bm = fbh[31 - 2 * k];
;         if (k == 0) { const f32x2 m0 = b2 ? fb[31] : fa[0]; Bm = hi ? Bm : m0; }
;         const f32x2 H = MODE == 0 ? (f32x2){(A.x + Bm.x) * SC, (A.y - Bm.y) * SC} : (f32x2){(A.y + Bm.y) * SC, (Bm.x - A.x) * SC};
;         v[k] = cmul(v[k], H); }
	v_pk_mul_f32 v[126:127], v[122:123], s[90:91] op_sel:[1,1] op_sel_hi:[0,1]
	v_pk_fma_f32 v[122:123], v[122:123], s[90:91], v[126:127] op_sel_hi:[1,0,1] neg_lo:[0,0,1]
	v_pk_mul_f32 v[118:119], v[130:131], s[98:99] op_sel:[1,1] op_sel_hi:[0,1]
	v_pk_fma_f32 v[130:131], v[130:131], s[98:99], v[118:119] op_sel_hi:[1,0,1] neg_lo:[0,0,1]
	v_pk_add_f32 v[186:187], v[100:101], v[116:117]
	v_pk_add_f32 v[188:189], v[100:101], v[116:117] neg_lo:[0,1] neg_hi:[0,1]
	v_pk_add_f32 v[180:181], v[108:109], v[124:125]
	v_pk_add_f32 v[182:183], v[108:109], v[124:125] neg_lo:[0,1] neg_hi:[0,1]
	v_pk_add_f32 v[100:101], v[186:187], v[180:181]
	v_pk_add_f32 v[116:117], v[186:187], v[180:181] neg_lo:[0,1] neg_hi:[0,1]
	v_pk_add_f32 v[108:109], v[188:189], v[182:183] op_sel:[0,1] op_sel_hi:[1,0] neg_hi:[0,1]
	v_pk_add_f32 v[124:125], v[188:189], v[182:183] op_sel:[0,1] op_sel_hi:[1,0] neg_lo:[0,1]
	v_pk_add_f32 v[110:111], v[178:179], v[166:167]
	v_pk_add_f32 v[102:103], v[178:179], v[166:167] neg_lo:[0,1] neg_hi:[0,1]
	v_pk_add_f32 v[184:185], v[176:177], v[174:175]
	v_pk_add_f32 v[168:169], v[176:177], v[174:175] neg_lo:[0,1] neg_hi:[0,1]
	v_pk_add_f32 v[178:179], v[110:111], v[184:185]
	v_pk_add_f32 v[166:167], v[110:111], v[184:185] neg_lo:[0,1] neg_hi:[0,1]
	v_pk_add_f32 v[176:177], v[102:103], v[168:169] op_sel:[0,1] op_sel_hi:[1,0] neg_hi:[0,1]
	v_pk_add_f32 v[174:175], v[102:103], v[168:169] op_sel:[0,1] op_sel_hi:[1,0] neg_lo:[0,1]
	v_pk_add_f32 v[126:127], v[104:105], v[120:121] op_sel:[0,1] op_sel_hi:[1,0] neg_hi:[0,1]
	v_pk_add_f32 v[118:119], v[104:105], v[120:121] op_sel:[0,1] op_sel_hi:[1,0] neg_lo:[0,1]
	v_pk_add_f32 v[186:187], v[112:113], v[128:129]
	v_pk_add_f32 v[188:189], v[112:113], v[128:129] neg_lo:[0,1] neg_hi:[0,1]
	v_pk_add_f32 v[104:105], v[126:127], v[186:187]
	v_pk_add_f32 v[120:121], v[126:127], v[186:187] neg_lo:[0,1] neg_hi:[0,1]
	v_pk_add_f32 v[112:113], v[118:119], v[188:189] op_sel:[0,1] op_sel_hi:[1,0] neg_hi:[0,1]
	v_pk_add_f32 v[128:129], v[118:119], v[188:189] op_sel:[0,1] op_sel_hi:[1,0] neg_lo:[0,1]
	v_pk_add_f32 v[180:181], v[106:107], v[122:123]
	v_pk_add_f32 v[182:183], v[106:107], v[122:123] neg_lo:[0,1] neg_hi:[0,1]
	v_pk_add_f32 v[110:111], v[114:115], v[130:131]
	v_pk_add_f32 v[102:103], v[114:115], v[130:131] neg_lo:[0,1] neg_hi:[0,1]
	v_pk_add_f32 v[106:107], v[180:181], v[110:111]
	v_pk_add_f32 v[122:123], v[180:181], v[110:111] neg_lo:[0,1] neg_hi:[0,1]
	v_pk_add_f32 v[114:115], v[182:183], v[102:103] op_sel:[0,1] op_sel_hi:[1,0] neg_hi:[0,1]
	v_pk_add_f32 v[130:131], v[182:183], v[102:103] op_sel:[0,1] op_sel_hi:[1,0] neg_lo:[0,1]
	ds_read_b64 v[184:185], v200
	ds_read_b64 v[186:187], v204
	ds_read_b64 v[168:169], v200 offset:16
	ds_read_b64 v[188:189], v202 offset:232
	ds_read_b64 v[126:127], v200 offset:32
	ds_read_b64 v[180:181], v202 offset:216
	ds_read_b64 v[118:119], v200 offset:48
	ds_read_b64 v[182:183], v202 offset:200
	s_waitcnt lgkmcnt(6)
	v_pk_add_f32 v[184:185], v[184:185], v[186:187] neg_hi:[0,1]
	v_pk_mul_f32 v[110:111], v[100:101], v[184:185] op_sel:[1,1] op_sel_hi:[0,1]
	v_pk_fma_f32 v[100:101], v[100:101], v[184:185], v[110:111] op_sel_hi:[1,0,1] neg_lo:[0,0,1]
	s_waitcnt lgkmcnt(4)
	v_pk_add_f32 v[168:169], v[168:169], v[188:189] neg_hi:[0,1]
	v_pk_mul_f32 v[102:103], v[178:179], v[168:169] op_sel:[1,1] op_sel_hi:[0,1]
	v_pk_fma_f32 v[178:179], v[178:179], v[168:169], v[102:103] op_sel_hi:[1,0,1] neg_lo:[0,0,1]
	s_waitcnt lgkmcnt(2)
	v_pk_add_f32 v[126:127], v[126:127], v[180:181] neg_hi:[0,1]
	v_pk_mul_f32 v[110:111], v[104:105], v[126:127] op_sel:[1,1] op_sel_hi:[0,1]
	v_pk_fma_f32 v[104:105], v[104:105], v[126:127], v[110:111] op_sel_hi:[1,0,1] neg_lo:[0,0,1]
	s_waitcnt lgkmcnt(0)
	v_pk_add_f32 v[118:119], v[118:119], v[182:183] neg_hi:[0,1]
	v_pk_mul_f32 v[102:103], v[106:107], v[118:119] op_sel:[1,1] op_sel_hi:[0,1]
	v_pk_fma_f32 v[106:107], v[106:107], v[118:119], v[102:103] op_sel_hi:[1,0,1] neg_lo:[0,0,1]
	ds_read_b64 v[110:111], v200 offset:64
	ds_read_b64 v[126:127], v202 offset:184
	ds_read_b64 v[102:103], v200 offset:80
	ds_read_b64 v[118:119], v202 offset:168
	ds_read_b64 v[184:185], v200 offset:96
	ds_read_b64 v[186:187], v202 offset:152
	ds_read_b64 v[168:169], v200 offset:112
	ds_read_b64 v[188:189], v202 offset:136
	s_waitcnt lgkmcnt(6)
	v_pk_add_f32 v[110:111], v[110:111], v[126:127] neg_hi:[0,1]
	v_pk_mul_f32 v[180:181], v[108:109], v[110:111] op_sel:[1,1] op_sel_hi:[0,1]
	v_pk_fma_f32 v[108:109], v[108:109], v[110:111], v[180:181] op_sel_hi:[1,0,1] neg_lo:[0,0,1]
	s_waitcnt lgkmcnt(4)
	v_pk_add_f32 v[102:103], v[102:103], v[118:119] neg_hi:[0,1]
	v_pk_mul_f32 v[182:183], v[176:177], v[102:103] op_sel:[1,1] op_sel_hi:[0,1]
	v_pk_fma_f32 v[176:177], v[176:177], v[102:103], v[182:183] op_sel_hi:[1,0,1] neg_lo:[0,0,1]
	s_waitcnt lgkmcnt(2)
	v_pk_add_f32 v[184:185], v[184:185], v[186:187] neg_hi:[0,1]
	v_pk_mul_f32 v[180:181], v[112:113], v[184:185] op_sel:[1,1] op_sel_hi:[0,1]
	v_pk_fma_f32 v[112:113], v[112:113], v[184:185], v[180:181] op_sel_hi:[1,0,1] neg_lo:[0,0,1]
	s_waitcnt lgkmcnt(0)
	v_pk_add_f32 v[168:169], v[168:169], v[188:189] neg_hi:[0,1]
	v_pk_mul_f32 v[182:183], v[114:115], v[168:169] op_sel:[1,1] op_sel_hi:[0,1]
	v_pk_fma_f32 v[114:115], v[114:115], v[168:169], v[182:183] op_sel_hi:[1,0,1] neg_lo:[0,0,1]
	ds_read_b64 v[180:181], v200 offset:128
	ds_read_b64 v[184:185], v202 offset:120
	ds_read_b64 v[182:183], v200 offset:144
	ds_read_b64 v[168:169], v202 offset:104
	ds_read_b64 v[110:111], v200 offset:160
	ds_read_b64 v[126:127], v202 offset:88
	ds_read_b64 v[102:103], v200 offset:176
	ds_read_b64 v[118:119], v202 offset:72
	s_waitcnt lgkmcnt(6)
; __device__ __forceinline__ f32x2 cmul(f32x2 a, f32x2 b) { return (f32x2){a.x * b.x - a.y * b.y, a.x * b.y + a.y * b.x}; }
; template <bool INV> __device__ __forceinline__ f32x2 cmul_tw(f32x2 a, f32x2 w) { return INV ? cmulc(a, w) : cmul(a, w); }
; template <bool INV> __device__ __forceinline__ void dft16(f32x2 (&x)[16]) {
;     constexpr float C1 = 0.92387953251128674f, S1 = 0.38268343236508977f, C2 = 0.70710678118654752f;
; #pragma unroll
;     for (int b = 0; b < 4; ++b) dft4<INV>(x[b], x[4 + b], x[8 + b], x[12 + b]);
;     const f32x2 w1 = {C1, -S1}, w2 = {C2, -C2}, w3 = {S1, -C1}, w4 = {0.f, -1.f}, w6 = {-C2, -C2}, w9 = {-C1, S1};
;     x[4 * 1 + 1] = cmul_tw<INV>(x[5], w1); x[4 * 1 + 2] = cmul_tw<INV>(x[6], w2); x[4 * 1 + 3] = cmul_tw<INV>(x[7], w3);
;     x[4 * 2 + 1] = cmul_tw<INV>(x[9], w2); x[4 * 2 + 2] = cmul_tw<INV>(x[10], w4); x[4 * 2 + 3] = cmul_tw<INV>(x[11], w6);
;     x[4 * 3 + 1] = cmul_tw<INV>(x[13], w3); x[4 * 3 + 2] = cmul_tw<INV>(x[14], w6); x[4 * 3 + 3] = cmul_tw<INV>(x[15], w9);
; #pragma unroll
;     for (int c = 0; c < 4; ++c) dft4<INV>(x[4 * c], x[4 * c + 1], x[4 * c + 2], x[4 * c + 3]);
; template <int MODE> __device__ __forceinline__ void fft_pair32(LAS f32x2* B, const LAS f32x2* F, int wave, int lane) {
;     ...
;     for (int k = 0; k < 16; ++k) { const f32x2 A = fah[2 * k]; f32x2 Bm = fbh[31 - 2 * k];
;         if (k == 0) { const f32x2 m0 = b2 ? fb[31] : fa[0]; Bm = hi ? Bm : m0; }
;         const f32x2 H = MODE == 0 ? (f32x2){(A.x + Bm.x) * SC, (A.y - Bm.y) * SC} : (f32x2){(A.y + Bm.y) * SC, (Bm.x - A.x) * SC};
;         v[k] = cmul(v[k], H); }
;     dft16<true>(v);
	v_pk_add_f32 v[180:181], v[180:181], v[184:185] neg_hi:[0,1]
	v_pk_mul_f32 v[186:187], v[116:117], v[180:181] op_sel:[1,1] op_sel_hi:[0,1]
	v_pk_fma_f32 v[116:117], v[116:117], v[180:181], v[186:187] op_sel_hi:[1,0,1] neg_lo:[0,0,1]
	s_waitcnt lgkmcnt(4)
	v_pk_add_f32 v[182:183], v[182:183], v[168:169] neg_hi:[0,1]
	v_pk_mul_f32 v[188:189], v[166:167], v[182:183] op_sel:[1,1] op_sel_hi:[0,1]
	v_pk_fma_f32 v[166:167], v[166:167], v[182:183], v[188:189] op_sel_hi:[1,0,1] neg_lo:[0,0,1]
	s_waitcnt lgkmcnt(2)
	v_pk_add_f32 v[110:111], v[110:111], v[126:127] neg_hi:[0,1]
	v_pk_mul_f32 v[186:187], v[120:121], v[110:111] op_sel:[1,1] op_sel_hi:[0,1]
	v_pk_fma_f32 v[120:121], v[120:121], v[110:111], v[186:187] op_sel_hi:[1,0,1] neg_lo:[0,0,1]
	s_waitcnt lgkmcnt(0)
	v_pk_add_f32 v[102:103], v[102:103], v[118:119] neg_hi:[0,1]
	v_pk_mul_f32 v[188:189], v[122:123], v[102:103] op_sel:[1,1] op_sel_hi:[0,1]
	v_pk_fma_f32 v[122:123], v[122:123], v[102:103], v[188:189] op_sel_hi:[1,0,1] neg_lo:[0,0,1]
	ds_read_b64 v[186:187], v200 offset:192
	ds_read_b64 v[110:111], v202 offset:56
	ds_read_b64 v[188:189], v200 offset:208
	ds_read_b64 v[102:103], v202 offset:40
	ds_read_b64 v[180:181], v200 offset:224
	ds_read_b64 v[184:185], v202 offset:24
	ds_read_b64 v[182:183], v200 offset:240
	ds_read_b64 v[168:169], v202 offset:8
	s_waitcnt lgkmcnt(6)
	v_pk_add_f32 v[186:187], v[186:187], v[110:111] neg_hi:[0,1]
	v_pk_mul_f32 v[126:127], v[124:125], v[186:187] op_sel:[1,1] op_sel_hi:[0,1]
	v_pk_fma_f32 v[124:125], v[124:125], v[186:187], v[126:127] op_sel_hi:[1,0,1] neg_lo:[0,0,1]
	s_waitcnt lgkmcnt(4)
	v_pk_add_f32 v[188:189], v[188:189], v[102:103] neg_hi:[0,1]
	v_pk_mul_f32 v[118:119], v[174:175], v[188:189] op_sel:[1,1] op_sel_hi:[0,1]
	v_pk_fma_f32 v[174:175], v[174:175], v[188:189], v[118:119] op_sel_hi:[1,0,1] neg_lo:[0,0,1]
	s_waitcnt lgkmcnt(2)
	v_pk_add_f32 v[180:181], v[180:181], v[184:185] neg_hi:[0,1]
	v_pk_mul_f32 v[126:127], v[128:129], v[180:181] op_sel:[1,1] op_sel_hi:[0,1]
	v_pk_fma_f32 v[128:129], v[128:129], v[180:181], v[126:127] op_sel_hi:[1,0,1] neg_lo:[0,0,1]
	s_waitcnt lgkmcnt(0)
	v_pk_add_f32 v[182:183], v[182:183], v[168:169] neg_hi:[0,1]
	v_pk_mul_f32 v[118:119], v[130:131], v[182:183] op_sel:[1,1] op_sel_hi:[0,1]
	v_pk_fma_f32 v[130:131], v[130:131], v[182:183], v[118:119] op_sel_hi:[1,0,1] neg_lo:[0,0,1]
	v_pk_add_f32 v[126:127], v[100:101], v[116:117]
	v_pk_add_f32 v[118:119], v[100:101], v[116:117] neg_lo:[0,1] neg_hi:[0,1]
	v_pk_add_f32 v[186:187], v[108:109], v[124:125]
	v_pk_add_f32 v[188:189], v[108:109], v[124:125] neg_lo:[0,1] neg_hi:[0,1]
	v_pk_add_f32 v[100:101], v[126:127], v[186:187]
	v_pk_add_f32 v[116:117], v[126:127], v[186:187] neg_lo:[0,1] neg_hi:[0,1]
	v_pk_add_f32 v[108:109], v[118:119], v[188:189] op_sel:[0,1] op_sel_hi:[1,0] neg_lo:[0,1]
	v_pk_add_f32 v[124:125], v[118:119], v[188:189] op_sel:[0,1] op_sel_hi:[1,0] neg_hi:[0,1]
	v_pk_add_f32 v[180:181], v[178:179], v[166:167]
	v_pk_add_f32 v[182:183], v[178:179], v[166:167] neg_lo:[0,1] neg_hi:[0,1]
	v_pk_add_f32 v[110:111], v[176:177], v[174:175]
	v_pk_add_f32 v[102:103], v[176:177], v[174:175] neg_lo:[0,1] neg_hi:[0,1]
	v_pk_add_f32 v[178:179], v[180:181], v[110:111]
	v_pk_add_f32 v[166:167], v[180:181], v[110:111] neg_lo:[0,1] neg_hi:[0,1]
	v_pk_add_f32 v[176:177], v[182:183], v[102:103] op_sel:[0,1] op_sel_hi:[1,0] neg_lo:[0,1]
	v_pk_add_f32 v[174:175], v[182:183], v[102:103] op_sel:[0,1] op_sel_hi:[1,0] neg_hi:[0,1]
	v_pk_add_f32 v[184:185], v[104:105], v[120:121]
	v_pk_add_f32 v[168:169], v[104:105], v[120:121] neg_lo:[0,1] neg_hi:[0,1]
	v_pk_add_f32 v[126:127], v[112:113], v[128:129]
	v_pk_add_f32 v[118:119], v[112:113], v[128:129] neg_lo:[0,1] neg_hi:[0,1]
	v_pk_add_f32 v[104:105], v[184:185], v[126:127]
	v_pk_add_f32 v[120:121], v[184:185], v[126:127] neg_lo:[0,1] neg_hi:[0,1]
	v_pk_add_f32 v[112:113], v[168:169], v[118:119] op_sel:[0,1] op_sel_hi:[1,0] neg_lo:[0,1]
	v_pk_add_f32 v[128:129], v[168:169], v[118:119] op_sel:[0,1] op_sel_hi:[1,0] neg_hi:[0,1]
	v_pk_add_f32 v[186:187], v[106:107], v[122:123]
	v_pk_add_f32 v[188:189], v[106:107], v[122:123] neg_lo:[0,1] neg_hi:[0,1]
	v_pk_add_f32 v[180:181], v[114:115], v[130:131]
	v_pk_add_f32 v[182:183], v[114:115], v[130:131] neg_lo:[0,1] neg_hi:[0,1]
	v_pk_add_f32 v[106:107], v[186:187], v[180:181]
	v_pk_add_f32 v[122:123], v[186:187], v[180:181] neg_lo:[0,1] neg_hi:[0,1]
	v_pk_add_f32 v[114:115], v[188:189], v[182:183] op_sel:[0,1] op_sel_hi:[1,0] neg_lo:[0,1]
	v_pk_add_f32 v[130:131], v[188:189], v[182:183] op_sel:[0,1] op_sel_hi:[1,0] neg_hi:[0,1]
	v_pk_mul_f32 v[110:111], v[176:177], s[68:69] op_sel:[1,1] op_sel_hi:[0,1]
	v_pk_fma_f32 v[176:177], v[176:177], s[68:69], v[110:111] op_sel_hi:[1,0,1] neg_hi:[0,0,1]
	v_pk_mul_f32 v[102:103], v[112:113], s[84:85] op_sel:[1,1] op_sel_hi:[0,1]
	v_pk_fma_f32 v[112:113], v[112:113], s[84:85], v[102:103] op_sel_hi:[1,0,1] neg_hi:[0,0,1]
	v_pk_mul_f32 v[184:185], v[114:115], s[88:89] op_sel:[1,1] op_sel_hi:[0,1]
	v_pk_fma_f32 v[114:115], v[114:115], s[88:89], v[184:185] op_sel_hi:[1,0,1] neg_hi:[0,0,1]
	v_pk_mul_f32 v[168:169], v[166:167], s[84:85] op_sel:[1,1] op_sel_hi:[0,1]
	v_pk_fma_f32 v[166:167], v[166:167], s[84:85], v[168:169] op_sel_hi:[1,0,1] neg_hi:[0,0,1]
	v_pk_mul_f32 v[126:127], v[122:123], s[90:91] op_sel:[1,1] op_sel_hi:[0,1]
	v_pk_fma_f32 v[122:123], v[122:123], s[90:91], v[126:127] op_sel_hi:[1,0,1] neg_hi:[0,0,1]
	v_pk_mul_f32 v[118:119], v[174:175], s[88:89] op_sel:[1,1] op_sel_hi:[0,1]
	v_pk_fma_f32 v[174:175], v[174:175], s[88:89], v[118:119] op_sel_hi:[1,0,1] neg_hi:[0,0,1]
	v_pk_mul_f32 v[186:187], v[128:129], s[90:91] op_sel:[1,1] op_sel_hi:[0,1]
; __device__ __forceinline__ f32x2 cmulc(f32x2 a, f32x2 b) { return (f32x2){a.x * b.x + a.y * b.y, a.y * b.x - a.x * b.y}; }
; template <bool INV> __device__ __forceinline__ f32x2 cmul_tw(f32x2 a, f32x2 w) { return INV ? cmulc(a, w) : cmul(a, w); }
; template <bool INV> __device__ __forceinline__ void dft16(f32x2 (&x)[16]) {
;     constexpr float C1 = 0.92387953251128674f, S1 = 0.38268343236508977f, C2 = 0.70710678118654752f;
; #pragma unroll
;     for (int b = 0; b < 4; ++b) dft4<INV>(x[b], x[4 + b], x[8 + b], x[12 + b]);
;     const f32x2 w1 = {C1, -S1}, w2 = {C2, -C2}, w3 = {S1, -C1}, w4 = {0.f, -1.f}, w6 = {-C2, -C2}, w9 = {-C1, S1};
;     x[4 * 1 + 1] = cmul_tw<INV>(x[5], w1); x[4 * 1 + 2] = cmul_tw<INV>(x[6], w2); x[4 * 1 + 3] = cmul_tw<INV>(x[7], w3);
;     x[4 * 2 + 1] = cmul_tw<INV>(x[9], w2); x[4 * 2 + 2] = cmul_tw<INV>(x[10], w4); x[4 * 2 + 3] = cmul_tw<INV>(x[11], w6);
;     x[4 * 3 + 1] = cmul_tw<INV>(x[13], w3); x[4 * 3 + 2] = cmul_tw<INV>(x[14], w6); x[4 * 3 + 3] = cmul_tw<INV>(x[15], w9);
; #pragma unroll
;     for (int c = 0; c < 4; ++c) dft4<INV>(x[4 * c], x[4 * c + 1], x[4 * c + 2], x[4 * c + 3]);
; template <int MODE> __device__ __forceinline__ void fft_pair32(LAS f32x2* B, const LAS f32x2* F, int wave, int lane) {
;     ...
; #pragma unroll
;     for (int j = 0; j < 16; ++j) { const f32x2 w = {hi ? CS[j] : 1.f, hi ? -SN[j] : 0.f}; const f32x2 u = j == 0 ? v[j] : cmulc(v[j], w);
;         const auto rx = __builtin_amdgcn_permlane32_swap(__float_as_uint(u.x), __float_as_uint(u.x), false, false);
;         const auto ry = __builtin_amdgcn_permlane32_swap(__float_as_uint(u.y), __float_as_uint(u.y), false, false);
;         const f32x2 a = {__uint_as_float(rx[0]), __uint_as_float(ry[0])}, b = {__uint_as_float(rx[1]), __uint_as_float(ry[1])};
;         p[16 * hi + j] = a + b * sg; }
	v_pk_fma_f32 v[128:129], v[128:129], s[90:91], v[186:187] op_sel_hi:[1,0,1] neg_hi:[0,0,1]
	v_pk_mul_f32 v[188:189], v[130:131], s[98:99] op_sel:[1,1] op_sel_hi:[0,1]
	v_pk_fma_f32 v[130:131], v[130:131], s[98:99], v[188:189] op_sel_hi:[1,0,1] neg_hi:[0,0,1]
	v_pk_add_f32 v[180:181], v[100:101], v[104:105]
	v_pk_add_f32 v[182:183], v[100:101], v[104:105] neg_lo:[0,1] neg_hi:[0,1]
	v_pk_add_f32 v[110:111], v[178:179], v[106:107]
	v_pk_add_f32 v[102:103], v[178:179], v[106:107] neg_lo:[0,1] neg_hi:[0,1]
	v_pk_add_f32 v[100:101], v[180:181], v[110:111]
	v_pk_add_f32 v[104:105], v[180:181], v[110:111] neg_lo:[0,1] neg_hi:[0,1]
	v_pk_add_f32 v[178:179], v[182:183], v[102:103] op_sel:[0,1] op_sel_hi:[1,0] neg_lo:[0,1]
	v_pk_add_f32 v[106:107], v[182:183], v[102:103] op_sel:[0,1] op_sel_hi:[1,0] neg_hi:[0,1]
	v_pk_add_f32 v[184:185], v[108:109], v[112:113]
	v_pk_add_f32 v[168:169], v[108:109], v[112:113] neg_lo:[0,1] neg_hi:[0,1]
	v_pk_add_f32 v[126:127], v[176:177], v[114:115]
	v_pk_add_f32 v[118:119], v[176:177], v[114:115] neg_lo:[0,1] neg_hi:[0,1]
	v_pk_add_f32 v[108:109], v[184:185], v[126:127]
	v_pk_add_f32 v[112:113], v[184:185], v[126:127] neg_lo:[0,1] neg_hi:[0,1]
	v_pk_add_f32 v[176:177], v[168:169], v[118:119] op_sel:[0,1] op_sel_hi:[1,0] neg_lo:[0,1]
	v_pk_add_f32 v[114:115], v[168:169], v[118:119] op_sel:[0,1] op_sel_hi:[1,0] neg_hi:[0,1]
	v_pk_add_f32 v[186:187], v[116:117], v[120:121] op_sel:[0,1] op_sel_hi:[1,0] neg_lo:[0,1]
	v_pk_add_f32 v[188:189], v[116:117], v[120:121] op_sel:[0,1] op_sel_hi:[1,0] neg_hi:[0,1]
	v_pk_add_f32 v[180:181], v[166:167], v[122:123]
	v_pk_add_f32 v[182:183], v[166:167], v[122:123] neg_lo:[0,1] neg_hi:[0,1]
	v_pk_add_f32 v[116:117], v[186:187], v[180:181]
	v_pk_add_f32 v[120:121], v[186:187], v[180:181] neg_lo:[0,1] neg_hi:[0,1]
	v_pk_add_f32 v[166:167], v[188:189], v[182:183] op_sel:[0,1] op_sel_hi:[1,0] neg_lo:[0,1]
	v_pk_add_f32 v[122:123], v[188:189], v[182:183] op_sel:[0,1] op_sel_hi:[1,0] neg_hi:[0,1]
	v_pk_add_f32 v[110:111], v[124:125], v[128:129]
	v_pk_add_f32 v[102:103], v[124:125], v[128:129] neg_lo:[0,1] neg_hi:[0,1]
	v_pk_add_f32 v[184:185], v[174:175], v[130:131]
	v_pk_add_f32 v[168:169], v[174:175], v[130:131] neg_lo:[0,1] neg_hi:[0,1]
	v_pk_add_f32 v[124:125], v[110:111], v[184:185]
	v_pk_add_f32 v[128:129], v[110:111], v[184:185] neg_lo:[0,1] neg_hi:[0,1]
	v_pk_add_f32 v[174:175], v[102:103], v[168:169] op_sel:[0,1] op_sel_hi:[1,0] neg_lo:[0,1]
	v_pk_add_f32 v[130:131], v[102:103], v[168:169] op_sel:[0,1] op_sel_hi:[1,0] neg_hi:[0,1]
	v_mov_b32_e32 v126, v100
	v_mov_b32_e32 v127, v101
	v_pk_mul_f32 v[180:181], v[108:109], v[36:37] op_sel:[1,1] op_sel_hi:[0,1]
	v_pk_fma_f32 v[118:119], v[108:109], v[36:37], v[180:181] op_sel_hi:[1,0,1] neg_hi:[0,0,1]
	v_pk_fma_f32 v[108:109], v[108:109], v[36:37], v[180:181] op_sel_hi:[1,0,1] neg_hi:[0,0,1]
	v_pk_mul_f32 v[182:183], v[116:117], v[38:39] op_sel:[1,1] op_sel_hi:[0,1]
	v_pk_fma_f32 v[186:187], v[116:117], v[38:39], v[182:183] op_sel_hi:[1,0,1] neg_hi:[0,0,1]
	v_pk_fma_f32 v[116:117], v[116:117], v[38:39], v[182:183] op_sel_hi:[1,0,1] neg_hi:[0,0,1]
	v_pk_mul_f32 v[110:111], v[124:125], v[40:41] op_sel:[1,1] op_sel_hi:[0,1]
	v_pk_fma_f32 v[188:189], v[124:125], v[40:41], v[110:111] op_sel_hi:[1,0,1] neg_hi:[0,0,1]
	v_pk_fma_f32 v[124:125], v[124:125], v[40:41], v[110:111] op_sel_hi:[1,0,1] neg_hi:[0,0,1]
	s_nop 1
	v_permlane32_swap_b32_e32 v100, v126
	v_permlane32_swap_b32_e32 v101, v127
	v_permlane32_swap_b32_e32 v108, v118
	v_permlane32_swap_b32_e32 v109, v119
	v_permlane32_swap_b32_e32 v116, v186
	v_permlane32_swap_b32_e32 v117, v187
	v_permlane32_swap_b32_e32 v124, v188
	v_permlane32_swap_b32_e32 v125, v189
	v_pk_fma_f32 v[100:101], v[126:127], v[190:191], v[100:101] op_sel_hi:[1,0,1]
	ds_write_b64 v198, v[100:101]
	v_pk_fma_f32 v[108:109], v[118:119], v[190:191], v[108:109] op_sel_hi:[1,0,1]
	ds_write_b64 v198, v[108:109] offset:8
	v_pk_fma_f32 v[116:117], v[186:187], v[190:191], v[116:117] op_sel_hi:[1,0,1]
	ds_write_b64 v198, v[116:117] offset:16
	v_pk_fma_f32 v[124:125], v[188:189], v[190:191], v[124:125] op_sel_hi:[1,0,1]
	ds_write_b64 v198, v[124:125] offset:24
	v_pk_mul_f32 v[182:183], v[178:179], v[42:43] op_sel:[1,1] op_sel_hi:[0,1]
	v_pk_fma_f32 v[102:103], v[178:179], v[42:43], v[182:183] op_sel_hi:[1,0,1] neg_hi:[0,0,1]
	v_pk_fma_f32 v[178:179], v[178:179], v[42:43], v[182:183] op_sel_hi:[1,0,1] neg_hi:[0,0,1]
	v_pk_mul_f32 v[110:111], v[176:177], v[44:45] op_sel:[1,1] op_sel_hi:[0,1]
	v_pk_fma_f32 v[184:185], v[176:177], v[44:45], v[110:111] op_sel_hi:[1,0,1] neg_hi:[0,0,1]
	v_pk_fma_f32 v[176:177], v[176:177], v[44:45], v[110:111] op_sel_hi:[1,0,1] neg_hi:[0,0,1]
	v_pk_mul_f32 v[126:127], v[166:167], v[46:47] op_sel:[1,1] op_sel_hi:[0,1]
	v_pk_fma_f32 v[168:169], v[166:167], v[46:47], v[126:127] op_sel_hi:[1,0,1] neg_hi:[0,0,1]
	v_pk_fma_f32 v[166:167], v[166:167], v[46:47], v[126:127] op_sel_hi:[1,0,1] neg_hi:[0,0,1]
	v_pk_mul_f32 v[118:119], v[174:175], v[48:49] op_sel:[1,1] op_sel_hi:[0,1]
	v_pk_fma_f32 v[180:181], v[174:175], v[48:49], v[118:119] op_sel_hi:[1,0,1] neg_hi:[0,0,1]
	v_pk_fma_f32 v[174:175], v[174:175], v[48:49], v[118:119] op_sel_hi:[1,0,1] neg_hi:[0,0,1]
	s_nop 1
	v_permlane32_swap_b32_e32 v178, v102
	v_permlane32_swap_b32_e32 v179, v103
	v_permlane32_swap_b32_e32 v176, v184
	v_permlane32_swap_b32_e32 v177, v185
	v_permlane32_swap_b32_e32 v166, v168
	v_permlane32_swap_b32_e32 v167, v169
	v_permlane32_swap_b32_e32 v174, v180
	v_permlane32_swap_b32_e32 v175, v181
	v_pk_fma_f32 v[178:179], v[102:103], v[190:191], v[178:179] op_sel_hi:[1,0,1]
	ds_write_b64 v198, v[178:179] offset:32
; #define LAS __attribute__((address_space(3)))
; __device__ __forceinline__ f32x2 cmulc(f32x2 a, f32x2 b) { return (f32x2){a.x * b.x + a.y * b.y, a.y * b.x - a.x * b.y}; }
; __device__ __forceinline__ void fft_inv2(LAS f32x2* B, const LAS f32x2* TW2, int tid) {
;     asm volatile("" : "+v"(tid));
;     const int b = tid >> 5, n2 = tid & 31, base = 512 * b + n2; f32x2 x[16];
;     x[0] = B[fpad(base)];
; #pragma unroll
;     for (int k = 1; k < 16; ++k) x[k] = cmulc(B[fpad(base + 32 * k)], TW2[k * 32 + n2]);
;     dft16<true>(x);
; template <int MODE> __device__ __forceinline__ void fft_pair32(LAS f32x2* B, const LAS f32x2* F, int wave, int lane) {
;     ...
; #pragma unroll
;     for (int j = 0; j < 16; ++j) { const f32x2 w = {hi ? CS[j] : 1.f, hi ? -SN[j] : 0.f}; const f32x2 u = j == 0 ? v[j] : cmulc(v[j], w);
;         const auto rx = __builtin_amdgcn_permlane32_swap(__float_as_uint(u.x), __float_as_uint(u.x), false, false);
;         const auto ry = __builtin_amdgcn_permlane32_swap(__float_as_uint(u.y), __float_as_uint(u.y), false, false);
;         const f32x2 a = {__uint_as_float(rx[0]), __uint_as_float(ry[0])}, b = {__uint_as_float(rx[1]), __uint_as_float(ry[1])};
;         p[16 * hi + j] = a + b * sg; }
	v_pk_fma_f32 v[176:177], v[184:185], v[190:191], v[176:177] op_sel_hi:[1,0,1]
	ds_write_b64 v198, v[176:177] offset:40
	v_pk_fma_f32 v[166:167], v[168:169], v[190:191], v[166:167] op_sel_hi:[1,0,1]
	ds_write_b64 v198, v[166:167] offset:48
	v_pk_fma_f32 v[174:175], v[180:181], v[190:191], v[174:175] op_sel_hi:[1,0,1]
	ds_write_b64 v198, v[174:175] offset:56
	v_pk_mul_f32 v[126:127], v[104:105], v[50:51] op_sel:[1,1] op_sel_hi:[0,1]
	v_pk_fma_f32 v[186:187], v[104:105], v[50:51], v[126:127] op_sel_hi:[1,0,1] neg_hi:[0,0,1]
	v_pk_fma_f32 v[104:105], v[104:105], v[50:51], v[126:127] op_sel_hi:[1,0,1] neg_hi:[0,0,1]
	v_pk_mul_f32 v[118:119], v[112:113], v[52:53] op_sel:[1,1] op_sel_hi:[0,1]
	v_pk_fma_f32 v[188:189], v[112:113], v[52:53], v[118:119] op_sel_hi:[1,0,1] neg_hi:[0,0,1]
	v_pk_fma_f32 v[112:113], v[112:113], v[52:53], v[118:119] op_sel_hi:[1,0,1] neg_hi:[0,0,1]
	v_pk_mul_f32 v[102:103], v[120:121], v[54:55] op_sel:[1,1] op_sel_hi:[0,1]
	v_pk_fma_f32 v[182:183], v[120:121], v[54:55], v[102:103] op_sel_hi:[1,0,1] neg_hi:[0,0,1]
	v_pk_fma_f32 v[120:121], v[120:121], v[54:55], v[102:103] op_sel_hi:[1,0,1] neg_hi:[0,0,1]
	v_pk_mul_f32 v[184:185], v[128:129], v[90:91] op_sel:[1,1] op_sel_hi:[0,1]
	v_pk_fma_f32 v[110:111], v[128:129], v[90:91], v[184:185] op_sel_hi:[1,0,1] neg_hi:[0,0,1]
	v_pk_fma_f32 v[128:129], v[128:129], v[90:91], v[184:185] op_sel_hi:[1,0,1] neg_hi:[0,0,1]
	s_nop 1
	v_permlane32_swap_b32_e32 v104, v186
	v_permlane32_swap_b32_e32 v105, v187
	v_permlane32_swap_b32_e32 v112, v188
	v_permlane32_swap_b32_e32 v113, v189
	v_permlane32_swap_b32_e32 v120, v182
	v_permlane32_swap_b32_e32 v121, v183
	v_permlane32_swap_b32_e32 v128, v110
	v_permlane32_swap_b32_e32 v129, v111
	v_pk_fma_f32 v[104:105], v[186:187], v[190:191], v[104:105] op_sel_hi:[1,0,1]
	ds_write_b64 v198, v[104:105] offset:64
	v_pk_fma_f32 v[112:113], v[188:189], v[190:191], v[112:113] op_sel_hi:[1,0,1]
	ds_write_b64 v198, v[112:113] offset:72
	v_pk_fma_f32 v[120:121], v[182:183], v[190:191], v[120:121] op_sel_hi:[1,0,1]
	ds_write_b64 v198, v[120:121] offset:80
	v_pk_fma_f32 v[128:129], v[110:111], v[190:191], v[128:129] op_sel_hi:[1,0,1]
	ds_write_b64 v198, v[128:129] offset:88
	v_pk_mul_f32 v[102:103], v[106:107], v[92:93] op_sel:[1,1] op_sel_hi:[0,1]
	v_pk_fma_f32 v[168:169], v[106:107], v[92:93], v[102:103] op_sel_hi:[1,0,1] neg_hi:[0,0,1]
	v_pk_fma_f32 v[106:107], v[106:107], v[92:93], v[102:103] op_sel_hi:[1,0,1] neg_hi:[0,0,1]
	v_pk_mul_f32 v[184:185], v[114:115], v[94:95] op_sel:[1,1] op_sel_hi:[0,1]
	v_pk_fma_f32 v[180:181], v[114:115], v[94:95], v[184:185] op_sel_hi:[1,0,1] neg_hi:[0,0,1]
	v_pk_fma_f32 v[114:115], v[114:115], v[94:95], v[184:185] op_sel_hi:[1,0,1] neg_hi:[0,0,1]
	v_pk_mul_f32 v[186:187], v[122:123], v[96:97] op_sel:[1,1] op_sel_hi:[0,1]
	v_pk_fma_f32 v[126:127], v[122:123], v[96:97], v[186:187] op_sel_hi:[1,0,1] neg_hi:[0,0,1]
	v_pk_fma_f32 v[122:123], v[122:123], v[96:97], v[186:187] op_sel_hi:[1,0,1] neg_hi:[0,0,1]
	v_pk_mul_f32 v[188:189], v[130:131], v[98:99] op_sel:[1,1] op_sel_hi:[0,1]
	v_pk_fma_f32 v[118:119], v[130:131], v[98:99], v[188:189] op_sel_hi:[1,0,1] neg_hi:[0,0,1]
	v_pk_fma_f32 v[130:131], v[130:131], v[98:99], v[188:189] op_sel_hi:[1,0,1] neg_hi:[0,0,1]
	s_nop 1
	v_permlane32_swap_b32_e32 v106, v168
	v_permlane32_swap_b32_e32 v107, v169
	v_permlane32_swap_b32_e32 v114, v180
	v_permlane32_swap_b32_e32 v115, v181
	v_permlane32_swap_b32_e32 v122, v126
	v_permlane32_swap_b32_e32 v123, v127
	v_permlane32_swap_b32_e32 v130, v118
	v_permlane32_swap_b32_e32 v131, v119
	v_pk_fma_f32 v[106:107], v[168:169], v[190:191], v[106:107] op_sel_hi:[1,0,1]
	ds_write_b64 v198, v[106:107] offset:96
	v_pk_fma_f32 v[114:115], v[180:181], v[190:191], v[114:115] op_sel_hi:[1,0,1]
	ds_write_b64 v198, v[114:115] offset:104
	v_pk_fma_f32 v[122:123], v[126:127], v[190:191], v[122:123] op_sel_hi:[1,0,1]
	ds_write_b64 v198, v[122:123] offset:112
	v_pk_fma_f32 v[130:131], v[118:119], v[190:191], v[130:131] op_sel_hi:[1,0,1]
	ds_write_b64 v198, v[130:131] offset:120
	s_waitcnt lgkmcnt(0)
	ds_read_b64 v[100:101], v5
	ds_read_b64 v[108:109], v5 offset:264
	ds_read_b64 v[182:183], v56 offset:256
	ds_read_b64 v[116:117], v5 offset:528
	ds_read_b64 v[110:111], v56 offset:512
	ds_read_b64 v[124:125], v5 offset:792
	ds_read_b64 v[102:103], v56 offset:768
	ds_read_b64 v[178:179], v5 offset:1056
	ds_read_b64 v[184:185], v56 offset:1024
	ds_read_b64 v[176:177], v5 offset:1320
	ds_read_b64 v[186:187], v56 offset:1280
	s_waitcnt lgkmcnt(8)
	v_pk_mul_f32 v[188:189], v[108:109], v[182:183] op_sel:[1,1] op_sel_hi:[0,1]
	v_pk_fma_f32 v[108:109], v[108:109], v[182:183], v[188:189] op_sel_hi:[1,0,1] neg_hi:[0,0,1]
	s_waitcnt lgkmcnt(6)
	v_pk_mul_f32 v[168:169], v[116:117], v[110:111] op_sel:[1,1] op_sel_hi:[0,1]
	v_pk_fma_f32 v[116:117], v[116:117], v[110:111], v[168:169] op_sel_hi:[1,0,1] neg_hi:[0,0,1]
	s_waitcnt lgkmcnt(4)
	v_pk_mul_f32 v[180:181], v[124:125], v[102:103] op_sel:[1,1] op_sel_hi:[0,1]
	v_pk_fma_f32 v[124:125], v[124:125], v[102:103], v[180:181] op_sel_hi:[1,0,1] neg_hi:[0,0,1]
	s_waitcnt lgkmcnt(2)
	v_pk_mul_f32 v[126:127], v[178:179], v[184:185] op_sel:[1,1] op_sel_hi:[0,1]
	v_pk_fma_f32 v[178:179], v[178:179], v[184:185], v[126:127] op_sel_hi:[1,0,1] neg_hi:[0,0,1]
	s_waitcnt lgkmcnt(0)
	v_pk_mul_f32 v[118:119], v[176:177], v[186:187] op_sel:[1,1] op_sel_hi:[0,1]
	v_pk_fma_f32 v[176:177], v[176:177], v[186:187], v[118:119] op_sel_hi:[1,0,1] neg_hi:[0,0,1]
	ds_read_b64 v[166:167], v5 offset:1584
	ds_read_b64 v[188:189], v56 offset:1536
	ds_read_b64 v[174:175], v5 offset:1848
	ds_read_b64 v[168:169], v56 offset:1792
	ds_read_b64 v[104:105], v5 offset:2112
	ds_read_b64 v[180:181], v56 offset:2048
	ds_read_b64 v[112:113], v5 offset:2376
	ds_read_b64 v[126:127], v56 offset:2304
	ds_read_b64 v[120:121], v5 offset:2640
	ds_read_b64 v[118:119], v56 offset:2560
	s_waitcnt lgkmcnt(8)
; __device__ __forceinline__ f32x2 cmulc(f32x2 a, f32x2 b) { return (f32x2){a.x * b.x + a.y * b.y, a.y * b.x - a.x * b.y}; }
; template <bool INV> __device__ __forceinline__ f32x2 cmul_tw(f32x2 a, f32x2 w) { return INV ? cmulc(a, w) : cmul(a, w); }
; template <bool INV> __device__ __forceinline__ void dft16(f32x2 (&x)[16]) {
;     constexpr float C1 = 0.92387953251128674f, S1 = 0.38268343236508977f, C2 = 0.70710678118654752f;
; #pragma unroll
;     for (int b = 0; b < 4; ++b) dft4<INV>(x[b], x[4 + b], x[8 + b], x[12 + b]);
;     const f32x2 w1 = {C1, -S1}, w2 = {C2, -C2}, w3 = {S1, -C1}, w4 = {0.f, -1.f}, w6 = {-C2, -C2}, w9 = {-C1, S1};
;     x[4 * 1 + 1] = cmul_tw<INV>(x[5], w1); x[4 * 1 + 2] = cmul_tw<INV>(x[6], w2); x[4 * 1 + 3] = cmul_tw<INV>(x[7], w3);
;     x[4 * 2 + 1] = cmul_tw<INV>(x[9], w2); x[4 * 2 + 2] = cmul_tw<INV>(x[10], w4); x[4 * 2 + 3] = cmul_tw<INV>(x[11], w6);
;     x[4 * 3 + 1] = cmul_tw<INV>(x[13], w3); x[4 * 3 + 2] = cmul_tw<INV>(x[14], w6); x[4 * 3 + 3] = cmul_tw<INV>(x[15], w9);
; #pragma unroll
;     for (int c = 0; c < 4; ++c) dft4<INV>(x[4 * c], x[4 * c + 1], x[4 * c + 2], x[4 * c + 3]);
; __device__ __forceinline__ void fft_inv2(LAS f32x2* B, const LAS f32x2* TW2, int tid) {
;     ...
;     x[0] = B[fpad(base)];
; #pragma unroll
;     for (int k = 1; k < 16; ++k) x[k] = cmulc(B[fpad(base + 32 * k)], TW2[k * 32 + n2]);
;     dft16<true>(x);
	v_pk_mul_f32 v[182:183], v[166:167], v[188:189] op_sel:[1,1] op_sel_hi:[0,1]
	v_pk_fma_f32 v[166:167], v[166:167], v[188:189], v[182:183] op_sel_hi:[1,0,1] neg_hi:[0,0,1]
	s_waitcnt lgkmcnt(6)
	v_pk_mul_f32 v[110:111], v[174:175], v[168:169] op_sel:[1,1] op_sel_hi:[0,1]
	v_pk_fma_f32 v[174:175], v[174:175], v[168:169], v[110:111] op_sel_hi:[1,0,1] neg_hi:[0,0,1]
	s_waitcnt lgkmcnt(4)
	v_pk_mul_f32 v[102:103], v[104:105], v[180:181] op_sel:[1,1] op_sel_hi:[0,1]
	v_pk_fma_f32 v[104:105], v[104:105], v[180:181], v[102:103] op_sel_hi:[1,0,1] neg_hi:[0,0,1]
	s_waitcnt lgkmcnt(2)
	v_pk_mul_f32 v[184:185], v[112:113], v[126:127] op_sel:[1,1] op_sel_hi:[0,1]
	v_pk_fma_f32 v[112:113], v[112:113], v[126:127], v[184:185] op_sel_hi:[1,0,1] neg_hi:[0,0,1]
	s_waitcnt lgkmcnt(0)
	v_pk_mul_f32 v[186:187], v[120:121], v[118:119] op_sel:[1,1] op_sel_hi:[0,1]
	v_pk_fma_f32 v[120:121], v[120:121], v[118:119], v[186:187] op_sel_hi:[1,0,1] neg_hi:[0,0,1]
	ds_read_b64 v[128:129], v5 offset:2904
	ds_read_b64 v[182:183], v56 offset:2816
	ds_read_b64 v[106:107], v5 offset:3168
	ds_read_b64 v[110:111], v56 offset:3072
	ds_read_b64 v[114:115], v5 offset:3432
	ds_read_b64 v[102:103], v56 offset:3328
	ds_read_b64 v[122:123], v5 offset:3696
	ds_read_b64 v[184:185], v56 offset:3584
	ds_read_b64 v[130:131], v5 offset:3960
	ds_read_b64 v[186:187], v56 offset:3840
	s_waitcnt lgkmcnt(8)
	v_pk_mul_f32 v[188:189], v[128:129], v[182:183] op_sel:[1,1] op_sel_hi:[0,1]
	v_pk_fma_f32 v[128:129], v[128:129], v[182:183], v[188:189] op_sel_hi:[1,0,1] neg_hi:[0,0,1]
	s_waitcnt lgkmcnt(6)
	v_pk_mul_f32 v[168:169], v[106:107], v[110:111] op_sel:[1,1] op_sel_hi:[0,1]
	v_pk_fma_f32 v[106:107], v[106:107], v[110:111], v[168:169] op_sel_hi:[1,0,1] neg_hi:[0,0,1]
	s_waitcnt lgkmcnt(4)
	v_pk_mul_f32 v[180:181], v[114:115], v[102:103] op_sel:[1,1] op_sel_hi:[0,1]
	v_pk_fma_f32 v[114:115], v[114:115], v[102:103], v[180:181] op_sel_hi:[1,0,1] neg_hi:[0,0,1]
	s_waitcnt lgkmcnt(2)
	v_pk_mul_f32 v[126:127], v[122:123], v[184:185] op_sel:[1,1] op_sel_hi:[0,1]
	v_pk_fma_f32 v[122:123], v[122:123], v[184:185], v[126:127] op_sel_hi:[1,0,1] neg_hi:[0,0,1]
	s_waitcnt lgkmcnt(0)
	v_pk_mul_f32 v[118:119], v[130:131], v[186:187] op_sel:[1,1] op_sel_hi:[0,1]
	v_pk_fma_f32 v[130:131], v[130:131], v[186:187], v[118:119] op_sel_hi:[1,0,1] neg_hi:[0,0,1]
	v_pk_add_f32 v[188:189], v[100:101], v[104:105]
	v_pk_add_f32 v[168:169], v[100:101], v[104:105] neg_lo:[0,1] neg_hi:[0,1]
	v_pk_add_f32 v[180:181], v[178:179], v[106:107]
	v_pk_add_f32 v[126:127], v[178:179], v[106:107] neg_lo:[0,1] neg_hi:[0,1]
	v_pk_add_f32 v[100:101], v[188:189], v[180:181]
	v_pk_add_f32 v[104:105], v[188:189], v[180:181] neg_lo:[0,1] neg_hi:[0,1]
	v_pk_add_f32 v[178:179], v[168:169], v[126:127] op_sel:[0,1] op_sel_hi:[1,0] neg_lo:[0,1]
	v_pk_add_f32 v[106:107], v[168:169], v[126:127] op_sel:[0,1] op_sel_hi:[1,0] neg_hi:[0,1]
	v_pk_add_f32 v[118:119], v[108:109], v[112:113]
	v_pk_add_f32 v[182:183], v[108:109], v[112:113] neg_lo:[0,1] neg_hi:[0,1]
	v_pk_add_f32 v[110:111], v[176:177], v[114:115]
	v_pk_add_f32 v[102:103], v[176:177], v[114:115] neg_lo:[0,1] neg_hi:[0,1]
	v_pk_add_f32 v[108:109], v[118:119], v[110:111]
	v_pk_add_f32 v[112:113], v[118:119], v[110:111] neg_lo:[0,1] neg_hi:[0,1]
	v_pk_add_f32 v[176:177], v[182:183], v[102:103] op_sel:[0,1] op_sel_hi:[1,0] neg_lo:[0,1]
	v_pk_add_f32 v[114:115], v[182:183], v[102:103] op_sel:[0,1] op_sel_hi:[1,0] neg_hi:[0,1]
	v_pk_add_f32 v[184:185], v[116:117], v[120:121]
	v_pk_add_f32 v[186:187], v[116:117], v[120:121] neg_lo:[0,1] neg_hi:[0,1]
	v_pk_add_f32 v[188:189], v[166:167], v[122:123]
	v_pk_add_f32 v[168:169], v[166:167], v[122:123] neg_lo:[0,1] neg_hi:[0,1]
	v_pk_add_f32 v[116:117], v[184:185], v[188:189]
	v_pk_add_f32 v[120:121], v[184:185], v[188:189] neg_lo:[0,1] neg_hi:[0,1]
	v_pk_add_f32 v[166:167], v[186:187], v[168:169] op_sel:[0,1] op_sel_hi:[1,0] neg_lo:[0,1]
	v_pk_add_f32 v[122:123], v[186:187], v[168:169] op_sel:[0,1] op_sel_hi:[1,0] neg_hi:[0,1]
	v_pk_add_f32 v[180:181], v[124:125], v[128:129]
	v_pk_add_f32 v[126:127], v[124:125], v[128:129] neg_lo:[0,1] neg_hi:[0,1]
	v_pk_add_f32 v[118:119], v[174:175], v[130:131]
	v_pk_add_f32 v[182:183], v[174:175], v[130:131] neg_lo:[0,1] neg_hi:[0,1]
	v_pk_add_f32 v[124:125], v[180:181], v[118:119]
	v_pk_add_f32 v[128:129], v[180:181], v[118:119] neg_lo:[0,1] neg_hi:[0,1]
	v_pk_add_f32 v[174:175], v[126:127], v[182:183] op_sel:[0,1] op_sel_hi:[1,0] neg_lo:[0,1]
	v_pk_add_f32 v[130:131], v[126:127], v[182:183] op_sel:[0,1] op_sel_hi:[1,0] neg_hi:[0,1]
	v_pk_mul_f32 v[110:111], v[176:177], s[68:69] op_sel:[1,1] op_sel_hi:[0,1]
	v_pk_fma_f32 v[176:177], v[176:177], s[68:69], v[110:111] op_sel_hi:[1,0,1] neg_hi:[0,0,1]
	v_pk_mul_f32 v[102:103], v[166:167], s[84:85] op_sel:[1,1] op_sel_hi:[0,1]
	v_pk_fma_f32 v[166:167], v[166:167], s[84:85], v[102:103] op_sel_hi:[1,0,1] neg_hi:[0,0,1]
	v_pk_mul_f32 v[184:185], v[174:175], s[88:89] op_sel:[1,1] op_sel_hi:[0,1]
	v_pk_fma_f32 v[174:175], v[174:175], s[88:89], v[184:185] op_sel_hi:[1,0,1] neg_hi:[0,0,1]
	v_pk_mul_f32 v[186:187], v[112:113], s[84:85] op_sel:[1,1] op_sel_hi:[0,1]
	v_pk_fma_f32 v[112:113], v[112:113], s[84:85], v[186:187] op_sel_hi:[1,0,1] neg_hi:[0,0,1]
	v_pk_mul_f32 v[188:189], v[128:129], s[90:91] op_sel:[1,1] op_sel_hi:[0,1]
	v_pk_fma_f32 v[128:129], v[128:129], s[90:91], v[188:189] op_sel_hi:[1,0,1] neg_hi:[0,0,1]
	v_pk_mul_f32 v[168:169], v[114:115], s[88:89] op_sel:[1,1] op_sel_hi:[0,1]
	v_pk_fma_f32 v[114:115], v[114:115], s[88:89], v[168:169] op_sel_hi:[1,0,1] neg_hi:[0,0,1]
	v_pk_mul_f32 v[180:181], v[122:123], s[90:91] op_sel:[1,1] op_sel_hi:[0,1]
; #define LAS __attribute__((address_space(3)))
; __device__ __forceinline__ f32x2 cmulc(f32x2 a, f32x2 b) { return (f32x2){a.x * b.x + a.y * b.y, a.y * b.x - a.x * b.y}; }
; __device__ __forceinline__ void fft_inv2(LAS f32x2* B, const LAS f32x2* TW2, int tid) {
;     ...
; #pragma unroll
;     for (int r = 0; r < 16; ++r) B[fpad(base + 32 * r)] = x[r];
; }
; __device__ __forceinline__ void fft_inv1(f32x2 (&x)[16], const LAS f32x2* B, int n2, const f32x2 (&w)[16]) {
;     asm volatile("" : "+v"(n2));
;     x[0] = B[fpad(n2)];
; #pragma unroll
;     for (int k = 1; k < 16; ++k) x[k] = cmulc(B[fpad(512 * k + n2)], w[k]);
;     dft16_inv_lo(x);
	v_pk_fma_f32 v[122:123], v[122:123], s[90:91], v[180:181] op_sel_hi:[1,0,1] neg_hi:[0,0,1]
	v_pk_mul_f32 v[126:127], v[130:131], s[98:99] op_sel:[1,1] op_sel_hi:[0,1]
	v_pk_fma_f32 v[130:131], v[130:131], s[98:99], v[126:127] op_sel_hi:[1,0,1] neg_hi:[0,0,1]
	v_pk_add_f32 v[118:119], v[100:101], v[116:117]
	v_pk_add_f32 v[182:183], v[100:101], v[116:117] neg_lo:[0,1] neg_hi:[0,1]
	v_pk_add_f32 v[110:111], v[108:109], v[124:125]
	v_pk_add_f32 v[102:103], v[108:109], v[124:125] neg_lo:[0,1] neg_hi:[0,1]
	v_pk_add_f32 v[100:101], v[118:119], v[110:111]
	v_pk_add_f32 v[116:117], v[118:119], v[110:111] neg_lo:[0,1] neg_hi:[0,1]
	v_pk_add_f32 v[108:109], v[182:183], v[102:103] op_sel:[0,1] op_sel_hi:[1,0] neg_lo:[0,1]
	v_pk_add_f32 v[124:125], v[182:183], v[102:103] op_sel:[0,1] op_sel_hi:[1,0] neg_hi:[0,1]
	v_pk_add_f32 v[184:185], v[178:179], v[166:167]
	v_pk_add_f32 v[186:187], v[178:179], v[166:167] neg_lo:[0,1] neg_hi:[0,1]
	v_pk_add_f32 v[188:189], v[176:177], v[174:175]
	v_pk_add_f32 v[168:169], v[176:177], v[174:175] neg_lo:[0,1] neg_hi:[0,1]
	v_pk_add_f32 v[178:179], v[184:185], v[188:189]
	v_pk_add_f32 v[166:167], v[184:185], v[188:189] neg_lo:[0,1] neg_hi:[0,1]
	v_pk_add_f32 v[176:177], v[186:187], v[168:169] op_sel:[0,1] op_sel_hi:[1,0] neg_lo:[0,1]
	v_pk_add_f32 v[174:175], v[186:187], v[168:169] op_sel:[0,1] op_sel_hi:[1,0] neg_hi:[0,1]
	v_pk_add_f32 v[180:181], v[104:105], v[120:121] op_sel:[0,1] op_sel_hi:[1,0] neg_lo:[0,1]
	v_pk_add_f32 v[126:127], v[104:105], v[120:121] op_sel:[0,1] op_sel_hi:[1,0] neg_hi:[0,1]
	v_pk_add_f32 v[118:119], v[112:113], v[128:129]
	v_pk_add_f32 v[182:183], v[112:113], v[128:129] neg_lo:[0,1] neg_hi:[0,1]
	v_pk_add_f32 v[104:105], v[180:181], v[118:119]
	v_pk_add_f32 v[120:121], v[180:181], v[118:119] neg_lo:[0,1] neg_hi:[0,1]
	v_pk_add_f32 v[112:113], v[126:127], v[182:183] op_sel:[0,1] op_sel_hi:[1,0] neg_lo:[0,1]
	v_pk_add_f32 v[128:129], v[126:127], v[182:183] op_sel:[0,1] op_sel_hi:[1,0] neg_hi:[0,1]
	v_pk_add_f32 v[110:111], v[106:107], v[122:123]
	v_pk_add_f32 v[102:103], v[106:107], v[122:123] neg_lo:[0,1] neg_hi:[0,1]
	v_pk_add_f32 v[184:185], v[114:115], v[130:131]
	v_pk_add_f32 v[186:187], v[114:115], v[130:131] neg_lo:[0,1] neg_hi:[0,1]
	v_pk_add_f32 v[106:107], v[110:111], v[184:185]
	v_pk_add_f32 v[122:123], v[110:111], v[184:185] neg_lo:[0,1] neg_hi:[0,1]
	v_pk_add_f32 v[114:115], v[102:103], v[186:187] op_sel:[0,1] op_sel_hi:[1,0] neg_lo:[0,1]
	v_pk_add_f32 v[130:131], v[102:103], v[186:187] op_sel:[0,1] op_sel_hi:[1,0] neg_hi:[0,1]
	ds_write_b64 v5, v[100:101]
	ds_write_b64 v5, v[178:179] offset:264
	ds_write_b64 v5, v[104:105] offset:528
	ds_write_b64 v5, v[106:107] offset:792
	ds_write_b64 v5, v[108:109] offset:1056
	ds_write_b64 v5, v[176:177] offset:1320
	ds_write_b64 v5, v[112:113] offset:1584
	ds_write_b64 v5, v[114:115] offset:1848
	ds_write_b64 v5, v[116:117] offset:2112
	ds_write_b64 v5, v[166:167] offset:2376
	ds_write_b64 v5, v[120:121] offset:2640
	ds_write_b64 v5, v[122:123] offset:2904
	ds_write_b64 v5, v[124:125] offset:3168
	ds_write_b64 v5, v[174:175] offset:3432
	ds_write_b64 v5, v[128:129] offset:3696
	ds_write_b64 v5, v[130:131] offset:3960
	s_waitcnt lgkmcnt(0)
	s_barrier
	s_cbranch_vccz .Lhfft_st6
	s_sleep 4
.Lhfft_st6:
	ds_read_b64 v[100:101], v3
	ds_read_b64 v[108:109], v3 offset:16896
	ds_read_b64 v[116:117], v3 offset:33792
	ds_read_b64 v[124:125], v3 offset:50688
	ds_read_b64 v[178:179], v3 offset:4224
	ds_read_b64 v[176:177], v3 offset:21120
	ds_read_b64 v[166:167], v3 offset:38016
	ds_read_b64 v[174:175], v3 offset:54912
	ds_read_b64 v[104:105], v3 offset:8448
	ds_read_b64 v[112:113], v3 offset:25344
	ds_read_b64 v[120:121], v3 offset:42240
	ds_read_b64 v[128:129], v3 offset:59136
	ds_read_b64 v[106:107], v3 offset:12672
	ds_read_b64 v[114:115], v3 offset:29568
	ds_read_b64 v[122:123], v3 offset:46464
	ds_read_b64 v[130:131], v3 offset:63360
	s_waitcnt lgkmcnt(14)
	v_pk_mul_f32 v[188:189], v[108:109], v[12:13] op_sel:[1,1] op_sel_hi:[0,1]
	v_pk_fma_f32 v[108:109], v[108:109], v[12:13], v[188:189] op_sel_hi:[1,0,1] neg_hi:[0,0,1]
	s_waitcnt lgkmcnt(13)
	v_pk_mul_f32 v[168:169], v[116:117], v[20:21] op_sel:[1,1] op_sel_hi:[0,1]
	v_pk_fma_f32 v[116:117], v[116:117], v[20:21], v[168:169] op_sel_hi:[1,0,1] neg_hi:[0,0,1]
	s_waitcnt lgkmcnt(12)
	v_pk_mul_f32 v[180:181], v[124:125], v[28:29] op_sel:[1,1] op_sel_hi:[0,1]
	v_pk_fma_f32 v[124:125], v[124:125], v[28:29], v[180:181] op_sel_hi:[1,0,1] neg_hi:[0,0,1]
	s_waitcnt lgkmcnt(11)
	v_pk_mul_f32 v[126:127], v[178:179], v[6:7] op_sel:[1,1] op_sel_hi:[0,1]
	v_pk_fma_f32 v[178:179], v[178:179], v[6:7], v[126:127] op_sel_hi:[1,0,1] neg_hi:[0,0,1]
	s_waitcnt lgkmcnt(10)
	v_pk_mul_f32 v[118:119], v[176:177], v[14:15] op_sel:[1,1] op_sel_hi:[0,1]
	v_pk_fma_f32 v[176:177], v[176:177], v[14:15], v[118:119] op_sel_hi:[1,0,1] neg_hi:[0,0,1]
	s_waitcnt lgkmcnt(9)
	v_pk_mul_f32 v[182:183], v[166:167], v[22:23] op_sel:[1,1] op_sel_hi:[0,1]
	v_pk_fma_f32 v[166:167], v[166:167], v[22:23], v[182:183] op_sel_hi:[1,0,1] neg_hi:[0,0,1]
	s_waitcnt lgkmcnt(8)
	v_pk_mul_f32 v[110:111], v[174:175], v[30:31] op_sel:[1,1] op_sel_hi:[0,1]
	v_pk_fma_f32 v[174:175], v[174:175], v[30:31], v[110:111] op_sel_hi:[1,0,1] neg_hi:[0,0,1]
	s_waitcnt lgkmcnt(7)
	v_pk_mul_f32 v[102:103], v[104:105], v[8:9] op_sel:[1,1] op_sel_hi:[0,1]
	v_pk_fma_f32 v[104:105], v[104:105], v[8:9], v[102:103] op_sel_hi:[1,0,1] neg_hi:[0,0,1]
	s_waitcnt lgkmcnt(6)
	v_pk_mul_f32 v[184:185], v[112:113], v[16:17] op_sel:[1,1] op_sel_hi:[0,1]
	v_pk_fma_f32 v[112:113], v[112:113], v[16:17], v[184:185] op_sel_hi:[1,0,1] neg_hi:[0,0,1]
	s_waitcnt lgkmcnt(5)
; __device__ __forceinline__ f32x2 cmulc(f32x2 a, f32x2 b) { return (f32x2){a.x * b.x + a.y * b.y, a.y * b.x - a.x * b.y}; }
; __device__ __forceinline__ void dft16_inv_lo(f32x2 (&x)[16]) {
;     constexpr float C1 = 0.92387953251128674f, S1 = 0.38268343236508977f, C2 = 0.70710678118654752f;
; #pragma unroll
;     for (int b = 0; b < 4; ++b) dft4<true>(x[b], x[4 + b], x[8 + b], x[12 + b]);
;     const f32x2 w1 = {C1, -S1}, w2 = {C2, -C2}, w3 = {S1, -C1}, w4 = {0.f, -1.f}, w6 = {-C2, -C2}, w9 = {-C1, S1};
;     x[5] = cmulc(x[5], w1); x[6] = cmulc(x[6], w2); x[7] = cmulc(x[7], w3);
;     x[9] = cmulc(x[9], w2); x[10] = cmulc(x[10], w4); x[11] = cmulc(x[11], w6);
;     x[13] = cmulc(x[13], w3); x[14] = cmulc(x[14], w6); x[15] = cmulc(x[15], w9);
;     f32x2 y[8];
; #pragma unroll
;     for (int c = 0; c < 4; ++c) { const f32x2 t0 = x[4 * c] + x[4 * c + 2], t1 = x[4 * c] - x[4 * c + 2], t2 = x[4 * c + 1] + x[4 * c + 3], t3 = x[4 * c + 1] - x[4 * c + 3];
;         y[c] = t0 + t2; y[4 + c] = t1 + (f32x2){-t3.y, t3.x}; }
; #pragma unroll
;     for (int k = 0; k < 8; ++k) x[k] = y[k];
; __device__ __forceinline__ void hyena_fft(LAS unsigned char* lds, int layer, int G, const int wave_s) {
;     ...
;             { const float fb0 = fbias[c];
	v_pk_mul_f32 v[186:187], v[120:121], v[24:25] op_sel:[1,1] op_sel_hi:[0,1]
	v_pk_fma_f32 v[120:121], v[120:121], v[24:25], v[186:187] op_sel_hi:[1,0,1] neg_hi:[0,0,1]
	s_waitcnt lgkmcnt(4)
	v_pk_mul_f32 v[188:189], v[128:129], v[32:33] op_sel:[1,1] op_sel_hi:[0,1]
	v_pk_fma_f32 v[128:129], v[128:129], v[32:33], v[188:189] op_sel_hi:[1,0,1] neg_hi:[0,0,1]
	s_waitcnt lgkmcnt(3)
	v_pk_mul_f32 v[168:169], v[106:107], v[10:11] op_sel:[1,1] op_sel_hi:[0,1]
	v_pk_fma_f32 v[106:107], v[106:107], v[10:11], v[168:169] op_sel_hi:[1,0,1] neg_hi:[0,0,1]
	s_waitcnt lgkmcnt(2)
	v_pk_mul_f32 v[180:181], v[114:115], v[18:19] op_sel:[1,1] op_sel_hi:[0,1]
	v_pk_fma_f32 v[114:115], v[114:115], v[18:19], v[180:181] op_sel_hi:[1,0,1] neg_hi:[0,0,1]
	s_waitcnt lgkmcnt(1)
	v_pk_mul_f32 v[126:127], v[122:123], v[26:27] op_sel:[1,1] op_sel_hi:[0,1]
	v_pk_fma_f32 v[122:123], v[122:123], v[26:27], v[126:127] op_sel_hi:[1,0,1] neg_hi:[0,0,1]
	s_waitcnt lgkmcnt(0)
	v_pk_mul_f32 v[118:119], v[130:131], v[34:35] op_sel:[1,1] op_sel_hi:[0,1]
	v_pk_fma_f32 v[130:131], v[130:131], v[34:35], v[118:119] op_sel_hi:[1,0,1] neg_hi:[0,0,1]
	v_pk_add_f32 v[182:183], v[100:101], v[116:117]
	v_pk_add_f32 v[110:111], v[100:101], v[116:117] neg_lo:[0,1] neg_hi:[0,1]
	v_pk_add_f32 v[102:103], v[108:109], v[124:125]
	v_pk_add_f32 v[184:185], v[108:109], v[124:125] neg_lo:[0,1] neg_hi:[0,1]
	v_pk_add_f32 v[100:101], v[182:183], v[102:103]
	v_pk_add_f32 v[116:117], v[182:183], v[102:103] neg_lo:[0,1] neg_hi:[0,1]
	v_pk_add_f32 v[108:109], v[110:111], v[184:185] op_sel:[0,1] op_sel_hi:[1,0] neg_lo:[0,1]
	v_pk_add_f32 v[124:125], v[110:111], v[184:185] op_sel:[0,1] op_sel_hi:[1,0] neg_hi:[0,1]
	v_pk_add_f32 v[186:187], v[178:179], v[166:167]
	v_pk_add_f32 v[188:189], v[178:179], v[166:167] neg_lo:[0,1] neg_hi:[0,1]
	v_pk_add_f32 v[168:169], v[176:177], v[174:175]
	v_pk_add_f32 v[180:181], v[176:177], v[174:175] neg_lo:[0,1] neg_hi:[0,1]
	v_pk_add_f32 v[178:179], v[186:187], v[168:169]
	v_pk_add_f32 v[166:167], v[186:187], v[168:169] neg_lo:[0,1] neg_hi:[0,1]
	v_pk_add_f32 v[176:177], v[188:189], v[180:181] op_sel:[0,1] op_sel_hi:[1,0] neg_lo:[0,1]
	v_pk_add_f32 v[174:175], v[188:189], v[180:181] op_sel:[0,1] op_sel_hi:[1,0] neg_hi:[0,1]
	v_pk_add_f32 v[126:127], v[104:105], v[120:121]
	v_pk_add_f32 v[118:119], v[104:105], v[120:121] neg_lo:[0,1] neg_hi:[0,1]
	v_pk_add_f32 v[182:183], v[112:113], v[128:129]
	v_pk_add_f32 v[110:111], v[112:113], v[128:129] neg_lo:[0,1] neg_hi:[0,1]
	v_pk_add_f32 v[104:105], v[126:127], v[182:183]
	v_pk_add_f32 v[120:121], v[126:127], v[182:183] neg_lo:[0,1] neg_hi:[0,1]
	v_pk_add_f32 v[112:113], v[118:119], v[110:111] op_sel:[0,1] op_sel_hi:[1,0] neg_lo:[0,1]
	v_pk_add_f32 v[128:129], v[118:119], v[110:111] op_sel:[0,1] op_sel_hi:[1,0] neg_hi:[0,1]
	v_pk_add_f32 v[102:103], v[106:107], v[122:123]
	v_pk_add_f32 v[184:185], v[106:107], v[122:123] neg_lo:[0,1] neg_hi:[0,1]
	v_pk_add_f32 v[186:187], v[114:115], v[130:131]
	v_pk_add_f32 v[188:189], v[114:115], v[130:131] neg_lo:[0,1] neg_hi:[0,1]
	v_pk_add_f32 v[106:107], v[102:103], v[186:187]
	v_pk_add_f32 v[122:123], v[102:103], v[186:187] neg_lo:[0,1] neg_hi:[0,1]
	v_pk_add_f32 v[114:115], v[184:185], v[188:189] op_sel:[0,1] op_sel_hi:[1,0] neg_lo:[0,1]
	v_pk_add_f32 v[130:131], v[184:185], v[188:189] op_sel:[0,1] op_sel_hi:[1,0] neg_hi:[0,1]
	v_pk_mul_f32 v[168:169], v[176:177], s[68:69] op_sel:[1,1] op_sel_hi:[0,1]
	v_pk_fma_f32 v[176:177], v[176:177], s[68:69], v[168:169] op_sel_hi:[1,0,1] neg_hi:[0,0,1]
	v_pk_mul_f32 v[180:181], v[112:113], s[84:85] op_sel:[1,1] op_sel_hi:[0,1]
	v_pk_fma_f32 v[112:113], v[112:113], s[84:85], v[180:181] op_sel_hi:[1,0,1] neg_hi:[0,0,1]
	v_pk_mul_f32 v[126:127], v[114:115], s[88:89] op_sel:[1,1] op_sel_hi:[0,1]
	v_pk_fma_f32 v[114:115], v[114:115], s[88:89], v[126:127] op_sel_hi:[1,0,1] neg_hi:[0,0,1]
	v_pk_mul_f32 v[118:119], v[166:167], s[84:85] op_sel:[1,1] op_sel_hi:[0,1]
	v_pk_fma_f32 v[166:167], v[166:167], s[84:85], v[118:119] op_sel_hi:[1,0,1] neg_hi:[0,0,1]
	v_pk_mul_f32 v[182:183], v[122:123], s[90:91] op_sel:[1,1] op_sel_hi:[0,1]
	v_pk_fma_f32 v[122:123], v[122:123], s[90:91], v[182:183] op_sel_hi:[1,0,1] neg_hi:[0,0,1]
	v_pk_mul_f32 v[110:111], v[174:175], s[88:89] op_sel:[1,1] op_sel_hi:[0,1]
	v_pk_fma_f32 v[174:175], v[174:175], s[88:89], v[110:111] op_sel_hi:[1,0,1] neg_hi:[0,0,1]
	v_pk_mul_f32 v[102:103], v[128:129], s[90:91] op_sel:[1,1] op_sel_hi:[0,1]
	v_pk_fma_f32 v[128:129], v[128:129], s[90:91], v[102:103] op_sel_hi:[1,0,1] neg_hi:[0,0,1]
	v_pk_mul_f32 v[184:185], v[130:131], s[98:99] op_sel:[1,1] op_sel_hi:[0,1]
	v_pk_fma_f32 v[130:131], v[130:131], s[98:99], v[184:185] op_sel_hi:[1,0,1] neg_hi:[0,0,1]
	v_pk_add_f32 v[186:187], v[100:101], v[104:105]
	v_pk_add_f32 v[188:189], v[100:101], v[104:105] neg_lo:[0,1] neg_hi:[0,1]
	v_pk_add_f32 v[168:169], v[178:179], v[106:107]
	v_pk_add_f32 v[180:181], v[178:179], v[106:107] neg_lo:[0,1] neg_hi:[0,1]
	v_pk_add_f32 v[100:101], v[186:187], v[168:169]
	v_pk_add_f32 v[178:179], v[188:189], v[180:181] op_sel:[0,1] op_sel_hi:[1,0] neg_lo:[0,1]
	v_pk_add_f32 v[126:127], v[108:109], v[112:113]
	v_pk_add_f32 v[118:119], v[108:109], v[112:113] neg_lo:[0,1] neg_hi:[0,1]
	v_pk_add_f32 v[182:183], v[176:177], v[114:115]
	v_pk_add_f32 v[110:111], v[176:177], v[114:115] neg_lo:[0,1] neg_hi:[0,1]
	v_pk_add_f32 v[108:109], v[126:127], v[182:183]
	v_pk_add_f32 v[176:177], v[118:119], v[110:111] op_sel:[0,1] op_sel_hi:[1,0] neg_lo:[0,1]
	v_pk_add_f32 v[102:103], v[116:117], v[120:121] op_sel:[0,1] op_sel_hi:[1,0] neg_lo:[0,1]
	v_pk_add_f32 v[184:185], v[116:117], v[120:121] op_sel:[0,1] op_sel_hi:[1,0] neg_hi:[0,1]
	v_pk_add_f32 v[186:187], v[166:167], v[122:123]
	v_pk_add_f32 v[188:189], v[166:167], v[122:123] neg_lo:[0,1] neg_hi:[0,1]
	v_pk_add_f32 v[116:117], v[102:103], v[186:187]
	v_pk_add_f32 v[166:167], v[184:185], v[188:189] op_sel:[0,1] op_sel_hi:[1,0] neg_lo:[0,1]
	v_pk_add_f32 v[168:169], v[124:125], v[128:129]
	v_pk_add_f32 v[180:181], v[124:125], v[128:129] neg_lo:[0,1] neg_hi:[0,1]
	v_pk_add_f32 v[126:127], v[174:175], v[130:131]
	v_pk_add_f32 v[118:119], v[174:175], v[130:131] neg_lo:[0,1] neg_hi:[0,1]
	v_pk_add_f32 v[124:125], v[168:169], v[126:127]
	v_pk_add_f32 v[174:175], v[180:181], v[118:119] op_sel:[0,1] op_sel_hi:[1,0] neg_lo:[0,1]
	s_load_dword s35, s[50:51], 0x0
	s_waitcnt lgkmcnt(0)
; #define LAS __attribute__((address_space(3)))
; #define WG_SYNC() do { asm volatile("s_waitcnt lgkmcnt(0)" ::: "memory"); __builtin_amdgcn_s_barrier(); asm volatile("" ::: "memory"); } while (0)
; __device__ __forceinline__ void hy_stage(LAS float* plane, const bf16_t* PHY, int cg, int jc, int tid) {
;     asm volatile("" : "+v"(tid));
;     const u32x4* src = (const u32x4*)(PHY + (size_t)cg * MT * 4);
; #pragma unroll
;     for (int k = 0; k < 8; ++k) { const int i = tid + 512 * k; const u32x4 v = src[i];
;         const unsigned w0 = (jc & 2) ? v.y : v.x, w1 = (jc & 2) ? v.w : v.z;
;         f32x2 o; o.x = (jc & 1) ? bf_hi(w0) : bf_lo(w0); o.y = (jc & 1) ? bf_hi(w1) : bf_lo(w1);
;         *(LAS f32x2*)(plane + 2 * i) = o; }
; }
; __device__ __forceinline__ void hy_sconv(const LAS float* plane, float w0, float w1, float w2, float cb, int n2, float (&u)[8][2]) {
;     asm volatile("" : "+v"(n2));
; #pragma unroll
;     for (int r = 0; r < 8; ++r)
; #pragma unroll
;         for (int b = 0; b < 2; ++b) { const int t = n2 + 512 * r, row = b * SEQ + t;
;             float a = cb + w1 * plane[row];
;             if (t > 0) a += w0 * plane[row - 1];
;             if (t < SEQ - 1) a += w2 * plane[row + 1];
;             u[r][b] = a; }
; }
; __device__ __forceinline__ void hyena_fft(LAS unsigned char* lds, int layer, int G, const int wave_s) {
;     ...
;             { const float fb0 = fbias[c];
; #pragma unroll
;               for (int r = 0; r < 8; ++r) { uz[r][0] = ux[r][0] * (x[r].x + fb0 * uz[r][0]); uz[r][1] = ux[r][1] * (x[r].y + fb0 * uz[r][1]); } }
;             WG_SYNC();
;             hy_stage(pl0, PHY, (HY / 4) + unit, jc, tid);
;             WG_SYNC();
;             hy_sconv(pl0, cw[HY + c], cw[3 * HY + HY + c], cw[6 * HY + HY + c], cb[HY + c], n2, ux);
;             WG_SYNC();
	v_mov_b32_e32 v194, s35
	v_pk_fma_f32 v[182:183], v[132:133], v[194:195], v[100:101] op_sel_hi:[1,0,1]
	v_pk_mul_f32 v[132:133], v[148:149], v[182:183]
	v_pk_fma_f32 v[110:111], v[134:135], v[194:195], v[108:109] op_sel_hi:[1,0,1]
	v_pk_mul_f32 v[134:135], v[150:151], v[110:111]
	v_pk_fma_f32 v[102:103], v[136:137], v[194:195], v[116:117] op_sel_hi:[1,0,1]
	v_pk_mul_f32 v[136:137], v[152:153], v[102:103]
	v_pk_fma_f32 v[184:185], v[138:139], v[194:195], v[124:125] op_sel_hi:[1,0,1]
	v_pk_mul_f32 v[138:139], v[154:155], v[184:185]
	v_pk_fma_f32 v[186:187], v[140:141], v[194:195], v[178:179] op_sel_hi:[1,0,1]
	v_pk_mul_f32 v[140:141], v[158:159], v[186:187]
	v_pk_fma_f32 v[188:189], v[142:143], v[194:195], v[176:177] op_sel_hi:[1,0,1]
	v_pk_mul_f32 v[142:143], v[160:161], v[188:189]
	v_pk_fma_f32 v[168:169], v[144:145], v[194:195], v[166:167] op_sel_hi:[1,0,1]
	v_pk_mul_f32 v[144:145], v[162:163], v[168:169]
	v_pk_fma_f32 v[180:181], v[146:147], v[194:195], v[174:175] op_sel_hi:[1,0,1]
	v_pk_mul_f32 v[146:147], v[164:165], v[180:181]
	s_waitcnt lgkmcnt(0)
	s_barrier
	s_cbranch_vccz .Lhfft_st7
	s_sleep 4
.Lhfft_st7:
	s_waitcnt vmcnt(7)
	v_perm_b32 v126, 0, v58, s15
	v_perm_b32 v127, 0, v60, s15
	ds_write_b64 v206, v[126:127]
	s_waitcnt vmcnt(6)
	v_perm_b32 v118, 0, v62, s15
	v_perm_b32 v119, 0, v64, s15
	ds_write_b64 v206, v[118:119] offset:4096
	s_waitcnt vmcnt(5)
	v_perm_b32 v182, 0, v66, s15
	v_perm_b32 v183, 0, v68, s15
	ds_write_b64 v206, v[182:183] offset:8192
	s_waitcnt vmcnt(4)
	v_perm_b32 v110, 0, v70, s15
	v_perm_b32 v111, 0, v72, s15
	ds_write_b64 v206, v[110:111] offset:12288
	s_waitcnt vmcnt(3)
	v_perm_b32 v102, 0, v74, s15
	v_perm_b32 v103, 0, v76, s15
	ds_write_b64 v206, v[102:103] offset:16384
	s_waitcnt vmcnt(2)
	v_perm_b32 v184, 0, v78, s15
	v_perm_b32 v185, 0, v80, s15
	ds_write_b64 v206, v[184:185] offset:20480
	s_waitcnt vmcnt(1)
	v_perm_b32 v186, 0, v82, s15
	v_perm_b32 v187, 0, v84, s15
	ds_write_b64 v206, v[186:187] offset:24576
	s_waitcnt vmcnt(0)
	v_perm_b32 v188, 0, v86, s15
	v_perm_b32 v189, 0, v88, s15
	ds_write_b64 v206, v[188:189] offset:28672
	s_waitcnt lgkmcnt(0)
	s_barrier
	s_cbranch_vccz .Lhfft_st8
	s_sleep 4
.Lhfft_st8:
	v_mov_b32_e32 v168, s17
	v_mov_b32_e32 v169, s23
	v_mov_b32_e32 v180, s25
	v_mov_b32_e32 v181, s26
	ds_read_b32 v126, v208
	ds_read_b32 v118, v210
	ds_read_b32 v182, v208 offset:4
	ds_read_b32 v127, v208 offset:16384
	ds_read_b32 v119, v210 offset:16384
	ds_read_b32 v183, v208 offset:16388
	ds_read_b32 v110, v208 offset:2048
	ds_read_b32 v102, v208 offset:2044
	ds_read_b32 v184, v208 offset:2052
	ds_read_b32 v111, v208 offset:18432
	ds_read_b32 v103, v208 offset:18428
	ds_read_b32 v185, v208 offset:18436
	s_waitcnt lgkmcnt(10)
	v_cndmask_b32_e64 v118, v118, 0, s[10:11]
	s_waitcnt lgkmcnt(7)
	v_cndmask_b32_e64 v119, v119, 0, s[10:11]
	v_pk_fma_f32 v[148:149], v[168:169], v[126:127], v[180:181] op_sel:[1,0,1]
	v_pk_fma_f32 v[148:149], v[168:169], v[118:119], v[148:149] op_sel_hi:[0,1,1]
	s_waitcnt lgkmcnt(6)
	v_pk_fma_f32 v[148:149], v[180:181], v[182:183], v[148:149] op_sel_hi:[0,1,1]
	s_waitcnt lgkmcnt(2)
	v_pk_fma_f32 v[150:151], v[168:169], v[110:111], v[180:181] op_sel:[1,0,1]
	s_waitcnt lgkmcnt(1)
	v_pk_fma_f32 v[150:151], v[168:169], v[102:103], v[150:151] op_sel_hi:[0,1,1]
	s_waitcnt lgkmcnt(0)
	v_pk_fma_f32 v[150:151], v[180:181], v[184:185], v[150:151] op_sel_hi:[0,1,1]
	ds_read_b32 v186, v208 offset:4096
	ds_read_b32 v188, v208 offset:4092
	ds_read_b32 v126, v208 offset:4100
	ds_read_b32 v187, v208 offset:20480
	ds_read_b32 v189, v208 offset:20476
	ds_read_b32 v127, v208 offset:20484
	ds_read_b32 v118, v208 offset:6144
	ds_read_b32 v182, v208 offset:6140
	ds_read_b32 v110, v208 offset:6148
	ds_read_b32 v119, v208 offset:22528
	ds_read_b32 v183, v208 offset:22524
	ds_read_b32 v111, v208 offset:22532
	s_waitcnt lgkmcnt(8)
	v_pk_fma_f32 v[152:153], v[168:169], v[186:187], v[180:181] op_sel:[1,0,1]
	s_waitcnt lgkmcnt(7)
	v_pk_fma_f32 v[152:153], v[168:169], v[188:189], v[152:153] op_sel_hi:[0,1,1]
	s_waitcnt lgkmcnt(6)
	v_pk_fma_f32 v[152:153], v[180:181], v[126:127], v[152:153] op_sel_hi:[0,1,1]
	s_waitcnt lgkmcnt(2)
	v_pk_fma_f32 v[154:155], v[168:169], v[118:119], v[180:181] op_sel:[1,0,1]
	s_waitcnt lgkmcnt(1)
	v_pk_fma_f32 v[154:155], v[168:169], v[182:183], v[154:155] op_sel_hi:[0,1,1]
	s_waitcnt lgkmcnt(0)
	v_pk_fma_f32 v[154:155], v[180:181], v[110:111], v[154:155] op_sel_hi:[0,1,1]
	ds_read_b32 v102, v208 offset:8192
	ds_read_b32 v184, v208 offset:8188
	ds_read_b32 v186, v208 offset:8196
	ds_read_b32 v103, v208 offset:24576
	ds_read_b32 v185, v208 offset:24572
	ds_read_b32 v187, v208 offset:24580
	ds_read_b32 v188, v208 offset:10240
	ds_read_b32 v126, v208 offset:10236
	ds_read_b32 v118, v208 offset:10244
	ds_read_b32 v189, v208 offset:26624
	ds_read_b32 v127, v208 offset:26620
	ds_read_b32 v119, v208 offset:26628
	s_waitcnt lgkmcnt(8)
	v_pk_fma_f32 v[158:159], v[168:169], v[102:103], v[180:181] op_sel:[1,0,1]
	s_waitcnt lgkmcnt(7)
	v_pk_fma_f32 v[158:159], v[168:169], v[184:185], v[158:159] op_sel_hi:[0,1,1]
	s_waitcnt lgkmcnt(6)
	v_pk_fma_f32 v[158:159], v[180:181], v[186:187], v[158:159] op_sel_hi:[0,1,1]
	s_waitcnt lgkmcnt(2)
	v_pk_fma_f32 v[160:161], v[168:169], v[188:189], v[180:181] op_sel:[1,0,1]
	s_waitcnt lgkmcnt(1)
	v_pk_fma_f32 v[160:161], v[168:169], v[126:127], v[160:161] op_sel_hi:[0,1,1]
	s_waitcnt lgkmcnt(0)
	v_pk_fma_f32 v[160:161], v[180:181], v[118:119], v[160:161] op_sel_hi:[0,1,1]
	ds_read_b32 v182, v208 offset:12288
	ds_read_b32 v110, v208 offset:12284
	ds_read_b32 v102, v208 offset:12292
	ds_read_b32 v183, v208 offset:28672
	ds_read_b32 v111, v208 offset:28668
	ds_read_b32 v103, v208 offset:28676
	ds_read_b32 v184, v208 offset:14336
	ds_read_b32 v186, v208 offset:14332
	ds_read_b32 v188, v208 offset:14340
	ds_read_b32 v185, v208 offset:30720
	ds_read_b32 v187, v208 offset:30716
	ds_read_b32 v189, v208 offset:30724
	s_waitcnt lgkmcnt(8)
	v_pk_fma_f32 v[162:163], v[168:169], v[182:183], v[180:181] op_sel:[1,0,1]
	s_waitcnt lgkmcnt(7)
	v_pk_fma_f32 v[162:163], v[168:169], v[110:111], v[162:163] op_sel_hi:[0,1,1]
	s_waitcnt lgkmcnt(6)
	v_pk_fma_f32 v[162:163], v[180:181], v[102:103], v[162:163] op_sel_hi:[0,1,1]
	s_waitcnt lgkmcnt(3)
	v_cndmask_b32_e64 v188, v188, 0, s[28:29]
	s_waitcnt lgkmcnt(0)
	v_cndmask_b32_e64 v189, v189, 0, s[28:29]
	v_pk_fma_f32 v[164:165], v[168:169], v[184:185], v[180:181] op_sel:[1,0,1]
	v_pk_fma_f32 v[164:165], v[168:169], v[186:187], v[164:165] op_sel_hi:[0,1,1]
	v_pk_fma_f32 v[164:165], v[180:181], v[188:189], v[164:165] op_sel_hi:[0,1,1]
	s_waitcnt lgkmcnt(0)
	s_barrier
	s_cbranch_vccz .Lhfft_st9
	s_sleep 4
; #define LAS __attribute__((address_space(3)))
; __device__ __forceinline__ f32x2 cmul(f32x2 a, f32x2 b) { return (f32x2){a.x * b.x - a.y * b.y, a.x * b.y + a.y * b.x}; }
; __device__ __forceinline__ void dft16_fwd_lo(f32x2 (&x)[16]) {
;     constexpr float C1 = 0.92387953251128674f, S1 = 0.38268343236508977f, C2 = 0.70710678118654752f;
; #pragma unroll
;     for (int b = 0; b < 4; ++b) { const f32x2 x0 = x[b], x1 = x[4 + b]; const f32x2 j1 = {x1.y, -x1.x};
;         x[b] = x0 + x1; x[4 + b] = x0 + j1; x[8 + b] = x0 - x1; x[12 + b] = x0 - j1; }
;     const f32x2 w1 = {C1, -S1}, w2 = {C2, -C2}, w3 = {S1, -C1}, w4 = {0.f, -1.f}, w6 = {-C2, -C2}, w9 = {-C1, S1};
;     x[5] = cmul(x[5], w1); x[6] = cmul(x[6], w2); x[7] = cmul(x[7], w3);
;     x[9] = cmul(x[9], w2); x[10] = cmul(x[10], w4); x[11] = cmul(x[11], w6);
;     x[13] = cmul(x[13], w3); x[14] = cmul(x[14], w6); x[15] = cmul(x[15], w9);
; #pragma unroll
;     for (int c = 0; c < 4; ++c) dft4<false>(x[4 * c], x[4 * c + 1], x[4 * c + 2], x[4 * c + 3]);
;     f32x2 y[16];
; #pragma unroll
;     for (int k = 0; k < 16; ++k) y[k] = x[4 * (k & 3) + (k >> 2)];
; #pragma unroll
;     for (int k = 0; k < 16; ++k) x[k] = y[k];
; }
; template <bool LO> __device__ __forceinline__ void fft_fwd1(f32x2 (&x)[16], LAS f32x2* B, int n2, const f32x2 (&w)[16]) {
;     asm volatile("" : "+v"(n2));
;     if (LO) dft16_fwd_lo(x); else dft16<false>(x);
;     B[fpad(n2)] = x[0];
; #pragma unroll
;     for (int k = 1; k < 16; ++k) B[fpad(512 * k + n2)] = cmul(x[k], w[k]);
; }
.Lhfft_st9:
	v_pk_add_f32 v[104:105], v[132:133], v[140:141] neg_lo:[0,1] neg_hi:[0,1]
	v_pk_add_f32 v[106:107], v[132:133], v[140:141] op_sel:[0,1] op_sel_hi:[1,0] neg_lo:[0,1]
	v_pk_add_f32 v[126:127], v[132:133], v[140:141] op_sel:[0,1] op_sel_hi:[1,0] neg_hi:[0,1]
	v_pk_add_f32 v[100:101], v[132:133], v[140:141]
	v_pk_add_f32 v[112:113], v[134:135], v[142:143] neg_lo:[0,1] neg_hi:[0,1]
	v_pk_add_f32 v[114:115], v[134:135], v[142:143] op_sel:[0,1] op_sel_hi:[1,0] neg_lo:[0,1]
	v_pk_add_f32 v[118:119], v[134:135], v[142:143] op_sel:[0,1] op_sel_hi:[1,0] neg_hi:[0,1]
	v_pk_add_f32 v[108:109], v[134:135], v[142:143]
	v_pk_add_f32 v[120:121], v[136:137], v[144:145] neg_lo:[0,1] neg_hi:[0,1]
	v_pk_add_f32 v[122:123], v[136:137], v[144:145] op_sel:[0,1] op_sel_hi:[1,0] neg_lo:[0,1]
	v_pk_add_f32 v[182:183], v[136:137], v[144:145] op_sel:[0,1] op_sel_hi:[1,0] neg_hi:[0,1]
	v_pk_add_f32 v[116:117], v[136:137], v[144:145]
	v_pk_add_f32 v[128:129], v[138:139], v[146:147] neg_lo:[0,1] neg_hi:[0,1]
	v_pk_add_f32 v[130:131], v[138:139], v[146:147] op_sel:[0,1] op_sel_hi:[1,0] neg_lo:[0,1]
	v_pk_add_f32 v[110:111], v[138:139], v[146:147] op_sel:[0,1] op_sel_hi:[1,0] neg_hi:[0,1]
	v_pk_add_f32 v[124:125], v[138:139], v[146:147]
	v_pk_mul_f32 v[102:103], v[118:119], s[68:69] op_sel:[1,1] op_sel_hi:[0,1]
	v_pk_fma_f32 v[118:119], v[118:119], s[68:69], v[102:103] op_sel_hi:[1,0,1] neg_lo:[0,0,1]
	v_pk_mul_f32 v[184:185], v[182:183], s[84:85] op_sel:[1,1] op_sel_hi:[0,1]
	v_pk_fma_f32 v[182:183], v[182:183], s[84:85], v[184:185] op_sel_hi:[1,0,1] neg_lo:[0,0,1]
	v_pk_mul_f32 v[186:187], v[110:111], s[88:89] op_sel:[1,1] op_sel_hi:[0,1]
	v_pk_fma_f32 v[110:111], v[110:111], s[88:89], v[186:187] op_sel_hi:[1,0,1] neg_lo:[0,0,1]
	v_pk_mul_f32 v[188:189], v[112:113], s[84:85] op_sel:[1,1] op_sel_hi:[0,1]
	v_pk_fma_f32 v[112:113], v[112:113], s[84:85], v[188:189] op_sel_hi:[1,0,1] neg_lo:[0,0,1]
	v_pk_mul_f32 v[168:169], v[128:129], s[90:91] op_sel:[1,1] op_sel_hi:[0,1]
	v_pk_fma_f32 v[128:129], v[128:129], s[90:91], v[168:169] op_sel_hi:[1,0,1] neg_lo:[0,0,1]
	v_pk_mul_f32 v[180:181], v[114:115], s[88:89] op_sel:[1,1] op_sel_hi:[0,1]
	v_pk_fma_f32 v[114:115], v[114:115], s[88:89], v[180:181] op_sel_hi:[1,0,1] neg_lo:[0,0,1]
	v_pk_mul_f32 v[178:179], v[122:123], s[90:91] op_sel:[1,1] op_sel_hi:[0,1]
	v_pk_fma_f32 v[122:123], v[122:123], s[90:91], v[178:179] op_sel_hi:[1,0,1] neg_lo:[0,0,1]
	v_pk_mul_f32 v[176:177], v[130:131], s[98:99] op_sel:[1,1] op_sel_hi:[0,1]
	v_pk_fma_f32 v[130:131], v[130:131], s[98:99], v[176:177] op_sel_hi:[1,0,1] neg_lo:[0,0,1]
	v_pk_add_f32 v[166:167], v[100:101], v[116:117]
	v_pk_add_f32 v[174:175], v[100:101], v[116:117] neg_lo:[0,1] neg_hi:[0,1]
	v_pk_add_f32 v[102:103], v[108:109], v[124:125]
	v_pk_add_f32 v[184:185], v[108:109], v[124:125] neg_lo:[0,1] neg_hi:[0,1]
	v_pk_add_f32 v[100:101], v[166:167], v[102:103]
	v_pk_add_f32 v[116:117], v[166:167], v[102:103] neg_lo:[0,1] neg_hi:[0,1]
	v_pk_add_f32 v[108:109], v[174:175], v[184:185] op_sel:[0,1] op_sel_hi:[1,0] neg_hi:[0,1]
	v_pk_add_f32 v[124:125], v[174:175], v[184:185] op_sel:[0,1] op_sel_hi:[1,0] neg_lo:[0,1]
	v_pk_add_f32 v[186:187], v[126:127], v[182:183]
	v_pk_add_f32 v[188:189], v[126:127], v[182:183] neg_lo:[0,1] neg_hi:[0,1]
	v_pk_add_f32 v[168:169], v[118:119], v[110:111]
	v_pk_add_f32 v[180:181], v[118:119], v[110:111] neg_lo:[0,1] neg_hi:[0,1]
	v_pk_add_f32 v[126:127], v[186:187], v[168:169]
	v_pk_add_f32 v[182:183], v[186:187], v[168:169] neg_lo:[0,1] neg_hi:[0,1]
	v_pk_add_f32 v[118:119], v[188:189], v[180:181] op_sel:[0,1] op_sel_hi:[1,0] neg_hi:[0,1]
	v_pk_add_f32 v[110:111], v[188:189], v[180:181] op_sel:[0,1] op_sel_hi:[1,0] neg_lo:[0,1]
	v_pk_add_f32 v[178:179], v[104:105], v[120:121] op_sel:[0,1] op_sel_hi:[1,0] neg_hi:[0,1]
	v_pk_add_f32 v[176:177], v[104:105], v[120:121] op_sel:[0,1] op_sel_hi:[1,0] neg_lo:[0,1]
	v_pk_add_f32 v[166:167], v[112:113], v[128:129]
	v_pk_add_f32 v[174:175], v[112:113], v[128:129] neg_lo:[0,1] neg_hi:[0,1]
	v_pk_add_f32 v[104:105], v[178:179], v[166:167]
	v_pk_add_f32 v[120:121], v[178:179], v[166:167] neg_lo:[0,1] neg_hi:[0,1]
	v_pk_add_f32 v[112:113], v[176:177], v[174:175] op_sel:[0,1] op_sel_hi:[1,0] neg_hi:[0,1]
	v_pk_add_f32 v[128:129], v[176:177], v[174:175] op_sel:[0,1] op_sel_hi:[1,0] neg_lo:[0,1]
	v_pk_add_f32 v[102:103], v[106:107], v[122:123]
	v_pk_add_f32 v[184:185], v[106:107], v[122:123] neg_lo:[0,1] neg_hi:[0,1]
	v_pk_add_f32 v[186:187], v[114:115], v[130:131]
	v_pk_add_f32 v[188:189], v[114:115], v[130:131] neg_lo:[0,1] neg_hi:[0,1]
	v_pk_add_f32 v[106:107], v[102:103], v[186:187]
	v_pk_add_f32 v[122:123], v[102:103], v[186:187] neg_lo:[0,1] neg_hi:[0,1]
	v_pk_add_f32 v[114:115], v[184:185], v[188:189] op_sel:[0,1] op_sel_hi:[1,0] neg_hi:[0,1]
	v_pk_add_f32 v[130:131], v[184:185], v[188:189] op_sel:[0,1] op_sel_hi:[1,0] neg_lo:[0,1]
	ds_write_b64 v3, v[100:101]
	v_pk_mul_f32 v[180:181], v[126:127], v[6:7] op_sel:[1,1] op_sel_hi:[0,1]
	v_pk_fma_f32 v[168:169], v[126:127], v[6:7], v[180:181] op_sel_hi:[1,0,1] neg_lo:[0,0,1]
	ds_write_b64 v3, v[168:169] offset:4224
	v_pk_mul_f32 v[176:177], v[104:105], v[8:9] op_sel:[1,1] op_sel_hi:[0,1]
	v_pk_fma_f32 v[178:179], v[104:105], v[8:9], v[176:177] op_sel_hi:[1,0,1] neg_lo:[0,0,1]
	ds_write_b64 v3, v[178:179] offset:8448
	v_pk_mul_f32 v[174:175], v[106:107], v[10:11] op_sel:[1,1] op_sel_hi:[0,1]
	v_pk_fma_f32 v[166:167], v[106:107], v[10:11], v[174:175] op_sel_hi:[1,0,1] neg_lo:[0,0,1]
	ds_write_b64 v3, v[166:167] offset:12672
	v_pk_mul_f32 v[184:185], v[108:109], v[12:13] op_sel:[1,1] op_sel_hi:[0,1]
	v_pk_fma_f32 v[102:103], v[108:109], v[12:13], v[184:185] op_sel_hi:[1,0,1] neg_lo:[0,0,1]
; #define LAS __attribute__((address_space(3)))
; __device__ __forceinline__ f32x2 cmul(f32x2 a, f32x2 b) { return (f32x2){a.x * b.x - a.y * b.y, a.x * b.y + a.y * b.x}; }
; template <bool INV> __device__ __forceinline__ f32x2 cmul_tw(f32x2 a, f32x2 w) { return INV ? cmulc(a, w) : cmul(a, w); }
; template <bool INV> __device__ __forceinline__ void dft16(f32x2 (&x)[16]) {
;     ...
;     for (int b = 0; b < 4; ++b) dft4<INV>(x[b], x[4 + b], x[8 + b], x[12 + b]);
;     const f32x2 w1 = {C1, -S1}, w2 = {C2, -C2}, w3 = {S1, -C1}, w4 = {0.f, -1.f}, w6 = {-C2, -C2}, w9 = {-C1, S1};
;     x[4 * 1 + 1] = cmul_tw<INV>(x[5], w1); x[4 * 1 + 2] = cmul_tw<INV>(x[6], w2); x[4 * 1 + 3] = cmul_tw<INV>(x[7], w3);
;     x[4 * 2 + 1] = cmul_tw<INV>(x[9], w2); x[4 * 2 + 2] = cmul_tw<INV>(x[10], w4); x[4 * 2 + 3] = cmul_tw<INV>(x[11], w6);
;     x[4 * 3 + 1] = cmul_tw<INV>(x[13], w3); x[4 * 3 + 2] = cmul_tw<INV>(x[14], w6); x[4 * 3 + 3] = cmul_tw<INV>(x[15], w9);
; #pragma unroll
;     for (int c = 0; c < 4; ++c) dft4<INV>(x[4 * c], x[4 * c + 1], x[4 * c + 2], x[4 * c + 3]);
; template <bool LO> __device__ __forceinline__ void fft_fwd1(f32x2 (&x)[16], LAS f32x2* B, int n2, const f32x2 (&w)[16]) {
;     ...
;     B[fpad(n2)] = x[0];
; #pragma unroll
;     for (int k = 1; k < 16; ++k) B[fpad(512 * k + n2)] = cmul(x[k], w[k]);
; }
; __device__ __forceinline__ void fft_fwd2(LAS f32x2* B, const LAS f32x2* TW2, int tid) {
;     asm volatile("" : "+v"(tid));
;     const int b = tid >> 5, n2 = tid & 31, base = 512 * b + n2; f32x2 x[16];
; #pragma unroll
;     for (int r = 0; r < 16; ++r) x[r] = B[fpad(base + 32 * r)];
;     dft16<false>(x);
	ds_write_b64 v3, v[102:103] offset:16896
	v_pk_mul_f32 v[188:189], v[118:119], v[14:15] op_sel:[1,1] op_sel_hi:[0,1]
	v_pk_fma_f32 v[186:187], v[118:119], v[14:15], v[188:189] op_sel_hi:[1,0,1] neg_lo:[0,0,1]
	ds_write_b64 v3, v[186:187] offset:21120
	v_pk_mul_f32 v[168:169], v[112:113], v[16:17] op_sel:[1,1] op_sel_hi:[0,1]
	v_pk_fma_f32 v[180:181], v[112:113], v[16:17], v[168:169] op_sel_hi:[1,0,1] neg_lo:[0,0,1]
	ds_write_b64 v3, v[180:181] offset:25344
	v_pk_mul_f32 v[178:179], v[114:115], v[18:19] op_sel:[1,1] op_sel_hi:[0,1]
	v_pk_fma_f32 v[176:177], v[114:115], v[18:19], v[178:179] op_sel_hi:[1,0,1] neg_lo:[0,0,1]
	ds_write_b64 v3, v[176:177] offset:29568
	v_pk_mul_f32 v[166:167], v[116:117], v[20:21] op_sel:[1,1] op_sel_hi:[0,1]
	v_pk_fma_f32 v[174:175], v[116:117], v[20:21], v[166:167] op_sel_hi:[1,0,1] neg_lo:[0,0,1]
	ds_write_b64 v3, v[174:175] offset:33792
	v_pk_mul_f32 v[102:103], v[182:183], v[22:23] op_sel:[1,1] op_sel_hi:[0,1]
	v_pk_fma_f32 v[184:185], v[182:183], v[22:23], v[102:103] op_sel_hi:[1,0,1] neg_lo:[0,0,1]
	ds_write_b64 v3, v[184:185] offset:38016
	v_pk_mul_f32 v[186:187], v[120:121], v[24:25] op_sel:[1,1] op_sel_hi:[0,1]
	v_pk_fma_f32 v[188:189], v[120:121], v[24:25], v[186:187] op_sel_hi:[1,0,1] neg_lo:[0,0,1]
	ds_write_b64 v3, v[188:189] offset:42240
	v_pk_mul_f32 v[180:181], v[122:123], v[26:27] op_sel:[1,1] op_sel_hi:[0,1]
	v_pk_fma_f32 v[168:169], v[122:123], v[26:27], v[180:181] op_sel_hi:[1,0,1] neg_lo:[0,0,1]
	ds_write_b64 v3, v[168:169] offset:46464
	v_pk_mul_f32 v[176:177], v[124:125], v[28:29] op_sel:[1,1] op_sel_hi:[0,1]
	v_pk_fma_f32 v[178:179], v[124:125], v[28:29], v[176:177] op_sel_hi:[1,0,1] neg_lo:[0,0,1]
	ds_write_b64 v3, v[178:179] offset:50688
	v_pk_mul_f32 v[174:175], v[110:111], v[30:31] op_sel:[1,1] op_sel_hi:[0,1]
	v_pk_fma_f32 v[166:167], v[110:111], v[30:31], v[174:175] op_sel_hi:[1,0,1] neg_lo:[0,0,1]
	ds_write_b64 v3, v[166:167] offset:54912
	v_pk_mul_f32 v[184:185], v[128:129], v[32:33] op_sel:[1,1] op_sel_hi:[0,1]
	v_pk_fma_f32 v[102:103], v[128:129], v[32:33], v[184:185] op_sel_hi:[1,0,1] neg_lo:[0,0,1]
	ds_write_b64 v3, v[102:103] offset:59136
	v_pk_mul_f32 v[188:189], v[130:131], v[34:35] op_sel:[1,1] op_sel_hi:[0,1]
	v_pk_fma_f32 v[186:187], v[130:131], v[34:35], v[188:189] op_sel_hi:[1,0,1] neg_lo:[0,0,1]
	ds_write_b64 v3, v[186:187] offset:63360
	s_waitcnt lgkmcnt(0)
	s_barrier
	s_cbranch_vccz .Lhfft_st10
	s_sleep 4
.Lhfft_st10:
	ds_read_b64 v[100:101], v5
	ds_read_b64 v[108:109], v5 offset:1056
	ds_read_b64 v[116:117], v5 offset:2112
	ds_read_b64 v[124:125], v5 offset:3168
	ds_read_b64 v[126:127], v5 offset:264
	ds_read_b64 v[118:119], v5 offset:1320
	ds_read_b64 v[182:183], v5 offset:2376
	ds_read_b64 v[110:111], v5 offset:3432
	ds_read_b64 v[104:105], v5 offset:528
	ds_read_b64 v[112:113], v5 offset:1584
	ds_read_b64 v[120:121], v5 offset:2640
	ds_read_b64 v[128:129], v5 offset:3696
	s_waitcnt lgkmcnt(8)
	ds_read_b64 v[106:107], v5 offset:792
	ds_read_b64 v[114:115], v5 offset:1848
	ds_read_b64 v[122:123], v5 offset:2904
	ds_read_b64 v[130:131], v5 offset:3960
	v_pk_add_f32 v[180:181], v[100:101], v[116:117]
	v_pk_add_f32 v[168:169], v[100:101], v[116:117] neg_lo:[0,1] neg_hi:[0,1]
	v_pk_add_f32 v[176:177], v[108:109], v[124:125]
	v_pk_add_f32 v[178:179], v[108:109], v[124:125] neg_lo:[0,1] neg_hi:[0,1]
	v_pk_add_f32 v[100:101], v[180:181], v[176:177]
	v_pk_add_f32 v[116:117], v[180:181], v[176:177] neg_lo:[0,1] neg_hi:[0,1]
	v_pk_add_f32 v[108:109], v[168:169], v[178:179] op_sel:[0,1] op_sel_hi:[1,0] neg_hi:[0,1]
	v_pk_add_f32 v[124:125], v[168:169], v[178:179] op_sel:[0,1] op_sel_hi:[1,0] neg_lo:[0,1]
	s_waitcnt lgkmcnt(9)
	v_pk_add_f32 v[174:175], v[126:127], v[182:183]
	v_pk_add_f32 v[166:167], v[126:127], v[182:183] neg_lo:[0,1] neg_hi:[0,1]
	s_waitcnt lgkmcnt(8)
	v_pk_add_f32 v[184:185], v[118:119], v[110:111]
	v_pk_add_f32 v[102:103], v[118:119], v[110:111] neg_lo:[0,1] neg_hi:[0,1]
	v_pk_add_f32 v[126:127], v[174:175], v[184:185]
	v_pk_add_f32 v[182:183], v[174:175], v[184:185] neg_lo:[0,1] neg_hi:[0,1]
	v_pk_add_f32 v[118:119], v[166:167], v[102:103] op_sel:[0,1] op_sel_hi:[1,0] neg_hi:[0,1]
	v_pk_add_f32 v[110:111], v[166:167], v[102:103] op_sel:[0,1] op_sel_hi:[1,0] neg_lo:[0,1]
	s_waitcnt lgkmcnt(5)
	v_pk_add_f32 v[188:189], v[104:105], v[120:121]
	v_pk_add_f32 v[186:187], v[104:105], v[120:121] neg_lo:[0,1] neg_hi:[0,1]
	s_waitcnt lgkmcnt(4)
	v_pk_add_f32 v[180:181], v[112:113], v[128:129]
	v_pk_add_f32 v[168:169], v[112:113], v[128:129] neg_lo:[0,1] neg_hi:[0,1]
	v_pk_add_f32 v[104:105], v[188:189], v[180:181]
	v_pk_add_f32 v[120:121], v[188:189], v[180:181] neg_lo:[0,1] neg_hi:[0,1]
	v_pk_add_f32 v[112:113], v[186:187], v[168:169] op_sel:[0,1] op_sel_hi:[1,0] neg_hi:[0,1]
	v_pk_add_f32 v[128:129], v[186:187], v[168:169] op_sel:[0,1] op_sel_hi:[1,0] neg_lo:[0,1]
	s_waitcnt lgkmcnt(1)
	v_pk_add_f32 v[176:177], v[106:107], v[122:123]
	v_pk_add_f32 v[178:179], v[106:107], v[122:123] neg_lo:[0,1] neg_hi:[0,1]
	s_waitcnt lgkmcnt(0)
; __device__ __forceinline__ f32x2 cmul(f32x2 a, f32x2 b) { return (f32x2){a.x * b.x - a.y * b.y, a.x * b.y + a.y * b.x}; }
; template <bool INV> __device__ __forceinline__ f32x2 cmul_tw(f32x2 a, f32x2 w) { return INV ? cmulc(a, w) : cmul(a, w); }
; template <bool INV> __device__ __forceinline__ void dft16(f32x2 (&x)[16]) {
;     ...
;     for (int b = 0; b < 4; ++b) dft4<INV>(x[b], x[4 + b], x[8 + b], x[12 + b]);
;     const f32x2 w1 = {C1, -S1}, w2 = {C2, -C2}, w3 = {S1, -C1}, w4 = {0.f, -1.f}, w6 = {-C2, -C2}, w9 = {-C1, S1};
;     x[4 * 1 + 1] = cmul_tw<INV>(x[5], w1); x[4 * 1 + 2] = cmul_tw<INV>(x[6], w2); x[4 * 1 + 3] = cmul_tw<INV>(x[7], w3);
;     x[4 * 2 + 1] = cmul_tw<INV>(x[9], w2); x[4 * 2 + 2] = cmul_tw<INV>(x[10], w4); x[4 * 2 + 3] = cmul_tw<INV>(x[11], w6);
;     x[4 * 3 + 1] = cmul_tw<INV>(x[13], w3); x[4 * 3 + 2] = cmul_tw<INV>(x[14], w6); x[4 * 3 + 3] = cmul_tw<INV>(x[15], w9);
; #pragma unroll
;     for (int c = 0; c < 4; ++c) dft4<INV>(x[4 * c], x[4 * c + 1], x[4 * c + 2], x[4 * c + 3]);
;     f32x2 y[16];
; #pragma unroll
;     for (int k = 0; k < 16; ++k) y[k] = x[4 * (k & 3) + (k >> 2)];
; #pragma unroll
;     for (int k = 0; k < 16; ++k) x[k] = y[k];
; __device__ __forceinline__ void fft_fwd2(LAS f32x2* B, const LAS f32x2* TW2, int tid) {
;     ...
;     dft16<false>(x);
;     B[fpad(base)] = x[0];
; #pragma unroll
;     for (int k = 1; k < 16; ++k) B[fpad(base + 32 * k)] = cmul(x[k], TW2[k * 32 + n2]);
	v_pk_add_f32 v[174:175], v[114:115], v[130:131]
	v_pk_add_f32 v[166:167], v[114:115], v[130:131] neg_lo:[0,1] neg_hi:[0,1]
	v_pk_add_f32 v[106:107], v[176:177], v[174:175]
	v_pk_add_f32 v[122:123], v[176:177], v[174:175] neg_lo:[0,1] neg_hi:[0,1]
	v_pk_add_f32 v[114:115], v[178:179], v[166:167] op_sel:[0,1] op_sel_hi:[1,0] neg_hi:[0,1]
	v_pk_add_f32 v[130:131], v[178:179], v[166:167] op_sel:[0,1] op_sel_hi:[1,0] neg_lo:[0,1]
	v_pk_mul_f32 v[184:185], v[118:119], s[68:69] op_sel:[1,1] op_sel_hi:[0,1]
	v_pk_fma_f32 v[118:119], v[118:119], s[68:69], v[184:185] op_sel_hi:[1,0,1] neg_lo:[0,0,1]
	v_pk_mul_f32 v[102:103], v[112:113], s[84:85] op_sel:[1,1] op_sel_hi:[0,1]
	v_pk_fma_f32 v[112:113], v[112:113], s[84:85], v[102:103] op_sel_hi:[1,0,1] neg_lo:[0,0,1]
	v_pk_mul_f32 v[188:189], v[114:115], s[88:89] op_sel:[1,1] op_sel_hi:[0,1]
	v_pk_fma_f32 v[114:115], v[114:115], s[88:89], v[188:189] op_sel_hi:[1,0,1] neg_lo:[0,0,1]
	v_pk_mul_f32 v[186:187], v[182:183], s[84:85] op_sel:[1,1] op_sel_hi:[0,1]
	v_pk_fma_f32 v[182:183], v[182:183], s[84:85], v[186:187] op_sel_hi:[1,0,1] neg_lo:[0,0,1]
	v_pk_mul_f32 v[180:181], v[122:123], s[90:91] op_sel:[1,1] op_sel_hi:[0,1]
	v_pk_fma_f32 v[122:123], v[122:123], s[90:91], v[180:181] op_sel_hi:[1,0,1] neg_lo:[0,0,1]
	v_pk_mul_f32 v[168:169], v[110:111], s[88:89] op_sel:[1,1] op_sel_hi:[0,1]
	v_pk_fma_f32 v[110:111], v[110:111], s[88:89], v[168:169] op_sel_hi:[1,0,1] neg_lo:[0,0,1]
	v_pk_mul_f32 v[176:177], v[128:129], s[90:91] op_sel:[1,1] op_sel_hi:[0,1]
	v_pk_fma_f32 v[128:129], v[128:129], s[90:91], v[176:177] op_sel_hi:[1,0,1] neg_lo:[0,0,1]
	v_pk_mul_f32 v[178:179], v[130:131], s[98:99] op_sel:[1,1] op_sel_hi:[0,1]
	v_pk_fma_f32 v[130:131], v[130:131], s[98:99], v[178:179] op_sel_hi:[1,0,1] neg_lo:[0,0,1]
	v_pk_add_f32 v[174:175], v[100:101], v[104:105]
	v_pk_add_f32 v[166:167], v[100:101], v[104:105] neg_lo:[0,1] neg_hi:[0,1]
	v_pk_add_f32 v[184:185], v[126:127], v[106:107]
	v_pk_add_f32 v[102:103], v[126:127], v[106:107] neg_lo:[0,1] neg_hi:[0,1]
	v_pk_add_f32 v[100:101], v[174:175], v[184:185]
	v_pk_add_f32 v[104:105], v[174:175], v[184:185] neg_lo:[0,1] neg_hi:[0,1]
	v_pk_add_f32 v[126:127], v[166:167], v[102:103] op_sel:[0,1] op_sel_hi:[1,0] neg_hi:[0,1]
	v_pk_add_f32 v[106:107], v[166:167], v[102:103] op_sel:[0,1] op_sel_hi:[1,0] neg_lo:[0,1]
	v_pk_add_f32 v[188:189], v[108:109], v[112:113]
	v_pk_add_f32 v[186:187], v[108:109], v[112:113] neg_lo:[0,1] neg_hi:[0,1]
	v_pk_add_f32 v[180:181], v[118:119], v[114:115]
	v_pk_add_f32 v[168:169], v[118:119], v[114:115] neg_lo:[0,1] neg_hi:[0,1]
	v_pk_add_f32 v[108:109], v[188:189], v[180:181]
	v_pk_add_f32 v[112:113], v[188:189], v[180:181] neg_lo:[0,1] neg_hi:[0,1]
	v_pk_add_f32 v[118:119], v[186:187], v[168:169] op_sel:[0,1] op_sel_hi:[1,0] neg_hi:[0,1]
	v_pk_add_f32 v[114:115], v[186:187], v[168:169] op_sel:[0,1] op_sel_hi:[1,0] neg_lo:[0,1]
	v_pk_add_f32 v[176:177], v[116:117], v[120:121] op_sel:[0,1] op_sel_hi:[1,0] neg_hi:[0,1]
	v_pk_add_f32 v[178:179], v[116:117], v[120:121] op_sel:[0,1] op_sel_hi:[1,0] neg_lo:[0,1]
	v_pk_add_f32 v[174:175], v[182:183], v[122:123]
	v_pk_add_f32 v[166:167], v[182:183], v[122:123] neg_lo:[0,1] neg_hi:[0,1]
	v_pk_add_f32 v[116:117], v[176:177], v[174:175]
	v_pk_add_f32 v[120:121], v[176:177], v[174:175] neg_lo:[0,1] neg_hi:[0,1]
	v_pk_add_f32 v[182:183], v[178:179], v[166:167] op_sel:[0,1] op_sel_hi:[1,0] neg_hi:[0,1]
	v_pk_add_f32 v[122:123], v[178:179], v[166:167] op_sel:[0,1] op_sel_hi:[1,0] neg_lo:[0,1]
	v_pk_add_f32 v[184:185], v[124:125], v[128:129]
	v_pk_add_f32 v[102:103], v[124:125], v[128:129] neg_lo:[0,1] neg_hi:[0,1]
	v_pk_add_f32 v[188:189], v[110:111], v[130:131]
	v_pk_add_f32 v[186:187], v[110:111], v[130:131] neg_lo:[0,1] neg_hi:[0,1]
	v_pk_add_f32 v[124:125], v[184:185], v[188:189]
	v_pk_add_f32 v[128:129], v[184:185], v[188:189] neg_lo:[0,1] neg_hi:[0,1]
	v_pk_add_f32 v[110:111], v[102:103], v[186:187] op_sel:[0,1] op_sel_hi:[1,0] neg_hi:[0,1]
	v_pk_add_f32 v[130:131], v[102:103], v[186:187] op_sel:[0,1] op_sel_hi:[1,0] neg_lo:[0,1]
	ds_write_b64 v5, v[100:101]
	ds_read_b64 v[180:181], v56 offset:256
	ds_read_b64 v[168:169], v56 offset:512
	ds_read_b64 v[176:177], v56 offset:768
	ds_read_b64 v[178:179], v56 offset:1024
	s_waitcnt lgkmcnt(3)
	v_pk_mul_f32 v[174:175], v[108:109], v[180:181] op_sel:[1,1] op_sel_hi:[0,1]
	v_pk_fma_f32 v[108:109], v[108:109], v[180:181], v[174:175] op_sel_hi:[1,0,1] neg_lo:[0,0,1]
	ds_write_b64 v5, v[108:109] offset:264
	s_waitcnt lgkmcnt(3)
	v_pk_mul_f32 v[166:167], v[116:117], v[168:169] op_sel:[1,1] op_sel_hi:[0,1]
	v_pk_fma_f32 v[116:117], v[116:117], v[168:169], v[166:167] op_sel_hi:[1,0,1] neg_lo:[0,0,1]
	ds_write_b64 v5, v[116:117] offset:528
	s_waitcnt lgkmcnt(3)
	v_pk_mul_f32 v[184:185], v[124:125], v[176:177] op_sel:[1,1] op_sel_hi:[0,1]
	v_pk_fma_f32 v[124:125], v[124:125], v[176:177], v[184:185] op_sel_hi:[1,0,1] neg_lo:[0,0,1]
	ds_write_b64 v5, v[124:125] offset:792
	s_waitcnt lgkmcnt(3)
	v_pk_mul_f32 v[102:103], v[126:127], v[178:179] op_sel:[1,1] op_sel_hi:[0,1]
	v_pk_fma_f32 v[126:127], v[126:127], v[178:179], v[102:103] op_sel_hi:[1,0,1] neg_lo:[0,0,1]
	ds_write_b64 v5, v[126:127] offset:1056
	ds_read_b64 v[188:189], v56 offset:1280
	ds_read_b64 v[186:187], v56 offset:1536
	ds_read_b64 v[174:175], v56 offset:1792
	ds_read_b64 v[166:167], v56 offset:2048
	s_waitcnt lgkmcnt(3)
	v_pk_mul_f32 v[184:185], v[118:119], v[188:189] op_sel:[1,1] op_sel_hi:[0,1]
	v_pk_fma_f32 v[118:119], v[118:119], v[188:189], v[184:185] op_sel_hi:[1,0,1] neg_lo:[0,0,1]
	ds_write_b64 v5, v[118:119] offset:1320
	s_waitcnt lgkmcnt(3)
; #define LAS __attribute__((address_space(3)))
; __device__ __forceinline__ f32x2 cmul(f32x2 a, f32x2 b) { return (f32x2){a.x * b.x - a.y * b.y, a.x * b.y + a.y * b.x}; }
; __device__ __forceinline__ void fft_fwd2(LAS f32x2* B, const LAS f32x2* TW2, int tid) {
;     ...
;     B[fpad(base)] = x[0];
; #pragma unroll
;     for (int k = 1; k < 16; ++k) B[fpad(base + 32 * k)] = cmul(x[k], TW2[k * 32 + n2]);
; }
; template <int MODE> __device__ __forceinline__ void fft_pair32(LAS f32x2* B, const LAS f32x2* F, int wave, int lane) {
;     ...
;     LAS f32x2* p = B + 33 * blk; f32x2 v[16];
; #pragma unroll
;     for (int j = 0; j < 16; ++j) { const f32x2 d = p[j] + p[j + 16] * sg;
;         const f32x2 w = {hi ? CS[j] : 1.f, hi ? -SN[j] : 0.f}; v[j] = j == 0 ? d : cmul(d, w); }
	v_pk_mul_f32 v[102:103], v[182:183], v[186:187] op_sel:[1,1] op_sel_hi:[0,1]
	v_pk_fma_f32 v[182:183], v[182:183], v[186:187], v[102:103] op_sel_hi:[1,0,1] neg_lo:[0,0,1]
	ds_write_b64 v5, v[182:183] offset:1584
	s_waitcnt lgkmcnt(3)
	v_pk_mul_f32 v[180:181], v[110:111], v[174:175] op_sel:[1,1] op_sel_hi:[0,1]
	v_pk_fma_f32 v[110:111], v[110:111], v[174:175], v[180:181] op_sel_hi:[1,0,1] neg_lo:[0,0,1]
	ds_write_b64 v5, v[110:111] offset:1848
	s_waitcnt lgkmcnt(3)
	v_pk_mul_f32 v[168:169], v[104:105], v[166:167] op_sel:[1,1] op_sel_hi:[0,1]
	v_pk_fma_f32 v[104:105], v[104:105], v[166:167], v[168:169] op_sel_hi:[1,0,1] neg_lo:[0,0,1]
	ds_write_b64 v5, v[104:105] offset:2112
	ds_read_b64 v[176:177], v56 offset:2304
	ds_read_b64 v[178:179], v56 offset:2560
	ds_read_b64 v[184:185], v56 offset:2816
	ds_read_b64 v[102:103], v56 offset:3072
	s_waitcnt lgkmcnt(3)
	v_pk_mul_f32 v[180:181], v[112:113], v[176:177] op_sel:[1,1] op_sel_hi:[0,1]
	v_pk_fma_f32 v[112:113], v[112:113], v[176:177], v[180:181] op_sel_hi:[1,0,1] neg_lo:[0,0,1]
	ds_write_b64 v5, v[112:113] offset:2376
	s_waitcnt lgkmcnt(3)
	v_pk_mul_f32 v[168:169], v[120:121], v[178:179] op_sel:[1,1] op_sel_hi:[0,1]
	v_pk_fma_f32 v[120:121], v[120:121], v[178:179], v[168:169] op_sel_hi:[1,0,1] neg_lo:[0,0,1]
	ds_write_b64 v5, v[120:121] offset:2640
	s_waitcnt lgkmcnt(3)
	v_pk_mul_f32 v[188:189], v[128:129], v[184:185] op_sel:[1,1] op_sel_hi:[0,1]
	v_pk_fma_f32 v[128:129], v[128:129], v[184:185], v[188:189] op_sel_hi:[1,0,1] neg_lo:[0,0,1]
	ds_write_b64 v5, v[128:129] offset:2904
	s_waitcnt lgkmcnt(3)
	v_pk_mul_f32 v[186:187], v[106:107], v[102:103] op_sel:[1,1] op_sel_hi:[0,1]
	v_pk_fma_f32 v[106:107], v[106:107], v[102:103], v[186:187] op_sel_hi:[1,0,1] neg_lo:[0,0,1]
	ds_write_b64 v5, v[106:107] offset:3168
	ds_read_b64 v[174:175], v56 offset:3328
	ds_read_b64 v[166:167], v56 offset:3584
	ds_read_b64 v[180:181], v56 offset:3840
	s_waitcnt lgkmcnt(2)
	v_pk_mul_f32 v[168:169], v[114:115], v[174:175] op_sel:[1,1] op_sel_hi:[0,1]
	v_pk_fma_f32 v[114:115], v[114:115], v[174:175], v[168:169] op_sel_hi:[1,0,1] neg_lo:[0,0,1]
	ds_write_b64 v5, v[114:115] offset:3432
	s_waitcnt lgkmcnt(2)
	v_pk_mul_f32 v[188:189], v[122:123], v[166:167] op_sel:[1,1] op_sel_hi:[0,1]
	v_pk_fma_f32 v[122:123], v[122:123], v[166:167], v[188:189] op_sel_hi:[1,0,1] neg_lo:[0,0,1]
	ds_write_b64 v5, v[122:123] offset:3696
	s_waitcnt lgkmcnt(2)
	v_pk_mul_f32 v[186:187], v[130:131], v[180:181] op_sel:[1,1] op_sel_hi:[0,1]
	v_pk_fma_f32 v[130:131], v[130:131], v[180:181], v[186:187] op_sel_hi:[1,0,1] neg_lo:[0,0,1]
	ds_write_b64 v5, v[130:131] offset:3960
	s_waitcnt lgkmcnt(0)
	ds_read_b64 v[100:101], v156
	ds_read_b64 v[176:177], v156 offset:128
	ds_read_b64 v[108:109], v156 offset:8
	ds_read_b64 v[178:179], v156 offset:136
	ds_read_b64 v[116:117], v156 offset:16
	ds_read_b64 v[184:185], v156 offset:144
	ds_read_b64 v[124:125], v156 offset:24
	ds_read_b64 v[102:103], v156 offset:152
	s_waitcnt lgkmcnt(6)
	v_pk_fma_f32 v[100:101], v[176:177], v[190:191], v[100:101] op_sel_hi:[1,0,1]
	s_waitcnt lgkmcnt(4)
	v_pk_fma_f32 v[108:109], v[178:179], v[190:191], v[108:109] op_sel_hi:[1,0,1]
	v_pk_mul_f32 v[168:169], v[108:109], v[36:37] op_sel:[1,1] op_sel_hi:[0,1]
	v_pk_fma_f32 v[108:109], v[108:109], v[36:37], v[168:169] op_sel_hi:[1,0,1] neg_lo:[0,0,1]
	s_waitcnt lgkmcnt(2)
	v_pk_fma_f32 v[116:117], v[184:185], v[190:191], v[116:117] op_sel_hi:[1,0,1]
	v_pk_mul_f32 v[188:189], v[116:117], v[38:39] op_sel:[1,1] op_sel_hi:[0,1]
	v_pk_fma_f32 v[116:117], v[116:117], v[38:39], v[188:189] op_sel_hi:[1,0,1] neg_lo:[0,0,1]
	s_waitcnt lgkmcnt(0)
	v_pk_fma_f32 v[124:125], v[102:103], v[190:191], v[124:125] op_sel_hi:[1,0,1]
	v_pk_mul_f32 v[186:187], v[124:125], v[40:41] op_sel:[1,1] op_sel_hi:[0,1]
	v_pk_fma_f32 v[124:125], v[124:125], v[40:41], v[186:187] op_sel_hi:[1,0,1] neg_lo:[0,0,1]
	ds_read_b64 v[126:127], v156 offset:32
	ds_read_b64 v[174:175], v156 offset:160
	ds_read_b64 v[118:119], v156 offset:40
	ds_read_b64 v[166:167], v156 offset:168
	ds_read_b64 v[182:183], v156 offset:48
	ds_read_b64 v[180:181], v156 offset:176
	ds_read_b64 v[110:111], v156 offset:56
	ds_read_b64 v[168:169], v156 offset:184
	s_waitcnt lgkmcnt(6)
	v_pk_fma_f32 v[126:127], v[174:175], v[190:191], v[126:127] op_sel_hi:[1,0,1]
	v_pk_mul_f32 v[188:189], v[126:127], v[42:43] op_sel:[1,1] op_sel_hi:[0,1]
	v_pk_fma_f32 v[126:127], v[126:127], v[42:43], v[188:189] op_sel_hi:[1,0,1] neg_lo:[0,0,1]
	s_waitcnt lgkmcnt(4)
	v_pk_fma_f32 v[118:119], v[166:167], v[190:191], v[118:119] op_sel_hi:[1,0,1]
	v_pk_mul_f32 v[186:187], v[118:119], v[44:45] op_sel:[1,1] op_sel_hi:[0,1]
	v_pk_fma_f32 v[118:119], v[118:119], v[44:45], v[186:187] op_sel_hi:[1,0,1] neg_lo:[0,0,1]
	s_waitcnt lgkmcnt(2)
	v_pk_fma_f32 v[182:183], v[180:181], v[190:191], v[182:183] op_sel_hi:[1,0,1]
	v_pk_mul_f32 v[176:177], v[182:183], v[46:47] op_sel:[1,1] op_sel_hi:[0,1]
	v_pk_fma_f32 v[182:183], v[182:183], v[46:47], v[176:177] op_sel_hi:[1,0,1] neg_lo:[0,0,1]
	s_waitcnt lgkmcnt(0)
	v_pk_fma_f32 v[110:111], v[168:169], v[190:191], v[110:111] op_sel_hi:[1,0,1]
	v_pk_mul_f32 v[178:179], v[110:111], v[48:49] op_sel:[1,1] op_sel_hi:[0,1]
	v_pk_fma_f32 v[110:111], v[110:111], v[48:49], v[178:179] op_sel_hi:[1,0,1] neg_lo:[0,0,1]
	ds_read_b64 v[104:105], v156 offset:64
	ds_read_b64 v[184:185], v156 offset:192
	ds_read_b64 v[112:113], v156 offset:72
	ds_read_b64 v[102:103], v156 offset:200
	ds_read_b64 v[120:121], v156 offset:80
	ds_read_b64 v[188:189], v156 offset:208
	ds_read_b64 v[128:129], v156 offset:88
	ds_read_b64 v[186:187], v156 offset:216
	s_waitcnt lgkmcnt(6)
; __device__ __forceinline__ f32x2 cmul(f32x2 a, f32x2 b) { return (f32x2){a.x * b.x - a.y * b.y, a.x * b.y + a.y * b.x}; }
; template <bool INV> __device__ __forceinline__ f32x2 cmul_tw(f32x2 a, f32x2 w) { return INV ? cmulc(a, w) : cmul(a, w); }
; template <bool INV> __device__ __forceinline__ void dft16(f32x2 (&x)[16]) {
;     constexpr float C1 = 0.92387953251128674f, S1 = 0.38268343236508977f, C2 = 0.70710678118654752f;
; #pragma unroll
;     for (int b = 0; b < 4; ++b) dft4<INV>(x[b], x[4 + b], x[8 + b], x[12 + b]);
;     const f32x2 w1 = {C1, -S1}, w2 = {C2, -C2}, w3 = {S1, -C1}, w4 = {0.f, -1.f}, w6 = {-C2, -C2}, w9 = {-C1, S1};
;     x[4 * 1 + 1] = cmul_tw<INV>(x[5], w1); x[4 * 1 + 2] = cmul_tw<INV>(x[6], w2); x[4 * 1 + 3] = cmul_tw<INV>(x[7], w3);
;     x[4 * 2 + 1] = cmul_tw<INV>(x[9], w2); x[4 * 2 + 2] = cmul_tw<INV>(x[10], w4); x[4 * 2 + 3] = cmul_tw<INV>(x[11], w6);
;     x[4 * 3 + 1] = cmul_tw<INV>(x[13], w3); x[4 * 3 + 2] = cmul_tw<INV>(x[14], w6); x[4 * 3 + 3] = cmul_tw<INV>(x[15], w9);
; #pragma unroll
;     for (int c = 0; c < 4; ++c) dft4<INV>(x[4 * c], x[4 * c + 1], x[4 * c + 2], x[4 * c + 3]);
;     f32x2 y[16];
; #pragma unroll
;     for (int k = 0; k < 16; ++k) y[k] = x[4 * (k & 3) + (k >> 2)];
; #pragma unroll
;     for (int k = 0; k < 16; ++k) x[k] = y[k];
; }
; template <int MODE> __device__ __forceinline__ void fft_pair32(LAS f32x2* B, const LAS f32x2* F, int wave, int lane) {
;     ...
;     for (int j = 0; j < 16; ++j) { const f32x2 d = p[j] + p[j + 16] * sg;
;         const f32x2 w = {hi ? CS[j] : 1.f, hi ? -SN[j] : 0.f}; v[j] = j == 0 ? d : cmul(d, w); }
;     dft16<false>(v);
	v_pk_fma_f32 v[104:105], v[184:185], v[190:191], v[104:105] op_sel_hi:[1,0,1]
	v_pk_mul_f32 v[176:177], v[104:105], v[50:51] op_sel:[1,1] op_sel_hi:[0,1]
	v_pk_fma_f32 v[104:105], v[104:105], v[50:51], v[176:177] op_sel_hi:[1,0,1] neg_lo:[0,0,1]
	s_waitcnt lgkmcnt(4)
	v_pk_fma_f32 v[112:113], v[102:103], v[190:191], v[112:113] op_sel_hi:[1,0,1]
	v_pk_mul_f32 v[178:179], v[112:113], v[52:53] op_sel:[1,1] op_sel_hi:[0,1]
	v_pk_fma_f32 v[112:113], v[112:113], v[52:53], v[178:179] op_sel_hi:[1,0,1] neg_lo:[0,0,1]
	s_waitcnt lgkmcnt(2)
	v_pk_fma_f32 v[120:121], v[188:189], v[190:191], v[120:121] op_sel_hi:[1,0,1]
	v_pk_mul_f32 v[174:175], v[120:121], v[54:55] op_sel:[1,1] op_sel_hi:[0,1]
	v_pk_fma_f32 v[120:121], v[120:121], v[54:55], v[174:175] op_sel_hi:[1,0,1] neg_lo:[0,0,1]
	s_waitcnt lgkmcnt(0)
	v_pk_fma_f32 v[128:129], v[186:187], v[190:191], v[128:129] op_sel_hi:[1,0,1]
	v_pk_mul_f32 v[166:167], v[128:129], v[90:91] op_sel:[1,1] op_sel_hi:[0,1]
	v_pk_fma_f32 v[128:129], v[128:129], v[90:91], v[166:167] op_sel_hi:[1,0,1] neg_lo:[0,0,1]
	ds_read_b64 v[106:107], v156 offset:96
	ds_read_b64 v[180:181], v156 offset:224
	ds_read_b64 v[114:115], v156 offset:104
	ds_read_b64 v[168:169], v156 offset:232
	ds_read_b64 v[122:123], v156 offset:112
	ds_read_b64 v[176:177], v156 offset:240
	ds_read_b64 v[130:131], v156 offset:120
	ds_read_b64 v[178:179], v156 offset:248
	s_waitcnt lgkmcnt(6)
	v_pk_fma_f32 v[106:107], v[180:181], v[190:191], v[106:107] op_sel_hi:[1,0,1]
	v_pk_mul_f32 v[174:175], v[106:107], v[92:93] op_sel:[1,1] op_sel_hi:[0,1]
	v_pk_fma_f32 v[106:107], v[106:107], v[92:93], v[174:175] op_sel_hi:[1,0,1] neg_lo:[0,0,1]
	s_waitcnt lgkmcnt(4)
	v_pk_fma_f32 v[114:115], v[168:169], v[190:191], v[114:115] op_sel_hi:[1,0,1]
	v_pk_mul_f32 v[166:167], v[114:115], v[94:95] op_sel:[1,1] op_sel_hi:[0,1]
	v_pk_fma_f32 v[114:115], v[114:115], v[94:95], v[166:167] op_sel_hi:[1,0,1] neg_lo:[0,0,1]
	s_waitcnt lgkmcnt(2)
	v_pk_fma_f32 v[122:123], v[176:177], v[190:191], v[122:123] op_sel_hi:[1,0,1]
	v_pk_mul_f32 v[184:185], v[122:123], v[96:97] op_sel:[1,1] op_sel_hi:[0,1]
	v_pk_fma_f32 v[122:123], v[122:123], v[96:97], v[184:185] op_sel_hi:[1,0,1] neg_lo:[0,0,1]
	s_waitcnt lgkmcnt(0)
	v_pk_fma_f32 v[130:131], v[178:179], v[190:191], v[130:131] op_sel_hi:[1,0,1]
	v_pk_mul_f32 v[102:103], v[130:131], v[98:99] op_sel:[1,1] op_sel_hi:[0,1]
	v_pk_fma_f32 v[130:131], v[130:131], v[98:99], v[102:103] op_sel_hi:[1,0,1] neg_lo:[0,0,1]
	v_pk_add_f32 v[188:189], v[100:101], v[104:105]
	v_pk_add_f32 v[186:187], v[100:101], v[104:105] neg_lo:[0,1] neg_hi:[0,1]
	v_pk_add_f32 v[174:175], v[126:127], v[106:107]
	v_pk_add_f32 v[166:167], v[126:127], v[106:107] neg_lo:[0,1] neg_hi:[0,1]
	v_pk_add_f32 v[100:101], v[188:189], v[174:175]
	v_pk_add_f32 v[104:105], v[188:189], v[174:175] neg_lo:[0,1] neg_hi:[0,1]
	v_pk_add_f32 v[126:127], v[186:187], v[166:167] op_sel:[0,1] op_sel_hi:[1,0] neg_hi:[0,1]
	v_pk_add_f32 v[106:107], v[186:187], v[166:167] op_sel:[0,1] op_sel_hi:[1,0] neg_lo:[0,1]
	v_pk_add_f32 v[184:185], v[108:109], v[112:113]
	v_pk_add_f32 v[102:103], v[108:109], v[112:113] neg_lo:[0,1] neg_hi:[0,1]
	v_pk_add_f32 v[180:181], v[118:119], v[114:115]
	v_pk_add_f32 v[168:169], v[118:119], v[114:115] neg_lo:[0,1] neg_hi:[0,1]
	v_pk_add_f32 v[108:109], v[184:185], v[180:181]
	v_pk_add_f32 v[112:113], v[184:185], v[180:181] neg_lo:[0,1] neg_hi:[0,1]
	v_pk_add_f32 v[118:119], v[102:103], v[168:169] op_sel:[0,1] op_sel_hi:[1,0] neg_hi:[0,1]
	v_pk_add_f32 v[114:115], v[102:103], v[168:169] op_sel:[0,1] op_sel_hi:[1,0] neg_lo:[0,1]
	v_pk_add_f32 v[176:177], v[116:117], v[120:121]
	v_pk_add_f32 v[178:179], v[116:117], v[120:121] neg_lo:[0,1] neg_hi:[0,1]
	v_pk_add_f32 v[188:189], v[182:183], v[122:123]
	v_pk_add_f32 v[186:187], v[182:183], v[122:123] neg_lo:[0,1] neg_hi:[0,1]
	v_pk_add_f32 v[116:117], v[176:177], v[188:189]
	v_pk_add_f32 v[120:121], v[176:177], v[188:189] neg_lo:[0,1] neg_hi:[0,1]
	v_pk_add_f32 v[182:183], v[178:179], v[186:187] op_sel:[0,1] op_sel_hi:[1,0] neg_hi:[0,1]
	v_pk_add_f32 v[122:123], v[178:179], v[186:187] op_sel:[0,1] op_sel_hi:[1,0] neg_lo:[0,1]
	v_pk_add_f32 v[174:175], v[124:125], v[128:129]
	v_pk_add_f32 v[166:167], v[124:125], v[128:129] neg_lo:[0,1] neg_hi:[0,1]
	v_pk_add_f32 v[184:185], v[110:111], v[130:131]
	v_pk_add_f32 v[102:103], v[110:111], v[130:131] neg_lo:[0,1] neg_hi:[0,1]
	v_pk_add_f32 v[124:125], v[174:175], v[184:185]
	v_pk_add_f32 v[128:129], v[174:175], v[184:185] neg_lo:[0,1] neg_hi:[0,1]
	v_pk_add_f32 v[110:111], v[166:167], v[102:103] op_sel:[0,1] op_sel_hi:[1,0] neg_hi:[0,1]
	v_pk_add_f32 v[130:131], v[166:167], v[102:103] op_sel:[0,1] op_sel_hi:[1,0] neg_lo:[0,1]
	v_pk_mul_f32 v[180:181], v[118:119], s[68:69] op_sel:[1,1] op_sel_hi:[0,1]
	v_pk_fma_f32 v[118:119], v[118:119], s[68:69], v[180:181] op_sel_hi:[1,0,1] neg_lo:[0,0,1]
	v_pk_mul_f32 v[168:169], v[182:183], s[84:85] op_sel:[1,1] op_sel_hi:[0,1]
	v_pk_fma_f32 v[182:183], v[182:183], s[84:85], v[168:169] op_sel_hi:[1,0,1] neg_lo:[0,0,1]
	v_pk_mul_f32 v[176:177], v[110:111], s[88:89] op_sel:[1,1] op_sel_hi:[0,1]
	v_pk_fma_f32 v[110:111], v[110:111], s[88:89], v[176:177] op_sel_hi:[1,0,1] neg_lo:[0,0,1]
	v_pk_mul_f32 v[178:179], v[112:113], s[84:85] op_sel:[1,1] op_sel_hi:[0,1]
	v_pk_fma_f32 v[112:113], v[112:113], s[84:85], v[178:179] op_sel_hi:[1,0,1] neg_lo:[0,0,1]
	v_pk_mul_f32 v[188:189], v[128:129], s[90:91] op_sel:[1,1] op_sel_hi:[0,1]
	v_pk_fma_f32 v[128:129], v[128:129], s[90:91], v[188:189] op_sel_hi:[1,0,1] neg_lo:[0,0,1]
	v_pk_mul_f32 v[186:187], v[114:115], s[88:89] op_sel:[1,1] op_sel_hi:[0,1]
	v_pk_fma_f32 v[114:115], v[114:115], s[88:89], v[186:187] op_sel_hi:[1,0,1] neg_lo:[0,0,1]
; #define LAS __attribute__((address_space(3)))
; __device__ __forceinline__ f32x2 cmul(f32x2 a, f32x2 b) { return (f32x2){a.x * b.x - a.y * b.y, a.x * b.y + a.y * b.x}; }
; template <int MODE> __device__ __forceinline__ void fft_pair32(LAS f32x2* B, const LAS f32x2* F, int wave, int lane) {
;     ...
;     const int k1 = blk >> 4, k2 = blk & 15, kb1 = (16 - k1) & 15, b1 = k1 != 0 ? 1 : 0, kb2 = (16 - k2 - b1) & 15, b2 = (k2 != 0 || b1) ? 1 : 0;
;     const LAS f32x2* fa = F + 33 * blk; const LAS f32x2* fb = F + 33 * (16 * kb1 + kb2);
;     const LAS f32x2* fah = fa + hi; const LAS f32x2* fbh = fb + (1 - b2) - hi;
;     constexpr float SC = 1.0f / (2.0f * (float)FN);
; #pragma unroll
;     for (int k = 0; k < 16; ++k) { const f32x2 A = fah[2 * k]; f32x2 Bm = fbh[31 - 2 * k];
;         if (k == 0) { const f32x2 m0 = b2 ? fb[31] : fa[0]; Bm = hi ? Bm : m0; }
;         const f32x2 H = MODE == 0 ? (f32x2){(A.x + Bm.x) * SC, (A.y - Bm.y) * SC} : (f32x2){(A.y + Bm.y) * SC, (Bm.x - A.x) * SC};
;         v[k] = cmul(v[k], H); }
	v_pk_mul_f32 v[174:175], v[122:123], s[90:91] op_sel:[1,1] op_sel_hi:[0,1]
	v_pk_fma_f32 v[122:123], v[122:123], s[90:91], v[174:175] op_sel_hi:[1,0,1] neg_lo:[0,0,1]
	v_pk_mul_f32 v[166:167], v[130:131], s[98:99] op_sel:[1,1] op_sel_hi:[0,1]
	v_pk_fma_f32 v[130:131], v[130:131], s[98:99], v[166:167] op_sel_hi:[1,0,1] neg_lo:[0,0,1]
	v_pk_add_f32 v[184:185], v[100:101], v[116:117]
	v_pk_add_f32 v[102:103], v[100:101], v[116:117] neg_lo:[0,1] neg_hi:[0,1]
	v_pk_add_f32 v[180:181], v[108:109], v[124:125]
	v_pk_add_f32 v[168:169], v[108:109], v[124:125] neg_lo:[0,1] neg_hi:[0,1]
	v_pk_add_f32 v[100:101], v[184:185], v[180:181]
	v_pk_add_f32 v[116:117], v[184:185], v[180:181] neg_lo:[0,1] neg_hi:[0,1]
	v_pk_add_f32 v[108:109], v[102:103], v[168:169] op_sel:[0,1] op_sel_hi:[1,0] neg_hi:[0,1]
	v_pk_add_f32 v[124:125], v[102:103], v[168:169] op_sel:[0,1] op_sel_hi:[1,0] neg_lo:[0,1]
	v_pk_add_f32 v[176:177], v[126:127], v[182:183]
	v_pk_add_f32 v[178:179], v[126:127], v[182:183] neg_lo:[0,1] neg_hi:[0,1]
	v_pk_add_f32 v[188:189], v[118:119], v[110:111]
	v_pk_add_f32 v[186:187], v[118:119], v[110:111] neg_lo:[0,1] neg_hi:[0,1]
	v_pk_add_f32 v[126:127], v[176:177], v[188:189]
	v_pk_add_f32 v[182:183], v[176:177], v[188:189] neg_lo:[0,1] neg_hi:[0,1]
	v_pk_add_f32 v[118:119], v[178:179], v[186:187] op_sel:[0,1] op_sel_hi:[1,0] neg_hi:[0,1]
	v_pk_add_f32 v[110:111], v[178:179], v[186:187] op_sel:[0,1] op_sel_hi:[1,0] neg_lo:[0,1]
	v_pk_add_f32 v[174:175], v[104:105], v[120:121] op_sel:[0,1] op_sel_hi:[1,0] neg_hi:[0,1]
	v_pk_add_f32 v[166:167], v[104:105], v[120:121] op_sel:[0,1] op_sel_hi:[1,0] neg_lo:[0,1]
	v_pk_add_f32 v[184:185], v[112:113], v[128:129]
	v_pk_add_f32 v[102:103], v[112:113], v[128:129] neg_lo:[0,1] neg_hi:[0,1]
	v_pk_add_f32 v[104:105], v[174:175], v[184:185]
	v_pk_add_f32 v[120:121], v[174:175], v[184:185] neg_lo:[0,1] neg_hi:[0,1]
	v_pk_add_f32 v[112:113], v[166:167], v[102:103] op_sel:[0,1] op_sel_hi:[1,0] neg_hi:[0,1]
	v_pk_add_f32 v[128:129], v[166:167], v[102:103] op_sel:[0,1] op_sel_hi:[1,0] neg_lo:[0,1]
	v_pk_add_f32 v[180:181], v[106:107], v[122:123]
	v_pk_add_f32 v[168:169], v[106:107], v[122:123] neg_lo:[0,1] neg_hi:[0,1]
	v_pk_add_f32 v[176:177], v[114:115], v[130:131]
	v_pk_add_f32 v[178:179], v[114:115], v[130:131] neg_lo:[0,1] neg_hi:[0,1]
	v_pk_add_f32 v[106:107], v[180:181], v[176:177]
	v_pk_add_f32 v[122:123], v[180:181], v[176:177] neg_lo:[0,1] neg_hi:[0,1]
	v_pk_add_f32 v[114:115], v[168:169], v[178:179] op_sel:[0,1] op_sel_hi:[1,0] neg_hi:[0,1]
	v_pk_add_f32 v[130:131], v[168:169], v[178:179] op_sel:[0,1] op_sel_hi:[1,0] neg_lo:[0,1]
	ds_read_b64 v[188:189], v200
	ds_read_b64 v[184:185], v204
	ds_read_b64 v[186:187], v200 offset:16
	ds_read_b64 v[102:103], v202 offset:232
	ds_read_b64 v[174:175], v200 offset:32
	ds_read_b64 v[180:181], v202 offset:216
	ds_read_b64 v[166:167], v200 offset:48
	ds_read_b64 v[168:169], v202 offset:200
	s_waitcnt lgkmcnt(6)
	v_pk_add_f32 v[188:189], v[188:189], v[184:185] op_sel:[1,1] op_sel_hi:[0,0] neg_hi:[1,0]
	v_pk_mul_f32 v[176:177], v[100:101], v[188:189] op_sel:[1,1] op_sel_hi:[0,1]
	v_pk_fma_f32 v[100:101], v[100:101], v[188:189], v[176:177] op_sel_hi:[1,0,1] neg_lo:[0,0,1]
	s_waitcnt lgkmcnt(4)
	v_pk_add_f32 v[186:187], v[186:187], v[102:103] op_sel:[1,1] op_sel_hi:[0,0] neg_hi:[1,0]
	v_pk_mul_f32 v[178:179], v[126:127], v[186:187] op_sel:[1,1] op_sel_hi:[0,1]
	v_pk_fma_f32 v[126:127], v[126:127], v[186:187], v[178:179] op_sel_hi:[1,0,1] neg_lo:[0,0,1]
	s_waitcnt lgkmcnt(2)
	v_pk_add_f32 v[174:175], v[174:175], v[180:181] op_sel:[1,1] op_sel_hi:[0,0] neg_hi:[1,0]
	v_pk_mul_f32 v[176:177], v[104:105], v[174:175] op_sel:[1,1] op_sel_hi:[0,1]
	v_pk_fma_f32 v[104:105], v[104:105], v[174:175], v[176:177] op_sel_hi:[1,0,1] neg_lo:[0,0,1]
	s_waitcnt lgkmcnt(0)
	v_pk_add_f32 v[166:167], v[166:167], v[168:169] op_sel:[1,1] op_sel_hi:[0,0] neg_hi:[1,0]
	v_pk_mul_f32 v[178:179], v[106:107], v[166:167] op_sel:[1,1] op_sel_hi:[0,1]
	v_pk_fma_f32 v[106:107], v[106:107], v[166:167], v[178:179] op_sel_hi:[1,0,1] neg_lo:[0,0,1]
	ds_read_b64 v[176:177], v200 offset:64
	ds_read_b64 v[174:175], v202 offset:184
	ds_read_b64 v[178:179], v200 offset:80
	ds_read_b64 v[166:167], v202 offset:168
	ds_read_b64 v[188:189], v200 offset:96
	ds_read_b64 v[184:185], v202 offset:152
	ds_read_b64 v[186:187], v200 offset:112
	ds_read_b64 v[102:103], v202 offset:136
	s_waitcnt lgkmcnt(6)
	v_pk_add_f32 v[176:177], v[176:177], v[174:175] op_sel:[1,1] op_sel_hi:[0,0] neg_hi:[1,0]
	v_pk_mul_f32 v[180:181], v[108:109], v[176:177] op_sel:[1,1] op_sel_hi:[0,1]
	v_pk_fma_f32 v[108:109], v[108:109], v[176:177], v[180:181] op_sel_hi:[1,0,1] neg_lo:[0,0,1]
	s_waitcnt lgkmcnt(4)
	v_pk_add_f32 v[178:179], v[178:179], v[166:167] op_sel:[1,1] op_sel_hi:[0,0] neg_hi:[1,0]
	v_pk_mul_f32 v[168:169], v[118:119], v[178:179] op_sel:[1,1] op_sel_hi:[0,1]
	v_pk_fma_f32 v[118:119], v[118:119], v[178:179], v[168:169] op_sel_hi:[1,0,1] neg_lo:[0,0,1]
	s_waitcnt lgkmcnt(2)
	v_pk_add_f32 v[188:189], v[188:189], v[184:185] op_sel:[1,1] op_sel_hi:[0,0] neg_hi:[1,0]
	v_pk_mul_f32 v[180:181], v[112:113], v[188:189] op_sel:[1,1] op_sel_hi:[0,1]
	v_pk_fma_f32 v[112:113], v[112:113], v[188:189], v[180:181] op_sel_hi:[1,0,1] neg_lo:[0,0,1]
	s_waitcnt lgkmcnt(0)
	v_pk_add_f32 v[186:187], v[186:187], v[102:103] op_sel:[1,1] op_sel_hi:[0,0] neg_hi:[1,0]
	v_pk_mul_f32 v[168:169], v[114:115], v[186:187] op_sel:[1,1] op_sel_hi:[0,1]
	v_pk_fma_f32 v[114:115], v[114:115], v[186:187], v[168:169] op_sel_hi:[1,0,1] neg_lo:[0,0,1]
	ds_read_b64 v[180:181], v200 offset:128
	ds_read_b64 v[188:189], v202 offset:120
	ds_read_b64 v[168:169], v200 offset:144
	ds_read_b64 v[186:187], v202 offset:104
	ds_read_b64 v[176:177], v200 offset:160
	ds_read_b64 v[174:175], v202 offset:88
	ds_read_b64 v[178:179], v200 offset:176
	ds_read_b64 v[166:167], v202 offset:72
	s_waitcnt lgkmcnt(6)
; __device__ __forceinline__ f32x2 cmul(f32x2 a, f32x2 b) { return (f32x2){a.x * b.x - a.y * b.y, a.x * b.y + a.y * b.x}; }
; template <bool INV> __device__ __forceinline__ f32x2 cmul_tw(f32x2 a, f32x2 w) { return INV ? cmulc(a, w) : cmul(a, w); }
; template <bool INV> __device__ __forceinline__ void dft16(f32x2 (&x)[16]) {
;     constexpr float C1 = 0.92387953251128674f, S1 = 0.38268343236508977f, C2 = 0.70710678118654752f;
; #pragma unroll
;     for (int b = 0; b < 4; ++b) dft4<INV>(x[b], x[4 + b], x[8 + b], x[12 + b]);
;     const f32x2 w1 = {C1, -S1}, w2 = {C2, -C2}, w3 = {S1, -C1}, w4 = {0.f, -1.f}, w6 = {-C2, -C2}, w9 = {-C1, S1};
;     x[4 * 1 + 1] = cmul_tw<INV>(x[5], w1); x[4 * 1 + 2] = cmul_tw<INV>(x[6], w2); x[4 * 1 + 3] = cmul_tw<INV>(x[7], w3);
;     x[4 * 2 + 1] = cmul_tw<INV>(x[9], w2); x[4 * 2 + 2] = cmul_tw<INV>(x[10], w4); x[4 * 2 + 3] = cmul_tw<INV>(x[11], w6);
;     x[4 * 3 + 1] = cmul_tw<INV>(x[13], w3); x[4 * 3 + 2] = cmul_tw<INV>(x[14], w6); x[4 * 3 + 3] = cmul_tw<INV>(x[15], w9);
; #pragma unroll
;     for (int c = 0; c < 4; ++c) dft4<INV>(x[4 * c], x[4 * c + 1], x[4 * c + 2], x[4 * c + 3]);
;     f32x2 y[16];
; #pragma unroll
;     for (int k = 0; k < 16; ++k) y[k] = x[4 * (k & 3) + (k >> 2)];
; #pragma unroll
;     for (int k = 0; k < 16; ++k) x[k] = y[k];
; }
; template <int MODE> __device__ __forceinline__ void fft_pair32(LAS f32x2* B, const LAS f32x2* F, int wave, int lane) {
;     ...
;     for (int k = 0; k < 16; ++k) { const f32x2 A = fah[2 * k]; f32x2 Bm = fbh[31 - 2 * k];
;         if (k == 0) { const f32x2 m0 = b2 ? fb[31] : fa[0]; Bm = hi ? Bm : m0; }
;         const f32x2 H = MODE == 0 ? (f32x2){(A.x + Bm.x) * SC, (A.y - Bm.y) * SC} : (f32x2){(A.y + Bm.y) * SC, (Bm.x - A.x) * SC};
;         v[k] = cmul(v[k], H); }
;     dft16<true>(v);
	v_pk_add_f32 v[180:181], v[180:181], v[188:189] op_sel:[1,1] op_sel_hi:[0,0] neg_hi:[1,0]
	v_pk_mul_f32 v[184:185], v[116:117], v[180:181] op_sel:[1,1] op_sel_hi:[0,1]
	v_pk_fma_f32 v[116:117], v[116:117], v[180:181], v[184:185] op_sel_hi:[1,0,1] neg_lo:[0,0,1]
	s_waitcnt lgkmcnt(4)
	v_pk_add_f32 v[168:169], v[168:169], v[186:187] op_sel:[1,1] op_sel_hi:[0,0] neg_hi:[1,0]
	v_pk_mul_f32 v[102:103], v[182:183], v[168:169] op_sel:[1,1] op_sel_hi:[0,1]
	v_pk_fma_f32 v[182:183], v[182:183], v[168:169], v[102:103] op_sel_hi:[1,0,1] neg_lo:[0,0,1]
	s_waitcnt lgkmcnt(2)
	v_pk_add_f32 v[176:177], v[176:177], v[174:175] op_sel:[1,1] op_sel_hi:[0,0] neg_hi:[1,0]
	v_pk_mul_f32 v[184:185], v[120:121], v[176:177] op_sel:[1,1] op_sel_hi:[0,1]
	v_pk_fma_f32 v[120:121], v[120:121], v[176:177], v[184:185] op_sel_hi:[1,0,1] neg_lo:[0,0,1]
	s_waitcnt lgkmcnt(0)
	v_pk_add_f32 v[178:179], v[178:179], v[166:167] op_sel:[1,1] op_sel_hi:[0,0] neg_hi:[1,0]
	v_pk_mul_f32 v[102:103], v[122:123], v[178:179] op_sel:[1,1] op_sel_hi:[0,1]
	v_pk_fma_f32 v[122:123], v[122:123], v[178:179], v[102:103] op_sel_hi:[1,0,1] neg_lo:[0,0,1]
	ds_read_b64 v[184:185], v200 offset:192
	ds_read_b64 v[176:177], v202 offset:56
	ds_read_b64 v[102:103], v200 offset:208
	ds_read_b64 v[178:179], v202 offset:40
	ds_read_b64 v[180:181], v200 offset:224
	ds_read_b64 v[188:189], v202 offset:24
	ds_read_b64 v[168:169], v200 offset:240
	ds_read_b64 v[186:187], v202 offset:8
	s_waitcnt lgkmcnt(6)
	v_pk_add_f32 v[184:185], v[184:185], v[176:177] op_sel:[1,1] op_sel_hi:[0,0] neg_hi:[1,0]
	v_pk_mul_f32 v[174:175], v[124:125], v[184:185] op_sel:[1,1] op_sel_hi:[0,1]
	v_pk_fma_f32 v[124:125], v[124:125], v[184:185], v[174:175] op_sel_hi:[1,0,1] neg_lo:[0,0,1]
	s_waitcnt lgkmcnt(4)
	v_pk_add_f32 v[102:103], v[102:103], v[178:179] op_sel:[1,1] op_sel_hi:[0,0] neg_hi:[1,0]
	v_pk_mul_f32 v[166:167], v[110:111], v[102:103] op_sel:[1,1] op_sel_hi:[0,1]
	v_pk_fma_f32 v[110:111], v[110:111], v[102:103], v[166:167] op_sel_hi:[1,0,1] neg_lo:[0,0,1]
	s_waitcnt lgkmcnt(2)
	v_pk_add_f32 v[180:181], v[180:181], v[188:189] op_sel:[1,1] op_sel_hi:[0,0] neg_hi:[1,0]
	v_pk_mul_f32 v[174:175], v[128:129], v[180:181] op_sel:[1,1] op_sel_hi:[0,1]
	v_pk_fma_f32 v[128:129], v[128:129], v[180:181], v[174:175] op_sel_hi:[1,0,1] neg_lo:[0,0,1]
	s_waitcnt lgkmcnt(0)
	v_pk_add_f32 v[168:169], v[168:169], v[186:187] op_sel:[1,1] op_sel_hi:[0,0] neg_hi:[1,0]
	v_pk_mul_f32 v[166:167], v[130:131], v[168:169] op_sel:[1,1] op_sel_hi:[0,1]
	v_pk_fma_f32 v[130:131], v[130:131], v[168:169], v[166:167] op_sel_hi:[1,0,1] neg_lo:[0,0,1]
	v_pk_add_f32 v[174:175], v[100:101], v[116:117]
	v_pk_add_f32 v[166:167], v[100:101], v[116:117] neg_lo:[0,1] neg_hi:[0,1]
	v_pk_add_f32 v[184:185], v[108:109], v[124:125]
	v_pk_add_f32 v[102:103], v[108:109], v[124:125] neg_lo:[0,1] neg_hi:[0,1]
	v_pk_add_f32 v[100:101], v[174:175], v[184:185]
	v_pk_add_f32 v[116:117], v[174:175], v[184:185] neg_lo:[0,1] neg_hi:[0,1]
	v_pk_add_f32 v[108:109], v[166:167], v[102:103] op_sel:[0,1] op_sel_hi:[1,0] neg_lo:[0,1]
	v_pk_add_f32 v[124:125], v[166:167], v[102:103] op_sel:[0,1] op_sel_hi:[1,0] neg_hi:[0,1]
	v_pk_add_f32 v[180:181], v[126:127], v[182:183]
	v_pk_add_f32 v[168:169], v[126:127], v[182:183] neg_lo:[0,1] neg_hi:[0,1]
	v_pk_add_f32 v[176:177], v[118:119], v[110:111]
	v_pk_add_f32 v[178:179], v[118:119], v[110:111] neg_lo:[0,1] neg_hi:[0,1]
	v_pk_add_f32 v[126:127], v[180:181], v[176:177]
	v_pk_add_f32 v[182:183], v[180:181], v[176:177] neg_lo:[0,1] neg_hi:[0,1]
	v_pk_add_f32 v[118:119], v[168:169], v[178:179] op_sel:[0,1] op_sel_hi:[1,0] neg_lo:[0,1]
	v_pk_add_f32 v[110:111], v[168:169], v[178:179] op_sel:[0,1] op_sel_hi:[1,0] neg_hi:[0,1]
	v_pk_add_f32 v[188:189], v[104:105], v[120:121]
	v_pk_add_f32 v[186:187], v[104:105], v[120:121] neg_lo:[0,1] neg_hi:[0,1]
	v_pk_add_f32 v[174:175], v[112:113], v[128:129]
	v_pk_add_f32 v[166:167], v[112:113], v[128:129] neg_lo:[0,1] neg_hi:[0,1]
	v_pk_add_f32 v[104:105], v[188:189], v[174:175]
	v_pk_add_f32 v[120:121], v[188:189], v[174:175] neg_lo:[0,1] neg_hi:[0,1]
	v_pk_add_f32 v[112:113], v[186:187], v[166:167] op_sel:[0,1] op_sel_hi:[1,0] neg_lo:[0,1]
	v_pk_add_f32 v[128:129], v[186:187], v[166:167] op_sel:[0,1] op_sel_hi:[1,0] neg_hi:[0,1]
	v_pk_add_f32 v[184:185], v[106:107], v[122:123]
	v_pk_add_f32 v[102:103], v[106:107], v[122:123] neg_lo:[0,1] neg_hi:[0,1]
	v_pk_add_f32 v[180:181], v[114:115], v[130:131]
	v_pk_add_f32 v[168:169], v[114:115], v[130:131] neg_lo:[0,1] neg_hi:[0,1]
	v_pk_add_f32 v[106:107], v[184:185], v[180:181]
	v_pk_add_f32 v[122:123], v[184:185], v[180:181] neg_lo:[0,1] neg_hi:[0,1]
	v_pk_add_f32 v[114:115], v[102:103], v[168:169] op_sel:[0,1] op_sel_hi:[1,0] neg_lo:[0,1]
	v_pk_add_f32 v[130:131], v[102:103], v[168:169] op_sel:[0,1] op_sel_hi:[1,0] neg_hi:[0,1]
	v_pk_mul_f32 v[176:177], v[118:119], s[68:69] op_sel:[1,1] op_sel_hi:[0,1]
	v_pk_fma_f32 v[118:119], v[118:119], s[68:69], v[176:177] op_sel_hi:[1,0,1] neg_hi:[0,0,1]
	v_pk_mul_f32 v[178:179], v[112:113], s[84:85] op_sel:[1,1] op_sel_hi:[0,1]
	v_pk_fma_f32 v[112:113], v[112:113], s[84:85], v[178:179] op_sel_hi:[1,0,1] neg_hi:[0,0,1]
	v_pk_mul_f32 v[188:189], v[114:115], s[88:89] op_sel:[1,1] op_sel_hi:[0,1]
	v_pk_fma_f32 v[114:115], v[114:115], s[88:89], v[188:189] op_sel_hi:[1,0,1] neg_hi:[0,0,1]
	v_pk_mul_f32 v[186:187], v[182:183], s[84:85] op_sel:[1,1] op_sel_hi:[0,1]
	v_pk_fma_f32 v[182:183], v[182:183], s[84:85], v[186:187] op_sel_hi:[1,0,1] neg_hi:[0,0,1]
	v_pk_mul_f32 v[174:175], v[122:123], s[90:91] op_sel:[1,1] op_sel_hi:[0,1]
	v_pk_fma_f32 v[122:123], v[122:123], s[90:91], v[174:175] op_sel_hi:[1,0,1] neg_hi:[0,0,1]
; __device__ __forceinline__ f32x2 cmulc(f32x2 a, f32x2 b) { return (f32x2){a.x * b.x + a.y * b.y, a.y * b.x - a.x * b.y}; }
; template <int MODE> __device__ __forceinline__ void fft_pair32(LAS f32x2* B, const LAS f32x2* F, int wave, int lane) {
;     ...
;     dft16<true>(v);
; #pragma unroll
;     for (int j = 0; j < 16; ++j) { const f32x2 w = {hi ? CS[j] : 1.f, hi ? -SN[j] : 0.f}; const f32x2 u = j == 0 ? v[j] : cmulc(v[j], w);
;         const auto rx = __builtin_amdgcn_permlane32_swap(__float_as_uint(u.x), __float_as_uint(u.x), false, false);
;         const auto ry = __builtin_amdgcn_permlane32_swap(__float_as_uint(u.y), __float_as_uint(u.y), false, false);
;         const f32x2 a = {__uint_as_float(rx[0]), __uint_as_float(ry[0])}, b = {__uint_as_float(rx[1]), __uint_as_float(ry[1])};
;         p[16 * hi + j] = a + b * sg; }
	v_pk_mul_f32 v[166:167], v[110:111], s[88:89] op_sel:[1,1] op_sel_hi:[0,1]
	v_pk_fma_f32 v[110:111], v[110:111], s[88:89], v[166:167] op_sel_hi:[1,0,1] neg_hi:[0,0,1]
	v_pk_mul_f32 v[184:185], v[128:129], s[90:91] op_sel:[1,1] op_sel_hi:[0,1]
	v_pk_fma_f32 v[128:129], v[128:129], s[90:91], v[184:185] op_sel_hi:[1,0,1] neg_hi:[0,0,1]
	v_pk_mul_f32 v[102:103], v[130:131], s[98:99] op_sel:[1,1] op_sel_hi:[0,1]
	v_pk_fma_f32 v[130:131], v[130:131], s[98:99], v[102:103] op_sel_hi:[1,0,1] neg_hi:[0,0,1]
	v_pk_add_f32 v[180:181], v[100:101], v[104:105]
	v_pk_add_f32 v[168:169], v[100:101], v[104:105] neg_lo:[0,1] neg_hi:[0,1]
	v_pk_add_f32 v[176:177], v[126:127], v[106:107]
	v_pk_add_f32 v[178:179], v[126:127], v[106:107] neg_lo:[0,1] neg_hi:[0,1]
	v_pk_add_f32 v[100:101], v[180:181], v[176:177]
	v_pk_add_f32 v[104:105], v[180:181], v[176:177] neg_lo:[0,1] neg_hi:[0,1]
	v_pk_add_f32 v[126:127], v[168:169], v[178:179] op_sel:[0,1] op_sel_hi:[1,0] neg_lo:[0,1]
	v_pk_add_f32 v[106:107], v[168:169], v[178:179] op_sel:[0,1] op_sel_hi:[1,0] neg_hi:[0,1]
	v_pk_add_f32 v[188:189], v[108:109], v[112:113]
	v_pk_add_f32 v[186:187], v[108:109], v[112:113] neg_lo:[0,1] neg_hi:[0,1]
	v_pk_add_f32 v[174:175], v[118:119], v[114:115]
	v_pk_add_f32 v[166:167], v[118:119], v[114:115] neg_lo:[0,1] neg_hi:[0,1]
	v_pk_add_f32 v[108:109], v[188:189], v[174:175]
	v_pk_add_f32 v[112:113], v[188:189], v[174:175] neg_lo:[0,1] neg_hi:[0,1]
	v_pk_add_f32 v[118:119], v[186:187], v[166:167] op_sel:[0,1] op_sel_hi:[1,0] neg_lo:[0,1]
	v_pk_add_f32 v[114:115], v[186:187], v[166:167] op_sel:[0,1] op_sel_hi:[1,0] neg_hi:[0,1]
	v_pk_add_f32 v[184:185], v[116:117], v[120:121] op_sel:[0,1] op_sel_hi:[1,0] neg_lo:[0,1]
	v_pk_add_f32 v[102:103], v[116:117], v[120:121] op_sel:[0,1] op_sel_hi:[1,0] neg_hi:[0,1]
	v_pk_add_f32 v[180:181], v[182:183], v[122:123]
	v_pk_add_f32 v[168:169], v[182:183], v[122:123] neg_lo:[0,1] neg_hi:[0,1]
	v_pk_add_f32 v[116:117], v[184:185], v[180:181]
	v_pk_add_f32 v[120:121], v[184:185], v[180:181] neg_lo:[0,1] neg_hi:[0,1]
	v_pk_add_f32 v[182:183], v[102:103], v[168:169] op_sel:[0,1] op_sel_hi:[1,0] neg_lo:[0,1]
	v_pk_add_f32 v[122:123], v[102:103], v[168:169] op_sel:[0,1] op_sel_hi:[1,0] neg_hi:[0,1]
	v_pk_add_f32 v[176:177], v[124:125], v[128:129]
	v_pk_add_f32 v[178:179], v[124:125], v[128:129] neg_lo:[0,1] neg_hi:[0,1]
	v_pk_add_f32 v[188:189], v[110:111], v[130:131]
	v_pk_add_f32 v[186:187], v[110:111], v[130:131] neg_lo:[0,1] neg_hi:[0,1]
	v_pk_add_f32 v[124:125], v[176:177], v[188:189]
	v_pk_add_f32 v[128:129], v[176:177], v[188:189] neg_lo:[0,1] neg_hi:[0,1]
	v_pk_add_f32 v[110:111], v[178:179], v[186:187] op_sel:[0,1] op_sel_hi:[1,0] neg_lo:[0,1]
	v_pk_add_f32 v[130:131], v[178:179], v[186:187] op_sel:[0,1] op_sel_hi:[1,0] neg_hi:[0,1]
	v_mov_b32_e32 v174, v100
	v_mov_b32_e32 v175, v101
	v_pk_mul_f32 v[180:181], v[108:109], v[36:37] op_sel:[1,1] op_sel_hi:[0,1]
	v_pk_fma_f32 v[166:167], v[108:109], v[36:37], v[180:181] op_sel_hi:[1,0,1] neg_hi:[0,0,1]
	v_pk_fma_f32 v[108:109], v[108:109], v[36:37], v[180:181] op_sel_hi:[1,0,1] neg_hi:[0,0,1]
	v_pk_mul_f32 v[168:169], v[116:117], v[38:39] op_sel:[1,1] op_sel_hi:[0,1]
	v_pk_fma_f32 v[184:185], v[116:117], v[38:39], v[168:169] op_sel_hi:[1,0,1] neg_hi:[0,0,1]
	v_pk_fma_f32 v[116:117], v[116:117], v[38:39], v[168:169] op_sel_hi:[1,0,1] neg_hi:[0,0,1]
	v_pk_mul_f32 v[176:177], v[124:125], v[40:41] op_sel:[1,1] op_sel_hi:[0,1]
	v_pk_fma_f32 v[102:103], v[124:125], v[40:41], v[176:177] op_sel_hi:[1,0,1] neg_hi:[0,0,1]
	v_pk_fma_f32 v[124:125], v[124:125], v[40:41], v[176:177] op_sel_hi:[1,0,1] neg_hi:[0,0,1]
	s_nop 1
	v_permlane32_swap_b32_e32 v100, v174
	v_permlane32_swap_b32_e32 v101, v175
	v_permlane32_swap_b32_e32 v108, v166
	v_permlane32_swap_b32_e32 v109, v167
	v_permlane32_swap_b32_e32 v116, v184
	v_permlane32_swap_b32_e32 v117, v185
	v_permlane32_swap_b32_e32 v124, v102
	v_permlane32_swap_b32_e32 v125, v103
	v_pk_fma_f32 v[100:101], v[174:175], v[190:191], v[100:101] op_sel_hi:[1,0,1]
	ds_write_b64 v198, v[100:101]
	v_pk_fma_f32 v[108:109], v[166:167], v[190:191], v[108:109] op_sel_hi:[1,0,1]
	ds_write_b64 v198, v[108:109] offset:8
	v_pk_fma_f32 v[116:117], v[184:185], v[190:191], v[116:117] op_sel_hi:[1,0,1]
	ds_write_b64 v198, v[116:117] offset:16
	v_pk_fma_f32 v[124:125], v[102:103], v[190:191], v[124:125] op_sel_hi:[1,0,1]
	ds_write_b64 v198, v[124:125] offset:24
	v_pk_mul_f32 v[168:169], v[126:127], v[42:43] op_sel:[1,1] op_sel_hi:[0,1]
	v_pk_fma_f32 v[178:179], v[126:127], v[42:43], v[168:169] op_sel_hi:[1,0,1] neg_hi:[0,0,1]
	v_pk_fma_f32 v[126:127], v[126:127], v[42:43], v[168:169] op_sel_hi:[1,0,1] neg_hi:[0,0,1]
	v_pk_mul_f32 v[176:177], v[118:119], v[44:45] op_sel:[1,1] op_sel_hi:[0,1]
	v_pk_fma_f32 v[188:189], v[118:119], v[44:45], v[176:177] op_sel_hi:[1,0,1] neg_hi:[0,0,1]
	v_pk_fma_f32 v[118:119], v[118:119], v[44:45], v[176:177] op_sel_hi:[1,0,1] neg_hi:[0,0,1]
	v_pk_mul_f32 v[174:175], v[182:183], v[46:47] op_sel:[1,1] op_sel_hi:[0,1]
	v_pk_fma_f32 v[186:187], v[182:183], v[46:47], v[174:175] op_sel_hi:[1,0,1] neg_hi:[0,0,1]
	v_pk_fma_f32 v[182:183], v[182:183], v[46:47], v[174:175] op_sel_hi:[1,0,1] neg_hi:[0,0,1]
	v_pk_mul_f32 v[166:167], v[110:111], v[48:49] op_sel:[1,1] op_sel_hi:[0,1]
	v_pk_fma_f32 v[180:181], v[110:111], v[48:49], v[166:167] op_sel_hi:[1,0,1] neg_hi:[0,0,1]
	v_pk_fma_f32 v[110:111], v[110:111], v[48:49], v[166:167] op_sel_hi:[1,0,1] neg_hi:[0,0,1]
	s_nop 1
	v_permlane32_swap_b32_e32 v126, v178
	v_permlane32_swap_b32_e32 v127, v179
	v_permlane32_swap_b32_e32 v118, v188
	v_permlane32_swap_b32_e32 v119, v189
	v_permlane32_swap_b32_e32 v182, v186
; #define LAS __attribute__((address_space(3)))
; __device__ __forceinline__ f32x2 cmulc(f32x2 a, f32x2 b) { return (f32x2){a.x * b.x + a.y * b.y, a.y * b.x - a.x * b.y}; }
; __device__ __forceinline__ void fft_inv2(LAS f32x2* B, const LAS f32x2* TW2, int tid) {
;     asm volatile("" : "+v"(tid));
;     const int b = tid >> 5, n2 = tid & 31, base = 512 * b + n2; f32x2 x[16];
;     x[0] = B[fpad(base)];
; #pragma unroll
;     for (int k = 1; k < 16; ++k) x[k] = cmulc(B[fpad(base + 32 * k)], TW2[k * 32 + n2]);
;     dft16<true>(x);
; template <int MODE> __device__ __forceinline__ void fft_pair32(LAS f32x2* B, const LAS f32x2* F, int wave, int lane) {
;     ...
;     for (int j = 0; j < 16; ++j) { const f32x2 w = {hi ? CS[j] : 1.f, hi ? -SN[j] : 0.f}; const f32x2 u = j == 0 ? v[j] : cmulc(v[j], w);
;         const auto rx = __builtin_amdgcn_permlane32_swap(__float_as_uint(u.x), __float_as_uint(u.x), false, false);
;         const auto ry = __builtin_amdgcn_permlane32_swap(__float_as_uint(u.y), __float_as_uint(u.y), false, false);
;         const f32x2 a = {__uint_as_float(rx[0]), __uint_as_float(ry[0])}, b = {__uint_as_float(rx[1]), __uint_as_float(ry[1])};
;         p[16 * hi + j] = a + b * sg; }
	v_permlane32_swap_b32_e32 v183, v187
	v_permlane32_swap_b32_e32 v110, v180
	v_permlane32_swap_b32_e32 v111, v181
	v_pk_fma_f32 v[126:127], v[178:179], v[190:191], v[126:127] op_sel_hi:[1,0,1]
	ds_write_b64 v198, v[126:127] offset:32
	v_pk_fma_f32 v[118:119], v[188:189], v[190:191], v[118:119] op_sel_hi:[1,0,1]
	ds_write_b64 v198, v[118:119] offset:40
	v_pk_fma_f32 v[182:183], v[186:187], v[190:191], v[182:183] op_sel_hi:[1,0,1]
	ds_write_b64 v198, v[182:183] offset:48
	v_pk_fma_f32 v[110:111], v[180:181], v[190:191], v[110:111] op_sel_hi:[1,0,1]
	ds_write_b64 v198, v[110:111] offset:56
	v_pk_mul_f32 v[174:175], v[104:105], v[50:51] op_sel:[1,1] op_sel_hi:[0,1]
	v_pk_fma_f32 v[184:185], v[104:105], v[50:51], v[174:175] op_sel_hi:[1,0,1] neg_hi:[0,0,1]
	v_pk_fma_f32 v[104:105], v[104:105], v[50:51], v[174:175] op_sel_hi:[1,0,1] neg_hi:[0,0,1]
	v_pk_mul_f32 v[166:167], v[112:113], v[52:53] op_sel:[1,1] op_sel_hi:[0,1]
	v_pk_fma_f32 v[102:103], v[112:113], v[52:53], v[166:167] op_sel_hi:[1,0,1] neg_hi:[0,0,1]
	v_pk_fma_f32 v[112:113], v[112:113], v[52:53], v[166:167] op_sel_hi:[1,0,1] neg_hi:[0,0,1]
	v_pk_mul_f32 v[178:179], v[120:121], v[54:55] op_sel:[1,1] op_sel_hi:[0,1]
	v_pk_fma_f32 v[168:169], v[120:121], v[54:55], v[178:179] op_sel_hi:[1,0,1] neg_hi:[0,0,1]
	v_pk_fma_f32 v[120:121], v[120:121], v[54:55], v[178:179] op_sel_hi:[1,0,1] neg_hi:[0,0,1]
	v_pk_mul_f32 v[188:189], v[128:129], v[90:91] op_sel:[1,1] op_sel_hi:[0,1]
	v_pk_fma_f32 v[176:177], v[128:129], v[90:91], v[188:189] op_sel_hi:[1,0,1] neg_hi:[0,0,1]
	v_pk_fma_f32 v[128:129], v[128:129], v[90:91], v[188:189] op_sel_hi:[1,0,1] neg_hi:[0,0,1]
	s_nop 1
	v_permlane32_swap_b32_e32 v104, v184
	v_permlane32_swap_b32_e32 v105, v185
	v_permlane32_swap_b32_e32 v112, v102
	v_permlane32_swap_b32_e32 v113, v103
	v_permlane32_swap_b32_e32 v120, v168
	v_permlane32_swap_b32_e32 v121, v169
	v_permlane32_swap_b32_e32 v128, v176
	v_permlane32_swap_b32_e32 v129, v177
	v_pk_fma_f32 v[104:105], v[184:185], v[190:191], v[104:105] op_sel_hi:[1,0,1]
	ds_write_b64 v198, v[104:105] offset:64
	v_pk_fma_f32 v[112:113], v[102:103], v[190:191], v[112:113] op_sel_hi:[1,0,1]
	ds_write_b64 v198, v[112:113] offset:72
	v_pk_fma_f32 v[120:121], v[168:169], v[190:191], v[120:121] op_sel_hi:[1,0,1]
	ds_write_b64 v198, v[120:121] offset:80
	v_pk_fma_f32 v[128:129], v[176:177], v[190:191], v[128:129] op_sel_hi:[1,0,1]
	ds_write_b64 v198, v[128:129] offset:88
	v_pk_mul_f32 v[178:179], v[106:107], v[92:93] op_sel:[1,1] op_sel_hi:[0,1]
	v_pk_fma_f32 v[186:187], v[106:107], v[92:93], v[178:179] op_sel_hi:[1,0,1] neg_hi:[0,0,1]
	v_pk_fma_f32 v[106:107], v[106:107], v[92:93], v[178:179] op_sel_hi:[1,0,1] neg_hi:[0,0,1]
	v_pk_mul_f32 v[188:189], v[114:115], v[94:95] op_sel:[1,1] op_sel_hi:[0,1]
	v_pk_fma_f32 v[180:181], v[114:115], v[94:95], v[188:189] op_sel_hi:[1,0,1] neg_hi:[0,0,1]
	v_pk_fma_f32 v[114:115], v[114:115], v[94:95], v[188:189] op_sel_hi:[1,0,1] neg_hi:[0,0,1]
	v_pk_mul_f32 v[184:185], v[122:123], v[96:97] op_sel:[1,1] op_sel_hi:[0,1]
	v_pk_fma_f32 v[174:175], v[122:123], v[96:97], v[184:185] op_sel_hi:[1,0,1] neg_hi:[0,0,1]
	v_pk_fma_f32 v[122:123], v[122:123], v[96:97], v[184:185] op_sel_hi:[1,0,1] neg_hi:[0,0,1]
	v_pk_mul_f32 v[102:103], v[130:131], v[98:99] op_sel:[1,1] op_sel_hi:[0,1]
	v_pk_fma_f32 v[166:167], v[130:131], v[98:99], v[102:103] op_sel_hi:[1,0,1] neg_hi:[0,0,1]
	v_pk_fma_f32 v[130:131], v[130:131], v[98:99], v[102:103] op_sel_hi:[1,0,1] neg_hi:[0,0,1]
	s_nop 1
	v_permlane32_swap_b32_e32 v106, v186
	v_permlane32_swap_b32_e32 v107, v187
	v_permlane32_swap_b32_e32 v114, v180
	v_permlane32_swap_b32_e32 v115, v181
	v_permlane32_swap_b32_e32 v122, v174
	v_permlane32_swap_b32_e32 v123, v175
	v_permlane32_swap_b32_e32 v130, v166
	v_permlane32_swap_b32_e32 v131, v167
	v_pk_fma_f32 v[106:107], v[186:187], v[190:191], v[106:107] op_sel_hi:[1,0,1]
	ds_write_b64 v198, v[106:107] offset:96
	v_pk_fma_f32 v[114:115], v[180:181], v[190:191], v[114:115] op_sel_hi:[1,0,1]
	ds_write_b64 v198, v[114:115] offset:104
	v_pk_fma_f32 v[122:123], v[174:175], v[190:191], v[122:123] op_sel_hi:[1,0,1]
	ds_write_b64 v198, v[122:123] offset:112
	v_pk_fma_f32 v[130:131], v[166:167], v[190:191], v[130:131] op_sel_hi:[1,0,1]
	ds_write_b64 v198, v[130:131] offset:120
	s_waitcnt lgkmcnt(0)
	ds_read_b64 v[100:101], v5
	ds_read_b64 v[108:109], v5 offset:264
	ds_read_b64 v[168:169], v56 offset:256
	ds_read_b64 v[116:117], v5 offset:528
	ds_read_b64 v[176:177], v56 offset:512
	ds_read_b64 v[124:125], v5 offset:792
	ds_read_b64 v[178:179], v56 offset:768
	ds_read_b64 v[126:127], v5 offset:1056
	ds_read_b64 v[188:189], v56 offset:1024
	ds_read_b64 v[118:119], v5 offset:1320
	ds_read_b64 v[184:185], v56 offset:1280
	s_waitcnt lgkmcnt(8)
	v_pk_mul_f32 v[102:103], v[108:109], v[168:169] op_sel:[1,1] op_sel_hi:[0,1]
	v_pk_fma_f32 v[108:109], v[108:109], v[168:169], v[102:103] op_sel_hi:[1,0,1] neg_hi:[0,0,1]
	s_waitcnt lgkmcnt(6)
	v_pk_mul_f32 v[186:187], v[116:117], v[176:177] op_sel:[1,1] op_sel_hi:[0,1]
	v_pk_fma_f32 v[116:117], v[116:117], v[176:177], v[186:187] op_sel_hi:[1,0,1] neg_hi:[0,0,1]
	s_waitcnt lgkmcnt(4)
	v_pk_mul_f32 v[180:181], v[124:125], v[178:179] op_sel:[1,1] op_sel_hi:[0,1]
	v_pk_fma_f32 v[124:125], v[124:125], v[178:179], v[180:181] op_sel_hi:[1,0,1] neg_hi:[0,0,1]
	s_waitcnt lgkmcnt(2)
	v_pk_mul_f32 v[174:175], v[126:127], v[188:189] op_sel:[1,1] op_sel_hi:[0,1]
	v_pk_fma_f32 v[126:127], v[126:127], v[188:189], v[174:175] op_sel_hi:[1,0,1] neg_hi:[0,0,1]
	s_waitcnt lgkmcnt(0)
; __device__ __forceinline__ f32x2 cmulc(f32x2 a, f32x2 b) { return (f32x2){a.x * b.x + a.y * b.y, a.y * b.x - a.x * b.y}; }
; template <bool INV> __device__ __forceinline__ f32x2 cmul_tw(f32x2 a, f32x2 w) { return INV ? cmulc(a, w) : cmul(a, w); }
; template <bool INV> __device__ __forceinline__ void dft16(f32x2 (&x)[16]) {
;     constexpr float C1 = 0.92387953251128674f, S1 = 0.38268343236508977f, C2 = 0.70710678118654752f;
; #pragma unroll
;     for (int b = 0; b < 4; ++b) dft4<INV>(x[b], x[4 + b], x[8 + b], x[12 + b]);
;     const f32x2 w1 = {C1, -S1}, w2 = {C2, -C2}, w3 = {S1, -C1}, w4 = {0.f, -1.f}, w6 = {-C2, -C2}, w9 = {-C1, S1};
;     x[4 * 1 + 1] = cmul_tw<INV>(x[5], w1); x[4 * 1 + 2] = cmul_tw<INV>(x[6], w2); x[4 * 1 + 3] = cmul_tw<INV>(x[7], w3);
;     x[4 * 2 + 1] = cmul_tw<INV>(x[9], w2); x[4 * 2 + 2] = cmul_tw<INV>(x[10], w4); x[4 * 2 + 3] = cmul_tw<INV>(x[11], w6);
;     x[4 * 3 + 1] = cmul_tw<INV>(x[13], w3); x[4 * 3 + 2] = cmul_tw<INV>(x[14], w6); x[4 * 3 + 3] = cmul_tw<INV>(x[15], w9);
; #pragma unroll
;     for (int c = 0; c < 4; ++c) dft4<INV>(x[4 * c], x[4 * c + 1], x[4 * c + 2], x[4 * c + 3]);
; __device__ __forceinline__ void fft_inv2(LAS f32x2* B, const LAS f32x2* TW2, int tid) {
;     ...
;     x[0] = B[fpad(base)];
; #pragma unroll
;     for (int k = 1; k < 16; ++k) x[k] = cmulc(B[fpad(base + 32 * k)], TW2[k * 32 + n2]);
;     dft16<true>(x);
	v_pk_mul_f32 v[166:167], v[118:119], v[184:185] op_sel:[1,1] op_sel_hi:[0,1]
	v_pk_fma_f32 v[118:119], v[118:119], v[184:185], v[166:167] op_sel_hi:[1,0,1] neg_hi:[0,0,1]
	ds_read_b64 v[182:183], v5 offset:1584
	ds_read_b64 v[102:103], v56 offset:1536
	ds_read_b64 v[110:111], v5 offset:1848
	ds_read_b64 v[186:187], v56 offset:1792
	ds_read_b64 v[104:105], v5 offset:2112
	ds_read_b64 v[180:181], v56 offset:2048
	ds_read_b64 v[112:113], v5 offset:2376
	ds_read_b64 v[174:175], v56 offset:2304
	ds_read_b64 v[120:121], v5 offset:2640
	ds_read_b64 v[166:167], v56 offset:2560
	s_waitcnt lgkmcnt(8)
	v_pk_mul_f32 v[168:169], v[182:183], v[102:103] op_sel:[1,1] op_sel_hi:[0,1]
	v_pk_fma_f32 v[182:183], v[182:183], v[102:103], v[168:169] op_sel_hi:[1,0,1] neg_hi:[0,0,1]
	s_waitcnt lgkmcnt(6)
	v_pk_mul_f32 v[176:177], v[110:111], v[186:187] op_sel:[1,1] op_sel_hi:[0,1]
	v_pk_fma_f32 v[110:111], v[110:111], v[186:187], v[176:177] op_sel_hi:[1,0,1] neg_hi:[0,0,1]
	s_waitcnt lgkmcnt(4)
	v_pk_mul_f32 v[178:179], v[104:105], v[180:181] op_sel:[1,1] op_sel_hi:[0,1]
	v_pk_fma_f32 v[104:105], v[104:105], v[180:181], v[178:179] op_sel_hi:[1,0,1] neg_hi:[0,0,1]
	s_waitcnt lgkmcnt(2)
	v_pk_mul_f32 v[188:189], v[112:113], v[174:175] op_sel:[1,1] op_sel_hi:[0,1]
	v_pk_fma_f32 v[112:113], v[112:113], v[174:175], v[188:189] op_sel_hi:[1,0,1] neg_hi:[0,0,1]
	s_waitcnt lgkmcnt(0)
	v_pk_mul_f32 v[184:185], v[120:121], v[166:167] op_sel:[1,1] op_sel_hi:[0,1]
	v_pk_fma_f32 v[120:121], v[120:121], v[166:167], v[184:185] op_sel_hi:[1,0,1] neg_hi:[0,0,1]
	ds_read_b64 v[128:129], v5 offset:2904
	ds_read_b64 v[168:169], v56 offset:2816
	ds_read_b64 v[106:107], v5 offset:3168
	ds_read_b64 v[176:177], v56 offset:3072
	ds_read_b64 v[114:115], v5 offset:3432
	ds_read_b64 v[178:179], v56 offset:3328
	ds_read_b64 v[122:123], v5 offset:3696
	ds_read_b64 v[188:189], v56 offset:3584
	ds_read_b64 v[130:131], v5 offset:3960
	ds_read_b64 v[184:185], v56 offset:3840
	s_waitcnt lgkmcnt(8)
	v_pk_mul_f32 v[102:103], v[128:129], v[168:169] op_sel:[1,1] op_sel_hi:[0,1]
	v_pk_fma_f32 v[128:129], v[128:129], v[168:169], v[102:103] op_sel_hi:[1,0,1] neg_hi:[0,0,1]
	s_waitcnt lgkmcnt(6)
	v_pk_mul_f32 v[186:187], v[106:107], v[176:177] op_sel:[1,1] op_sel_hi:[0,1]
	v_pk_fma_f32 v[106:107], v[106:107], v[176:177], v[186:187] op_sel_hi:[1,0,1] neg_hi:[0,0,1]
	s_waitcnt lgkmcnt(4)
	v_pk_mul_f32 v[180:181], v[114:115], v[178:179] op_sel:[1,1] op_sel_hi:[0,1]
	v_pk_fma_f32 v[114:115], v[114:115], v[178:179], v[180:181] op_sel_hi:[1,0,1] neg_hi:[0,0,1]
	s_waitcnt lgkmcnt(2)
	v_pk_mul_f32 v[174:175], v[122:123], v[188:189] op_sel:[1,1] op_sel_hi:[0,1]
	v_pk_fma_f32 v[122:123], v[122:123], v[188:189], v[174:175] op_sel_hi:[1,0,1] neg_hi:[0,0,1]
	s_waitcnt lgkmcnt(0)
	v_pk_mul_f32 v[166:167], v[130:131], v[184:185] op_sel:[1,1] op_sel_hi:[0,1]
	v_pk_fma_f32 v[130:131], v[130:131], v[184:185], v[166:167] op_sel_hi:[1,0,1] neg_hi:[0,0,1]
	v_pk_add_f32 v[102:103], v[100:101], v[104:105]
	v_pk_add_f32 v[186:187], v[100:101], v[104:105] neg_lo:[0,1] neg_hi:[0,1]
	v_pk_add_f32 v[180:181], v[126:127], v[106:107]
	v_pk_add_f32 v[174:175], v[126:127], v[106:107] neg_lo:[0,1] neg_hi:[0,1]
	v_pk_add_f32 v[100:101], v[102:103], v[180:181]
	v_pk_add_f32 v[104:105], v[102:103], v[180:181] neg_lo:[0,1] neg_hi:[0,1]
	v_pk_add_f32 v[126:127], v[186:187], v[174:175] op_sel:[0,1] op_sel_hi:[1,0] neg_lo:[0,1]
	v_pk_add_f32 v[106:107], v[186:187], v[174:175] op_sel:[0,1] op_sel_hi:[1,0] neg_hi:[0,1]
	v_pk_add_f32 v[166:167], v[108:109], v[112:113]
	v_pk_add_f32 v[168:169], v[108:109], v[112:113] neg_lo:[0,1] neg_hi:[0,1]
	v_pk_add_f32 v[176:177], v[118:119], v[114:115]
	v_pk_add_f32 v[178:179], v[118:119], v[114:115] neg_lo:[0,1] neg_hi:[0,1]
	v_pk_add_f32 v[108:109], v[166:167], v[176:177]
	v_pk_add_f32 v[112:113], v[166:167], v[176:177] neg_lo:[0,1] neg_hi:[0,1]
	v_pk_add_f32 v[118:119], v[168:169], v[178:179] op_sel:[0,1] op_sel_hi:[1,0] neg_lo:[0,1]
	v_pk_add_f32 v[114:115], v[168:169], v[178:179] op_sel:[0,1] op_sel_hi:[1,0] neg_hi:[0,1]
	v_pk_add_f32 v[188:189], v[116:117], v[120:121]
	v_pk_add_f32 v[184:185], v[116:117], v[120:121] neg_lo:[0,1] neg_hi:[0,1]
	v_pk_add_f32 v[102:103], v[182:183], v[122:123]
	v_pk_add_f32 v[186:187], v[182:183], v[122:123] neg_lo:[0,1] neg_hi:[0,1]
	v_pk_add_f32 v[116:117], v[188:189], v[102:103]
	v_pk_add_f32 v[120:121], v[188:189], v[102:103] neg_lo:[0,1] neg_hi:[0,1]
	v_pk_add_f32 v[182:183], v[184:185], v[186:187] op_sel:[0,1] op_sel_hi:[1,0] neg_lo:[0,1]
	v_pk_add_f32 v[122:123], v[184:185], v[186:187] op_sel:[0,1] op_sel_hi:[1,0] neg_hi:[0,1]
	v_pk_add_f32 v[180:181], v[124:125], v[128:129]
	v_pk_add_f32 v[174:175], v[124:125], v[128:129] neg_lo:[0,1] neg_hi:[0,1]
	v_pk_add_f32 v[166:167], v[110:111], v[130:131]
	v_pk_add_f32 v[168:169], v[110:111], v[130:131] neg_lo:[0,1] neg_hi:[0,1]
	v_pk_add_f32 v[124:125], v[180:181], v[166:167]
	v_pk_add_f32 v[128:129], v[180:181], v[166:167] neg_lo:[0,1] neg_hi:[0,1]
	v_pk_add_f32 v[110:111], v[174:175], v[168:169] op_sel:[0,1] op_sel_hi:[1,0] neg_lo:[0,1]
	v_pk_add_f32 v[130:131], v[174:175], v[168:169] op_sel:[0,1] op_sel_hi:[1,0] neg_hi:[0,1]
	v_pk_mul_f32 v[176:177], v[118:119], s[68:69] op_sel:[1,1] op_sel_hi:[0,1]
	v_pk_fma_f32 v[118:119], v[118:119], s[68:69], v[176:177] op_sel_hi:[1,0,1] neg_hi:[0,0,1]
	v_pk_mul_f32 v[178:179], v[182:183], s[84:85] op_sel:[1,1] op_sel_hi:[0,1]
	v_pk_fma_f32 v[182:183], v[182:183], s[84:85], v[178:179] op_sel_hi:[1,0,1] neg_hi:[0,0,1]
	v_pk_mul_f32 v[188:189], v[110:111], s[88:89] op_sel:[1,1] op_sel_hi:[0,1]
	v_pk_fma_f32 v[110:111], v[110:111], s[88:89], v[188:189] op_sel_hi:[1,0,1] neg_hi:[0,0,1]
; #define LAS __attribute__((address_space(3)))
; __device__ __forceinline__ f32x2 cmulc(f32x2 a, f32x2 b) { return (f32x2){a.x * b.x + a.y * b.y, a.y * b.x - a.x * b.y}; }
; __device__ __forceinline__ void fft_inv2(LAS f32x2* B, const LAS f32x2* TW2, int tid) {
;     ...
;     dft16<true>(x);
; #pragma unroll
;     for (int r = 0; r < 16; ++r) B[fpad(base + 32 * r)] = x[r];
; __device__ __forceinline__ void fft_inv1(f32x2 (&x)[16], const LAS f32x2* B, int n2, const f32x2 (&w)[16]) {
;     asm volatile("" : "+v"(n2));
;     x[0] = B[fpad(n2)];
; #pragma unroll
;     for (int k = 1; k < 16; ++k) x[k] = cmulc(B[fpad(512 * k + n2)], w[k]);
;     dft16_inv_lo(x);
	v_pk_mul_f32 v[184:185], v[112:113], s[84:85] op_sel:[1,1] op_sel_hi:[0,1]
	v_pk_fma_f32 v[112:113], v[112:113], s[84:85], v[184:185] op_sel_hi:[1,0,1] neg_hi:[0,0,1]
	v_pk_mul_f32 v[102:103], v[128:129], s[90:91] op_sel:[1,1] op_sel_hi:[0,1]
	v_pk_fma_f32 v[128:129], v[128:129], s[90:91], v[102:103] op_sel_hi:[1,0,1] neg_hi:[0,0,1]
	v_pk_mul_f32 v[186:187], v[114:115], s[88:89] op_sel:[1,1] op_sel_hi:[0,1]
	v_pk_fma_f32 v[114:115], v[114:115], s[88:89], v[186:187] op_sel_hi:[1,0,1] neg_hi:[0,0,1]
	v_pk_mul_f32 v[180:181], v[122:123], s[90:91] op_sel:[1,1] op_sel_hi:[0,1]
	v_pk_fma_f32 v[122:123], v[122:123], s[90:91], v[180:181] op_sel_hi:[1,0,1] neg_hi:[0,0,1]
	v_pk_mul_f32 v[174:175], v[130:131], s[98:99] op_sel:[1,1] op_sel_hi:[0,1]
	v_pk_fma_f32 v[130:131], v[130:131], s[98:99], v[174:175] op_sel_hi:[1,0,1] neg_hi:[0,0,1]
	v_pk_add_f32 v[166:167], v[100:101], v[116:117]
	v_pk_add_f32 v[168:169], v[100:101], v[116:117] neg_lo:[0,1] neg_hi:[0,1]
	v_pk_add_f32 v[176:177], v[108:109], v[124:125]
	v_pk_add_f32 v[178:179], v[108:109], v[124:125] neg_lo:[0,1] neg_hi:[0,1]
	v_pk_add_f32 v[100:101], v[166:167], v[176:177]
	v_pk_add_f32 v[116:117], v[166:167], v[176:177] neg_lo:[0,1] neg_hi:[0,1]
	v_pk_add_f32 v[108:109], v[168:169], v[178:179] op_sel:[0,1] op_sel_hi:[1,0] neg_lo:[0,1]
	v_pk_add_f32 v[124:125], v[168:169], v[178:179] op_sel:[0,1] op_sel_hi:[1,0] neg_hi:[0,1]
	v_pk_add_f32 v[188:189], v[126:127], v[182:183]
	v_pk_add_f32 v[184:185], v[126:127], v[182:183] neg_lo:[0,1] neg_hi:[0,1]
	v_pk_add_f32 v[102:103], v[118:119], v[110:111]
	v_pk_add_f32 v[186:187], v[118:119], v[110:111] neg_lo:[0,1] neg_hi:[0,1]
	v_pk_add_f32 v[126:127], v[188:189], v[102:103]
	v_pk_add_f32 v[182:183], v[188:189], v[102:103] neg_lo:[0,1] neg_hi:[0,1]
	v_pk_add_f32 v[118:119], v[184:185], v[186:187] op_sel:[0,1] op_sel_hi:[1,0] neg_lo:[0,1]
	v_pk_add_f32 v[110:111], v[184:185], v[186:187] op_sel:[0,1] op_sel_hi:[1,0] neg_hi:[0,1]
	v_pk_add_f32 v[180:181], v[104:105], v[120:121] op_sel:[0,1] op_sel_hi:[1,0] neg_lo:[0,1]
	v_pk_add_f32 v[174:175], v[104:105], v[120:121] op_sel:[0,1] op_sel_hi:[1,0] neg_hi:[0,1]
	v_pk_add_f32 v[166:167], v[112:113], v[128:129]
	v_pk_add_f32 v[168:169], v[112:113], v[128:129] neg_lo:[0,1] neg_hi:[0,1]
	v_pk_add_f32 v[104:105], v[180:181], v[166:167]
	v_pk_add_f32 v[120:121], v[180:181], v[166:167] neg_lo:[0,1] neg_hi:[0,1]
	v_pk_add_f32 v[112:113], v[174:175], v[168:169] op_sel:[0,1] op_sel_hi:[1,0] neg_lo:[0,1]
	v_pk_add_f32 v[128:129], v[174:175], v[168:169] op_sel:[0,1] op_sel_hi:[1,0] neg_hi:[0,1]
	v_pk_add_f32 v[176:177], v[106:107], v[122:123]
	v_pk_add_f32 v[178:179], v[106:107], v[122:123] neg_lo:[0,1] neg_hi:[0,1]
	v_pk_add_f32 v[188:189], v[114:115], v[130:131]
	v_pk_add_f32 v[184:185], v[114:115], v[130:131] neg_lo:[0,1] neg_hi:[0,1]
	v_pk_add_f32 v[106:107], v[176:177], v[188:189]
	v_pk_add_f32 v[122:123], v[176:177], v[188:189] neg_lo:[0,1] neg_hi:[0,1]
	v_pk_add_f32 v[114:115], v[178:179], v[184:185] op_sel:[0,1] op_sel_hi:[1,0] neg_lo:[0,1]
	v_pk_add_f32 v[130:131], v[178:179], v[184:185] op_sel:[0,1] op_sel_hi:[1,0] neg_hi:[0,1]
	ds_write_b64 v5, v[100:101]
	ds_write_b64 v5, v[126:127] offset:264
	ds_write_b64 v5, v[104:105] offset:528
	ds_write_b64 v5, v[106:107] offset:792
	ds_write_b64 v5, v[108:109] offset:1056
	ds_write_b64 v5, v[118:119] offset:1320
	ds_write_b64 v5, v[112:113] offset:1584
	ds_write_b64 v5, v[114:115] offset:1848
	ds_write_b64 v5, v[116:117] offset:2112
	ds_write_b64 v5, v[182:183] offset:2376
	ds_write_b64 v5, v[120:121] offset:2640
	ds_write_b64 v5, v[122:123] offset:2904
	ds_write_b64 v5, v[124:125] offset:3168
	ds_write_b64 v5, v[110:111] offset:3432
	ds_write_b64 v5, v[128:129] offset:3696
	ds_write_b64 v5, v[130:131] offset:3960
	s_waitcnt lgkmcnt(0)
	s_barrier
	s_cbranch_vccz .Lhfft_st11
	s_sleep 4
.Lhfft_st11:
	ds_read_b64 v[100:101], v3
	ds_read_b64 v[108:109], v3 offset:16896
	ds_read_b64 v[116:117], v3 offset:33792
	ds_read_b64 v[124:125], v3 offset:50688
	ds_read_b64 v[126:127], v3 offset:4224
	ds_read_b64 v[118:119], v3 offset:21120
	ds_read_b64 v[182:183], v3 offset:38016
	ds_read_b64 v[110:111], v3 offset:54912
	ds_read_b64 v[104:105], v3 offset:8448
	ds_read_b64 v[112:113], v3 offset:25344
	ds_read_b64 v[120:121], v3 offset:42240
	ds_read_b64 v[128:129], v3 offset:59136
	ds_read_b64 v[106:107], v3 offset:12672
	ds_read_b64 v[114:115], v3 offset:29568
	ds_read_b64 v[122:123], v3 offset:46464
	ds_read_b64 v[130:131], v3 offset:63360
	s_waitcnt lgkmcnt(14)
	v_pk_mul_f32 v[102:103], v[108:109], v[12:13] op_sel:[1,1] op_sel_hi:[0,1]
	v_pk_fma_f32 v[108:109], v[108:109], v[12:13], v[102:103] op_sel_hi:[1,0,1] neg_hi:[0,0,1]
	s_waitcnt lgkmcnt(13)
	v_pk_mul_f32 v[186:187], v[116:117], v[20:21] op_sel:[1,1] op_sel_hi:[0,1]
	v_pk_fma_f32 v[116:117], v[116:117], v[20:21], v[186:187] op_sel_hi:[1,0,1] neg_hi:[0,0,1]
	s_waitcnt lgkmcnt(12)
	v_pk_mul_f32 v[180:181], v[124:125], v[28:29] op_sel:[1,1] op_sel_hi:[0,1]
	v_pk_fma_f32 v[124:125], v[124:125], v[28:29], v[180:181] op_sel_hi:[1,0,1] neg_hi:[0,0,1]
	s_waitcnt lgkmcnt(11)
	v_pk_mul_f32 v[174:175], v[126:127], v[6:7] op_sel:[1,1] op_sel_hi:[0,1]
	v_pk_fma_f32 v[126:127], v[126:127], v[6:7], v[174:175] op_sel_hi:[1,0,1] neg_hi:[0,0,1]
	s_waitcnt lgkmcnt(10)
	v_pk_mul_f32 v[166:167], v[118:119], v[14:15] op_sel:[1,1] op_sel_hi:[0,1]
	v_pk_fma_f32 v[118:119], v[118:119], v[14:15], v[166:167] op_sel_hi:[1,0,1] neg_hi:[0,0,1]
	s_waitcnt lgkmcnt(9)
	v_pk_mul_f32 v[168:169], v[182:183], v[22:23] op_sel:[1,1] op_sel_hi:[0,1]
	v_pk_fma_f32 v[182:183], v[182:183], v[22:23], v[168:169] op_sel_hi:[1,0,1] neg_hi:[0,0,1]
	s_waitcnt lgkmcnt(8)
; __device__ __forceinline__ f32x2 cmulc(f32x2 a, f32x2 b) { return (f32x2){a.x * b.x + a.y * b.y, a.y * b.x - a.x * b.y}; }
; __device__ __forceinline__ void dft16_inv_lo(f32x2 (&x)[16]) {
;     constexpr float C1 = 0.92387953251128674f, S1 = 0.38268343236508977f, C2 = 0.70710678118654752f;
; #pragma unroll
;     for (int b = 0; b < 4; ++b) dft4<true>(x[b], x[4 + b], x[8 + b], x[12 + b]);
;     const f32x2 w1 = {C1, -S1}, w2 = {C2, -C2}, w3 = {S1, -C1}, w4 = {0.f, -1.f}, w6 = {-C2, -C2}, w9 = {-C1, S1};
;     x[5] = cmulc(x[5], w1); x[6] = cmulc(x[6], w2); x[7] = cmulc(x[7], w3);
;     x[9] = cmulc(x[9], w2); x[10] = cmulc(x[10], w4); x[11] = cmulc(x[11], w6);
;     x[13] = cmulc(x[13], w3); x[14] = cmulc(x[14], w6); x[15] = cmulc(x[15], w9);
;     f32x2 y[8];
; #pragma unroll
;     for (int c = 0; c < 4; ++c) { const f32x2 t0 = x[4 * c] + x[4 * c + 2], t1 = x[4 * c] - x[4 * c + 2], t2 = x[4 * c + 1] + x[4 * c + 3], t3 = x[4 * c + 1] - x[4 * c + 3];
;         y[c] = t0 + t2; y[4 + c] = t1 + (f32x2){-t3.y, t3.x}; }
; #pragma unroll
;     for (int k = 0; k < 8; ++k) x[k] = y[k];
; }
; __device__ __forceinline__ void hyena_fft(LAS unsigned char* lds, int layer, int G, const int wave_s) {
;     ...
;             { const float fb1 = fbias[HY + c]; float* zo = ZT + (size_t)c * MT;
	v_pk_mul_f32 v[176:177], v[110:111], v[30:31] op_sel:[1,1] op_sel_hi:[0,1]
	v_pk_fma_f32 v[110:111], v[110:111], v[30:31], v[176:177] op_sel_hi:[1,0,1] neg_hi:[0,0,1]
	s_waitcnt lgkmcnt(7)
	v_pk_mul_f32 v[178:179], v[104:105], v[8:9] op_sel:[1,1] op_sel_hi:[0,1]
	v_pk_fma_f32 v[104:105], v[104:105], v[8:9], v[178:179] op_sel_hi:[1,0,1] neg_hi:[0,0,1]
	s_waitcnt lgkmcnt(6)
	v_pk_mul_f32 v[188:189], v[112:113], v[16:17] op_sel:[1,1] op_sel_hi:[0,1]
	v_pk_fma_f32 v[112:113], v[112:113], v[16:17], v[188:189] op_sel_hi:[1,0,1] neg_hi:[0,0,1]
	s_waitcnt lgkmcnt(5)
	v_pk_mul_f32 v[184:185], v[120:121], v[24:25] op_sel:[1,1] op_sel_hi:[0,1]
	v_pk_fma_f32 v[120:121], v[120:121], v[24:25], v[184:185] op_sel_hi:[1,0,1] neg_hi:[0,0,1]
	s_waitcnt lgkmcnt(4)
	v_pk_mul_f32 v[102:103], v[128:129], v[32:33] op_sel:[1,1] op_sel_hi:[0,1]
	v_pk_fma_f32 v[128:129], v[128:129], v[32:33], v[102:103] op_sel_hi:[1,0,1] neg_hi:[0,0,1]
	s_waitcnt lgkmcnt(3)
	v_pk_mul_f32 v[186:187], v[106:107], v[10:11] op_sel:[1,1] op_sel_hi:[0,1]
	v_pk_fma_f32 v[106:107], v[106:107], v[10:11], v[186:187] op_sel_hi:[1,0,1] neg_hi:[0,0,1]
	s_waitcnt lgkmcnt(2)
	v_pk_mul_f32 v[180:181], v[114:115], v[18:19] op_sel:[1,1] op_sel_hi:[0,1]
	v_pk_fma_f32 v[114:115], v[114:115], v[18:19], v[180:181] op_sel_hi:[1,0,1] neg_hi:[0,0,1]
	s_waitcnt lgkmcnt(1)
	v_pk_mul_f32 v[174:175], v[122:123], v[26:27] op_sel:[1,1] op_sel_hi:[0,1]
	v_pk_fma_f32 v[122:123], v[122:123], v[26:27], v[174:175] op_sel_hi:[1,0,1] neg_hi:[0,0,1]
	s_waitcnt lgkmcnt(0)
	v_pk_mul_f32 v[166:167], v[130:131], v[34:35] op_sel:[1,1] op_sel_hi:[0,1]
	v_pk_fma_f32 v[130:131], v[130:131], v[34:35], v[166:167] op_sel_hi:[1,0,1] neg_hi:[0,0,1]
	v_pk_add_f32 v[168:169], v[100:101], v[116:117]
	v_pk_add_f32 v[176:177], v[100:101], v[116:117] neg_lo:[0,1] neg_hi:[0,1]
	v_pk_add_f32 v[178:179], v[108:109], v[124:125]
	v_pk_add_f32 v[188:189], v[108:109], v[124:125] neg_lo:[0,1] neg_hi:[0,1]
	v_pk_add_f32 v[100:101], v[168:169], v[178:179]
	v_pk_add_f32 v[116:117], v[168:169], v[178:179] neg_lo:[0,1] neg_hi:[0,1]
	v_pk_add_f32 v[108:109], v[176:177], v[188:189] op_sel:[0,1] op_sel_hi:[1,0] neg_lo:[0,1]
	v_pk_add_f32 v[124:125], v[176:177], v[188:189] op_sel:[0,1] op_sel_hi:[1,0] neg_hi:[0,1]
	v_pk_add_f32 v[184:185], v[126:127], v[182:183]
	v_pk_add_f32 v[102:103], v[126:127], v[182:183] neg_lo:[0,1] neg_hi:[0,1]
	v_pk_add_f32 v[186:187], v[118:119], v[110:111]
	v_pk_add_f32 v[180:181], v[118:119], v[110:111] neg_lo:[0,1] neg_hi:[0,1]
	v_pk_add_f32 v[126:127], v[184:185], v[186:187]
	v_pk_add_f32 v[182:183], v[184:185], v[186:187] neg_lo:[0,1] neg_hi:[0,1]
	v_pk_add_f32 v[118:119], v[102:103], v[180:181] op_sel:[0,1] op_sel_hi:[1,0] neg_lo:[0,1]
	v_pk_add_f32 v[110:111], v[102:103], v[180:181] op_sel:[0,1] op_sel_hi:[1,0] neg_hi:[0,1]
	v_pk_add_f32 v[174:175], v[104:105], v[120:121]
	v_pk_add_f32 v[166:167], v[104:105], v[120:121] neg_lo:[0,1] neg_hi:[0,1]
	v_pk_add_f32 v[168:169], v[112:113], v[128:129]
	v_pk_add_f32 v[176:177], v[112:113], v[128:129] neg_lo:[0,1] neg_hi:[0,1]
	v_pk_add_f32 v[104:105], v[174:175], v[168:169]
	v_pk_add_f32 v[120:121], v[174:175], v[168:169] neg_lo:[0,1] neg_hi:[0,1]
	v_pk_add_f32 v[112:113], v[166:167], v[176:177] op_sel:[0,1] op_sel_hi:[1,0] neg_lo:[0,1]
	v_pk_add_f32 v[128:129], v[166:167], v[176:177] op_sel:[0,1] op_sel_hi:[1,0] neg_hi:[0,1]
	v_pk_add_f32 v[178:179], v[106:107], v[122:123]
	v_pk_add_f32 v[188:189], v[106:107], v[122:123] neg_lo:[0,1] neg_hi:[0,1]
	v_pk_add_f32 v[184:185], v[114:115], v[130:131]
	v_pk_add_f32 v[102:103], v[114:115], v[130:131] neg_lo:[0,1] neg_hi:[0,1]
	v_pk_add_f32 v[106:107], v[178:179], v[184:185]
	v_pk_add_f32 v[122:123], v[178:179], v[184:185] neg_lo:[0,1] neg_hi:[0,1]
	v_pk_add_f32 v[114:115], v[188:189], v[102:103] op_sel:[0,1] op_sel_hi:[1,0] neg_lo:[0,1]
	v_pk_add_f32 v[130:131], v[188:189], v[102:103] op_sel:[0,1] op_sel_hi:[1,0] neg_hi:[0,1]
	v_pk_mul_f32 v[186:187], v[118:119], s[68:69] op_sel:[1,1] op_sel_hi:[0,1]
	v_pk_fma_f32 v[118:119], v[118:119], s[68:69], v[186:187] op_sel_hi:[1,0,1] neg_hi:[0,0,1]
	v_pk_mul_f32 v[180:181], v[112:113], s[84:85] op_sel:[1,1] op_sel_hi:[0,1]
	v_pk_fma_f32 v[112:113], v[112:113], s[84:85], v[180:181] op_sel_hi:[1,0,1] neg_hi:[0,0,1]
	v_pk_mul_f32 v[174:175], v[114:115], s[88:89] op_sel:[1,1] op_sel_hi:[0,1]
	v_pk_fma_f32 v[114:115], v[114:115], s[88:89], v[174:175] op_sel_hi:[1,0,1] neg_hi:[0,0,1]
	v_pk_mul_f32 v[166:167], v[182:183], s[84:85] op_sel:[1,1] op_sel_hi:[0,1]
	v_pk_fma_f32 v[182:183], v[182:183], s[84:85], v[166:167] op_sel_hi:[1,0,1] neg_hi:[0,0,1]
	v_pk_mul_f32 v[168:169], v[122:123], s[90:91] op_sel:[1,1] op_sel_hi:[0,1]
	v_pk_fma_f32 v[122:123], v[122:123], s[90:91], v[168:169] op_sel_hi:[1,0,1] neg_hi:[0,0,1]
	v_pk_mul_f32 v[176:177], v[110:111], s[88:89] op_sel:[1,1] op_sel_hi:[0,1]
	v_pk_fma_f32 v[110:111], v[110:111], s[88:89], v[176:177] op_sel_hi:[1,0,1] neg_hi:[0,0,1]
	v_pk_mul_f32 v[178:179], v[128:129], s[90:91] op_sel:[1,1] op_sel_hi:[0,1]
	v_pk_fma_f32 v[128:129], v[128:129], s[90:91], v[178:179] op_sel_hi:[1,0,1] neg_hi:[0,0,1]
	v_pk_mul_f32 v[188:189], v[130:131], s[98:99] op_sel:[1,1] op_sel_hi:[0,1]
	v_pk_fma_f32 v[130:131], v[130:131], s[98:99], v[188:189] op_sel_hi:[1,0,1] neg_hi:[0,0,1]
	v_pk_add_f32 v[184:185], v[100:101], v[104:105]
	v_pk_add_f32 v[102:103], v[100:101], v[104:105] neg_lo:[0,1] neg_hi:[0,1]
	v_pk_add_f32 v[186:187], v[126:127], v[106:107]
	v_pk_add_f32 v[180:181], v[126:127], v[106:107] neg_lo:[0,1] neg_hi:[0,1]
	v_pk_add_f32 v[100:101], v[184:185], v[186:187]
	v_pk_add_f32 v[126:127], v[102:103], v[180:181] op_sel:[0,1] op_sel_hi:[1,0] neg_lo:[0,1]
	v_pk_add_f32 v[174:175], v[108:109], v[112:113]
	v_pk_add_f32 v[166:167], v[108:109], v[112:113] neg_lo:[0,1] neg_hi:[0,1]
	v_pk_add_f32 v[168:169], v[118:119], v[114:115]
	v_pk_add_f32 v[176:177], v[118:119], v[114:115] neg_lo:[0,1] neg_hi:[0,1]
	v_pk_add_f32 v[108:109], v[174:175], v[168:169]
	v_pk_add_f32 v[118:119], v[166:167], v[176:177] op_sel:[0,1] op_sel_hi:[1,0] neg_lo:[0,1]
	v_pk_add_f32 v[178:179], v[116:117], v[120:121] op_sel:[0,1] op_sel_hi:[1,0] neg_lo:[0,1]
	v_pk_add_f32 v[188:189], v[116:117], v[120:121] op_sel:[0,1] op_sel_hi:[1,0] neg_hi:[0,1]
	v_pk_add_f32 v[184:185], v[182:183], v[122:123]
	v_pk_add_f32 v[102:103], v[182:183], v[122:123] neg_lo:[0,1] neg_hi:[0,1]
	v_pk_add_f32 v[116:117], v[178:179], v[184:185]
	v_pk_add_f32 v[182:183], v[188:189], v[102:103] op_sel:[0,1] op_sel_hi:[1,0] neg_lo:[0,1]
	v_pk_add_f32 v[186:187], v[124:125], v[128:129]
	v_pk_add_f32 v[180:181], v[124:125], v[128:129] neg_lo:[0,1] neg_hi:[0,1]
	v_pk_add_f32 v[174:175], v[110:111], v[130:131]
	v_pk_add_f32 v[166:167], v[110:111], v[130:131] neg_lo:[0,1] neg_hi:[0,1]
	v_pk_add_f32 v[124:125], v[186:187], v[174:175]
	v_pk_add_f32 v[110:111], v[180:181], v[166:167] op_sel:[0,1] op_sel_hi:[1,0] neg_lo:[0,1]
	s_load_dword s35, s[50:51], 0x1000
	s_mul_i32 s43, s80, 0x8800
	s_add_u32 s46, s40, s43
	s_addc_u32 s47, s41, 0
	s_waitcnt lgkmcnt(0)
; __device__ __forceinline__ void hyena_fft(LAS unsigned char* lds, int layer, int G, const int wave_s) {
;     ...
;             { const float fb1 = fbias[HY + c]; float* zo = ZT + (size_t)c * MT;
; #pragma unroll
;               for (int r = 0; r < 8; ++r) { const int t = n2 + 512 * r;
;                   zo[t] = ux[r][0] * (x[r].x + fb1 * uz[r][0]); zo[SEQ + t] = ux[r][1] * (x[r].y + fb1 * uz[r][1]); } }
	v_mov_b32_e32 v194, s35
	v_pk_fma_f32 v[168:169], v[132:133], v[194:195], v[100:101] op_sel_hi:[1,0,1]
	v_pk_mul_f32 v[168:169], v[148:149], v[168:169]
	s_add_u32 s60, s46, 0
	s_addc_u32 s61, s47, 0
	s_add_u32 s62, s60, 0x4000
	s_addc_u32 s63, s61, 0
	global_store_dword v212, v168, s[60:61]
	global_store_dword v212, v169, s[62:63]
	v_pk_fma_f32 v[176:177], v[134:135], v[194:195], v[108:109] op_sel_hi:[1,0,1]
	v_pk_mul_f32 v[176:177], v[150:151], v[176:177]
	global_store_dword v212, v176, s[60:61] offset:2048
	global_store_dword v212, v177, s[62:63] offset:2048
	v_pk_fma_f32 v[178:179], v[136:137], v[194:195], v[116:117] op_sel_hi:[1,0,1]
	v_pk_mul_f32 v[178:179], v[152:153], v[178:179]
	s_add_u32 s60, s46, 0x1000
	s_addc_u32 s61, s47, 0
	s_add_u32 s62, s60, 0x4000
	s_addc_u32 s63, s61, 0
	global_store_dword v212, v178, s[60:61]
	global_store_dword v212, v179, s[62:63]
	v_pk_fma_f32 v[188:189], v[138:139], v[194:195], v[124:125] op_sel_hi:[1,0,1]
	v_pk_mul_f32 v[188:189], v[154:155], v[188:189]
	global_store_dword v212, v188, s[60:61] offset:2048
	global_store_dword v212, v189, s[62:63] offset:2048
	v_pk_fma_f32 v[184:185], v[140:141], v[194:195], v[126:127] op_sel_hi:[1,0,1]
	v_pk_mul_f32 v[184:185], v[158:159], v[184:185]
	s_add_u32 s60, s46, 0x2000
	s_addc_u32 s61, s47, 0
	s_add_u32 s62, s60, 0x4000
	s_addc_u32 s63, s61, 0
	global_store_dword v212, v184, s[60:61]
	global_store_dword v212, v185, s[62:63]
	v_pk_fma_f32 v[102:103], v[142:143], v[194:195], v[118:119] op_sel_hi:[1,0,1]
	v_pk_mul_f32 v[102:103], v[160:161], v[102:103]
	global_store_dword v212, v102, s[60:61] offset:2048
	global_store_dword v212, v103, s[62:63] offset:2048
	v_pk_fma_f32 v[186:187], v[144:145], v[194:195], v[182:183] op_sel_hi:[1,0,1]
	v_pk_mul_f32 v[186:187], v[162:163], v[186:187]
	s_add_u32 s60, s46, 0x3000
	s_addc_u32 s61, s47, 0
	s_add_u32 s62, s60, 0x4000
	s_addc_u32 s63, s61, 0
	global_store_dword v212, v186, s[60:61]
	global_store_dword v212, v187, s[62:63]
	v_pk_fma_f32 v[180:181], v[146:147], v[194:195], v[110:111] op_sel_hi:[1,0,1]
	v_pk_mul_f32 v[180:181], v[164:165], v[180:181]
	global_store_dword v212, v180, s[60:61] offset:2048
	global_store_dword v212, v181, s[62:63] offset:2048
	s_add_u32 s80, s80, 1
	s_cmp_lt_i32 s80, s93
	s_cbranch_scc1 .Lhfft_loop
	s_waitcnt vmcnt(0) lgkmcnt(0)
